# v5 + GEMM K-loops: the 8 independent MFMAs of each k-group reordered in Gray order of (m,n) so one operand repeats between consecutive MFMAs (operand-toggle/DVFS lever); bit-identical, same code size
# speedup vs baseline: 1.0021x; 1.0021x over previous
; #define PG8_STAGE(bufoff, gbase, voff) do { _Pragma("unroll") for (int _i = 0; _i < 2; ++_i) \
;         __builtin_amdgcn_global_load_lds((const unsigned*)((const char*)(gbase) + (voff)[_i]), (PG8_LAS unsigned*)(lds + (bufoff) + ldsw + _i * 8192), 16, 0, 0); } while (0)
; #define PG8_LDA(dst, b, h) do { _Pragma("unroll") for (int m = 0; m < 4; ++m) _Pragma("unroll") for (int k = 0; k < 2; ++k) dst[m][k] = *(const PG8_LAS bf16x8*)(lds + PG8_SA(b, h) + aoff + m * 2048 + k * 1024); } while (0)
; #define PG8_LDB(dst, b, h) do { _Pragma("unroll") for (int n = 0; n < 2; ++n) _Pragma("unroll") for (int k = 0; k < 2; ++k) dst[n][k] = *(const PG8_LAS bf16x8*)(lds + PG8_SB(b, h) + boff + n * 2048 + k * 1024); } while (0)
; #define PG8_MMA(ai, bj, At, Bt) do { __builtin_amdgcn_s_setprio(1); _Pragma("unroll") for (int m = 0; m < 4; ++m) _Pragma("unroll") for (int n = 0; n < 2; ++n) _Pragma("unroll") for (int k = 0; k < 2; ++k) \
;         acc[ai][bj][m][n] = __builtin_amdgcn_mfma_f32_16x16x32_bf16(Bt[n][k], At[m][k], acc[ai][bj][m][n], 0, 0, 0); __builtin_amdgcn_s_setprio(0); } while (0)
; #define PG8_WAIT_V(n) asm volatile("s_waitcnt vmcnt(" #n ")" ::: "memory")
; #define PG8_WAIT_L(n) asm volatile("s_waitcnt lgkmcnt(" #n ")" ::: "memory")
; #define PG8_BAR __builtin_amdgcn_s_barrier()
; #define PG8_SCHED __builtin_amdgcn_sched_barrier(0)
; template <class Epi, class Sched, bool ALIGN_EPI = false, bool SP2 = false>
; __device__ __forceinline__ void gemm_phase(PG8_LAS unsigned char* lds, const Gemm g, const Sched& S, const Epi& E, const int tid) {
;     ...
;             PG8_LDB(B0, 0, 0); PG8_LDB(B1, 0, 1); PG8_SCHED; PG8_LDA(At, 0, 0); PG8_STAGE(PG8_SA(1, 1), a1 + hstepA, voffA);
;             PG8_WAIT_V(8); PG8_WAIT_L(0); PG8_BAR; PG8_MMA(0, 0, At, B0); PG8_MMA(0, 1, At, B1); PG8_BAR; PG8_SCHED;
;             PG8_LDA(At, 0, 1); PG8_STAGE(PG8_SB(0, 0), b2, voffB); PG8_STAGE(PG8_SB(0, 1), b2 + hstepB, voffB); PG8_STAGE(PG8_SA(0, 0), a2, voffA);
;             PG8_WAIT_V(8); PG8_WAIT_L(0); PG8_BAR; PG8_MMA(1, 0, At, B0); PG8_MMA(1, 1, At, B1); PG8_BAR; PG8_SCHED;
.LBB0_109:
	s_add_u32 s10, s2, 0xfffc0080
	s_addc_u32 s11, s3, -1
	s_add_i32 s61, 0, 0x10000
	s_cmp_eq_u32 s62, 4
	s_cselect_b32 vcc_hi, s1, s11
	s_cselect_b32 vcc_lo, s22, s10
	v_add_u32_e32 v0, s61, v155
	s_cselect_b32 s93, s23, s60
	s_cselect_b32 s92, s29, s31
	s_add_i32 s88, 0, 0x14000
	ds_read_b128 v[142:145], v0
	ds_read_b128 v[146:149], v0 offset:1024
	ds_read_b128 v[150:153], v0 offset:2048
	ds_read_b128 v[158:161], v0 offset:3072
	v_add_u32_e32 v0, s88, v155
	ds_read_b128 v[162:165], v0
	ds_read_b128 v[166:169], v0 offset:1024
	ds_read_b128 v[170:173], v0 offset:2048
	ds_read_b128 v[174:177], v0 offset:3072
	v_lshl_add_u64 v[202:203], s[2:3], 0, v[140:141]
	s_add_i32 m0, s9, 0xc000
	ds_read_b128 v[178:181], v157
	ds_read_b128 v[182:185], v157 offset:1024
	ds_read_b128 v[186:189], v157 offset:2048
	ds_read_b128 v[190:193], v157 offset:3072
	ds_read_b128 v[198:201], v157 offset:4096
	ds_read_b128 v[212:215], v157 offset:5120
	ds_read_b128 v[216:219], v157 offset:6144
	ds_read_b128 v[220:223], v157 offset:7168
	global_load_lds_dwordx4 v[202:203], off
	v_lshl_add_u64 v[202:203], s[2:3], 0, v[138:139]
	s_add_i32 m0, s9, 0xe000
	s_nop 0
	global_load_lds_dwordx4 v[202:203], off
	s_waitcnt vmcnt(8)
	s_waitcnt lgkmcnt(0)
	s_barrier
	s_setprio 1
	s_waitcnt lgkmcnt(0)
	v_mfma_f32_16x16x32_bf16 v[126:129], v[142:145], v[178:181], v[126:129]
	v_mfma_f32_16x16x32_bf16 v[122:125], v[150:153], v[178:181], v[122:125]
	v_mfma_f32_16x16x32_bf16 v[106:109], v[150:153], v[186:189], v[106:109]
	v_mfma_f32_16x16x32_bf16 v[110:113], v[142:145], v[186:189], v[110:113]
	v_mfma_f32_16x16x32_bf16 v[94:97], v[142:145], v[198:201], v[94:97]
	v_mfma_f32_16x16x32_bf16 v[90:93], v[150:153], v[198:201], v[90:93]
	v_mfma_f32_16x16x32_bf16 v[74:77], v[150:153], v[216:219], v[74:77]
	v_mfma_f32_16x16x32_bf16 v[78:81], v[142:145], v[216:219], v[78:81]
	v_mfma_f32_16x16x32_bf16 v[126:129], v[146:149], v[182:185], v[126:129]
	v_mfma_f32_16x16x32_bf16 v[122:125], v[158:161], v[182:185], v[122:125]
	v_mfma_f32_16x16x32_bf16 v[106:109], v[158:161], v[190:193], v[106:109]
	v_mfma_f32_16x16x32_bf16 v[110:113], v[146:149], v[190:193], v[110:113]
	v_mfma_f32_16x16x32_bf16 v[94:97], v[146:149], v[212:215], v[94:97]
	v_mfma_f32_16x16x32_bf16 v[90:93], v[158:161], v[212:215], v[90:93]
	v_mfma_f32_16x16x32_bf16 v[74:77], v[158:161], v[220:223], v[74:77]
	v_mfma_f32_16x16x32_bf16 v[78:81], v[146:149], v[220:223], v[78:81]
	s_setprio 0
	s_setprio 1
	v_mfma_f32_16x16x32_bf16 v[118:121], v[162:165], v[178:181], v[118:121]
	v_mfma_f32_16x16x32_bf16 v[114:117], v[170:173], v[178:181], v[114:117]
	v_mfma_f32_16x16x32_bf16 v[98:101], v[170:173], v[186:189], v[98:101]
	v_mfma_f32_16x16x32_bf16 v[102:105], v[162:165], v[186:189], v[102:105]
	v_mfma_f32_16x16x32_bf16 v[86:89], v[162:165], v[198:201], v[86:89]
	v_mfma_f32_16x16x32_bf16 v[82:85], v[170:173], v[198:201], v[82:85]
	v_mfma_f32_16x16x32_bf16 v[66:69], v[170:173], v[216:219], v[66:69]
	v_mfma_f32_16x16x32_bf16 v[70:73], v[162:165], v[216:219], v[70:73]
	v_mfma_f32_16x16x32_bf16 v[118:121], v[166:169], v[182:185], v[118:121]
	v_mfma_f32_16x16x32_bf16 v[114:117], v[174:177], v[182:185], v[114:117]
	v_mfma_f32_16x16x32_bf16 v[98:101], v[174:177], v[190:193], v[98:101]
	v_mfma_f32_16x16x32_bf16 v[102:105], v[166:169], v[190:193], v[102:105]
	v_mfma_f32_16x16x32_bf16 v[86:89], v[166:169], v[212:215], v[86:89]
	v_mfma_f32_16x16x32_bf16 v[82:85], v[174:177], v[212:215], v[82:85]
	v_mfma_f32_16x16x32_bf16 v[66:69], v[174:177], v[220:223], v[66:69]
	v_mfma_f32_16x16x32_bf16 v[70:73], v[166:169], v[220:223], v[70:73]
	s_setprio 0
	s_barrier
	s_add_i32 s10, s61, s56
	v_lshl_add_u64 v[202:203], s[92:93], 0, v[132:133]
	s_mov_b32 m0, s10
	ds_read_b128 v[178:181], v157 offset:16384
	ds_read_b128 v[182:185], v157 offset:17408
	ds_read_b128 v[186:189], v157 offset:18432
	ds_read_b128 v[190:193], v157 offset:19456
	ds_read_b128 v[198:201], v157 offset:20480
	ds_read_b128 v[212:215], v157 offset:21504
	ds_read_b128 v[216:219], v157 offset:22528
	ds_read_b128 v[220:223], v157 offset:23552
	global_load_lds_dwordx4 v[202:203], off
	s_add_i32 m0, s10, 0x2000
	s_add_u32 s10, s92, 0x20000
	v_lshl_add_u64 v[224:225], s[92:93], 0, v[136:137]
	s_addc_u32 s11, s93, 0
	s_add_i32 s61, s88, s56
	global_load_lds_dwordx4 v[224:225], off
	v_lshl_add_u64 v[226:227], s[10:11], 0, v[132:133]
	s_mov_b32 m0, s61
	v_lshl_add_u64 v[228:229], vcc, 0, v[134:135]
	global_load_lds_dwordx4 v[226:227], off
	v_lshl_add_u64 v[226:227], s[10:11], 0, v[136:137]
	s_add_i32 m0, s61, 0x2000
	s_nop 0
	global_load_lds_dwordx4 v[226:227], off
	v_lshl_add_u64 v[226:227], vcc, 0, v[130:131]
	s_mov_b32 m0, s9
	s_nop 0
	global_load_lds_dwordx4 v[226:227], off
	s_mov_b32 m0, s63
	s_nop 0
	global_load_lds_dwordx4 v[228:229], off
	s_waitcnt vmcnt(8)
	s_waitcnt lgkmcnt(0)
	s_barrier
; #define PG8_STAGE(bufoff, gbase, voff) do { _Pragma("unroll") for (int _i = 0; _i < 2; ++_i) \
;         __builtin_amdgcn_global_load_lds((const unsigned*)((const char*)(gbase) + (voff)[_i]), (PG8_LAS unsigned*)(lds + (bufoff) + ldsw + _i * 8192), 16, 0, 0); } while (0)
; #define PG8_LDA(dst, b, h) do { _Pragma("unroll") for (int m = 0; m < 4; ++m) _Pragma("unroll") for (int k = 0; k < 2; ++k) dst[m][k] = *(const PG8_LAS bf16x8*)(lds + PG8_SA(b, h) + aoff + m * 2048 + k * 1024); } while (0)
; #define PG8_LDB(dst, b, h) do { _Pragma("unroll") for (int n = 0; n < 2; ++n) _Pragma("unroll") for (int k = 0; k < 2; ++k) dst[n][k] = *(const PG8_LAS bf16x8*)(lds + PG8_SB(b, h) + boff + n * 2048 + k * 1024); } while (0)
; #define PG8_MMA(ai, bj, At, Bt) do { __builtin_amdgcn_s_setprio(1); _Pragma("unroll") for (int m = 0; m < 4; ++m) _Pragma("unroll") for (int n = 0; n < 2; ++n) _Pragma("unroll") for (int k = 0; k < 2; ++k) \
;         acc[ai][bj][m][n] = __builtin_amdgcn_mfma_f32_16x16x32_bf16(Bt[n][k], At[m][k], acc[ai][bj][m][n], 0, 0, 0); __builtin_amdgcn_s_setprio(0); } while (0)
; #define PG8_WAIT_V(n) asm volatile("s_waitcnt vmcnt(" #n ")" ::: "memory")
; #define PG8_WAIT_L(n) asm volatile("s_waitcnt lgkmcnt(" #n ")" ::: "memory")
; #define PG8_BAR __builtin_amdgcn_s_barrier()
; #define PG8_SCHED __builtin_amdgcn_sched_barrier(0)
; template <class Epi, class Sched, bool ALIGN_EPI = false, bool SP2 = false>
; __device__ __forceinline__ void gemm_phase(PG8_LAS unsigned char* lds, const Gemm g, const Sched& S, const Epi& E, const int tid) {
;     ...
;             PG8_WAIT_V(8); PG8_WAIT_L(0); PG8_BAR; PG8_MMA(1, 0, At, B0); PG8_MMA(1, 1, At, B1); PG8_BAR; PG8_SCHED;
;             PG8_LDB(B0, 1, 0); PG8_LDB(B1, 1, 1); PG8_SCHED; PG8_LDA(At, 1, 0); PG8_STAGE(PG8_SA(0, 1), a2 + hstepA, voffA);
;             PG8_WAIT_V(8); PG8_WAIT_L(0); PG8_BAR; PG8_MMA(0, 0, At, B0); PG8_MMA(0, 1, At, B1); PG8_BAR; PG8_SCHED;
	s_setprio 1
	s_waitcnt lgkmcnt(0)
	v_mfma_f32_16x16x32_bf16 v[62:65], v[142:145], v[178:181], v[62:65]
	v_mfma_f32_16x16x32_bf16 v[58:61], v[150:153], v[178:181], v[58:61]
	v_mfma_f32_16x16x32_bf16 v[42:45], v[150:153], v[186:189], v[42:45]
	v_mfma_f32_16x16x32_bf16 v[46:49], v[142:145], v[186:189], v[46:49]
	v_mfma_f32_16x16x32_bf16 v[30:33], v[142:145], v[198:201], v[30:33]
	v_mfma_f32_16x16x32_bf16 v[26:29], v[150:153], v[198:201], v[26:29]
	v_mfma_f32_16x16x32_bf16 v[10:13], v[150:153], v[216:219], v[10:13]
	v_mfma_f32_16x16x32_bf16 v[14:17], v[142:145], v[216:219], v[14:17]
	v_mfma_f32_16x16x32_bf16 v[62:65], v[146:149], v[182:185], v[62:65]
	v_mfma_f32_16x16x32_bf16 v[58:61], v[158:161], v[182:185], v[58:61]
	v_mfma_f32_16x16x32_bf16 v[42:45], v[158:161], v[190:193], v[42:45]
	v_mfma_f32_16x16x32_bf16 v[46:49], v[146:149], v[190:193], v[46:49]
	v_mfma_f32_16x16x32_bf16 v[30:33], v[146:149], v[212:215], v[30:33]
	v_mfma_f32_16x16x32_bf16 v[26:29], v[158:161], v[212:215], v[26:29]
	v_mfma_f32_16x16x32_bf16 v[10:13], v[158:161], v[220:223], v[10:13]
	v_mfma_f32_16x16x32_bf16 v[14:17], v[146:149], v[220:223], v[14:17]
	s_setprio 0
	s_setprio 1
	v_mfma_f32_16x16x32_bf16 v[54:57], v[162:165], v[178:181], v[54:57]
	v_mfma_f32_16x16x32_bf16 v[50:53], v[170:173], v[178:181], v[50:53]
	v_mfma_f32_16x16x32_bf16 v[34:37], v[170:173], v[186:189], v[34:37]
	v_mfma_f32_16x16x32_bf16 v[38:41], v[162:165], v[186:189], v[38:41]
	v_mfma_f32_16x16x32_bf16 v[22:25], v[162:165], v[198:201], v[22:25]
	v_mfma_f32_16x16x32_bf16 v[18:21], v[170:173], v[198:201], v[18:21]
	v_mfma_f32_16x16x32_bf16 v[2:5], v[170:173], v[216:219], v[2:5]
	v_mfma_f32_16x16x32_bf16 v[6:9], v[162:165], v[216:219], v[6:9]
	v_mfma_f32_16x16x32_bf16 v[54:57], v[166:169], v[182:185], v[54:57]
	v_mfma_f32_16x16x32_bf16 v[50:53], v[174:177], v[182:185], v[50:53]
	v_mfma_f32_16x16x32_bf16 v[34:37], v[174:177], v[190:193], v[34:37]
	v_mfma_f32_16x16x32_bf16 v[38:41], v[166:169], v[190:193], v[38:41]
	v_mfma_f32_16x16x32_bf16 v[22:25], v[166:169], v[212:215], v[22:25]
	v_mfma_f32_16x16x32_bf16 v[18:21], v[174:177], v[212:215], v[18:21]
	v_mfma_f32_16x16x32_bf16 v[2:5], v[174:177], v[220:223], v[2:5]
	v_mfma_f32_16x16x32_bf16 v[6:9], v[166:169], v[220:223], v[6:9]
	s_setprio 0
	s_barrier
	s_add_i32 s61, 0, 0x18000
	v_add_u32_e32 v0, s61, v155
	s_add_i32 s88, 0, 0x1c000
	ds_read_b128 v[142:145], v0
	ds_read_b128 v[146:149], v0 offset:1024
	ds_read_b128 v[150:153], v0 offset:2048
	ds_read_b128 v[158:161], v0 offset:3072
	v_add_u32_e32 v0, s88, v155
	ds_read_b128 v[162:165], v0
	ds_read_b128 v[166:169], v0 offset:1024
	ds_read_b128 v[170:173], v0 offset:2048
	ds_read_b128 v[174:177], v0 offset:3072
	s_add_u32 s10, vcc_lo, 0x40000
	s_addc_u32 s11, vcc_hi, 0
	s_mov_b32 m0, s64
	v_lshl_add_u64 v[230:231], s[10:11], 0, v[130:131]
	ds_read_b128 v[178:181], v157 offset:32768
	ds_read_b128 v[182:185], v157 offset:33792
	ds_read_b128 v[186:189], v157 offset:34816
	ds_read_b128 v[190:193], v157 offset:35840
	ds_read_b128 v[198:201], v157 offset:36864
	ds_read_b128 v[212:215], v157 offset:37888
	ds_read_b128 v[216:219], v157 offset:38912
	ds_read_b128 v[220:223], v157 offset:39936
	global_load_lds_dwordx4 v[230:231], off
	v_lshl_add_u64 v[230:231], s[10:11], 0, v[134:135]
	s_mov_b32 m0, s65
	s_nop 0
	global_load_lds_dwordx4 v[230:231], off
	s_waitcnt vmcnt(8)
	s_waitcnt lgkmcnt(0)
	s_barrier
	s_setprio 1
	s_waitcnt lgkmcnt(0)
	v_mfma_f32_16x16x32_bf16 v[126:129], v[142:145], v[178:181], v[126:129]
	v_mfma_f32_16x16x32_bf16 v[122:125], v[150:153], v[178:181], v[122:125]
	v_mfma_f32_16x16x32_bf16 v[106:109], v[150:153], v[186:189], v[106:109]
	v_mfma_f32_16x16x32_bf16 v[110:113], v[142:145], v[186:189], v[110:113]
	v_mfma_f32_16x16x32_bf16 v[94:97], v[142:145], v[198:201], v[94:97]
	v_mfma_f32_16x16x32_bf16 v[90:93], v[150:153], v[198:201], v[90:93]
	v_mfma_f32_16x16x32_bf16 v[74:77], v[150:153], v[216:219], v[74:77]
	v_mfma_f32_16x16x32_bf16 v[78:81], v[142:145], v[216:219], v[78:81]
	v_mfma_f32_16x16x32_bf16 v[126:129], v[146:149], v[182:185], v[126:129]
	v_mfma_f32_16x16x32_bf16 v[122:125], v[158:161], v[182:185], v[122:125]
	v_mfma_f32_16x16x32_bf16 v[106:109], v[158:161], v[190:193], v[106:109]
	v_mfma_f32_16x16x32_bf16 v[110:113], v[146:149], v[190:193], v[110:113]
	v_mfma_f32_16x16x32_bf16 v[94:97], v[146:149], v[212:215], v[94:97]
	v_mfma_f32_16x16x32_bf16 v[90:93], v[158:161], v[212:215], v[90:93]
	v_mfma_f32_16x16x32_bf16 v[74:77], v[158:161], v[220:223], v[74:77]
	v_mfma_f32_16x16x32_bf16 v[78:81], v[146:149], v[220:223], v[78:81]
	s_setprio 0
	s_setprio 1
	v_mfma_f32_16x16x32_bf16 v[118:121], v[162:165], v[178:181], v[118:121]
	v_mfma_f32_16x16x32_bf16 v[114:117], v[170:173], v[178:181], v[114:117]
	v_mfma_f32_16x16x32_bf16 v[98:101], v[170:173], v[186:189], v[98:101]
	v_mfma_f32_16x16x32_bf16 v[102:105], v[162:165], v[186:189], v[102:105]
	v_mfma_f32_16x16x32_bf16 v[86:89], v[162:165], v[198:201], v[86:89]
	v_mfma_f32_16x16x32_bf16 v[82:85], v[170:173], v[198:201], v[82:85]
	v_mfma_f32_16x16x32_bf16 v[66:69], v[170:173], v[216:219], v[66:69]
	v_mfma_f32_16x16x32_bf16 v[70:73], v[162:165], v[216:219], v[70:73]
	v_mfma_f32_16x16x32_bf16 v[118:121], v[166:169], v[182:185], v[118:121]
	v_mfma_f32_16x16x32_bf16 v[114:117], v[174:177], v[182:185], v[114:117]
	v_mfma_f32_16x16x32_bf16 v[98:101], v[174:177], v[190:193], v[98:101]
	v_mfma_f32_16x16x32_bf16 v[102:105], v[166:169], v[190:193], v[102:105]
	v_mfma_f32_16x16x32_bf16 v[86:89], v[166:169], v[212:215], v[86:89]
	v_mfma_f32_16x16x32_bf16 v[82:85], v[174:177], v[212:215], v[82:85]
	v_mfma_f32_16x16x32_bf16 v[66:69], v[174:177], v[220:223], v[66:69]
	v_mfma_f32_16x16x32_bf16 v[70:73], v[166:169], v[220:223], v[70:73]
	s_setprio 0
	s_barrier
; #define PG8_STAGE(bufoff, gbase, voff) do { _Pragma("unroll") for (int _i = 0; _i < 2; ++_i) \
;         __builtin_amdgcn_global_load_lds((const unsigned*)((const char*)(gbase) + (voff)[_i]), (PG8_LAS unsigned*)(lds + (bufoff) + ldsw + _i * 8192), 16, 0, 0); } while (0)
; #define PG8_LDA(dst, b, h) do { _Pragma("unroll") for (int m = 0; m < 4; ++m) _Pragma("unroll") for (int k = 0; k < 2; ++k) dst[m][k] = *(const PG8_LAS bf16x8*)(lds + PG8_SA(b, h) + aoff + m * 2048 + k * 1024); } while (0)
; #define PG8_MMA(ai, bj, At, Bt) do { __builtin_amdgcn_s_setprio(1); _Pragma("unroll") for (int m = 0; m < 4; ++m) _Pragma("unroll") for (int n = 0; n < 2; ++n) _Pragma("unroll") for (int k = 0; k < 2; ++k) \
;         acc[ai][bj][m][n] = __builtin_amdgcn_mfma_f32_16x16x32_bf16(Bt[n][k], At[m][k], acc[ai][bj][m][n], 0, 0, 0); __builtin_amdgcn_s_setprio(0); } while (0)
; #define PG8_WAIT_V(n) asm volatile("s_waitcnt vmcnt(" #n ")" ::: "memory")
; #define PG8_WAIT_L(n) asm volatile("s_waitcnt lgkmcnt(" #n ")" ::: "memory")
; #define PG8_BAR __builtin_amdgcn_s_barrier()
; #define PG8_SCHED __builtin_amdgcn_sched_barrier(0)
; template <class Epi, class Sched, bool ALIGN_EPI = false, bool SP2 = false>
; __device__ __forceinline__ void gemm_phase(PG8_LAS unsigned char* lds, const Gemm g, const Sched& S, const Epi& E, const int tid) {
;     ...
;         for (int t = 0; t < nt; t += 2) {
;             const bool last = (t == nt - 2);
;             const char* a1 = cA + (size_t)(t + 1) * kstep;
;             const char* a2 = last ? nA : cA + (size_t)(t + 2) * kstep; const char* b2 = last ? nB : cB + (size_t)(t + 2) * kstep;
;             const char* a3 = a2 + kstep; const char* b3 = b2 + kstep;
;             if (last && has_next) S.a_ready(nxt);
;     ...
;             PG8_LDA(At, 1, 1); PG8_STAGE(PG8_SB(1, 0), b3, voffB); PG8_STAGE(PG8_SB(1, 1), b3 + hstepB, voffB); PG8_STAGE(PG8_SA(1, 0), a3, voffA);
;             PG8_WAIT_V(8); PG8_WAIT_L(0); PG8_BAR; PG8_MMA(1, 0, At, B0); PG8_MMA(1, 1, At, B1); PG8_BAR; PG8_SCHED;
	s_add_i32 s10, s61, s56
	v_lshl_add_u64 v[202:203], v[202:203], 0, s[70:71]
	s_mov_b32 m0, s10
	ds_read_b128 v[178:181], v157 offset:49152
	ds_read_b128 v[182:185], v157 offset:50176
	ds_read_b128 v[186:189], v157 offset:51200
	ds_read_b128 v[190:193], v157 offset:52224
	ds_read_b128 v[198:201], v157 offset:53248
	ds_read_b128 v[212:215], v157 offset:54272
	ds_read_b128 v[216:219], v157 offset:55296
	ds_read_b128 v[220:223], v157 offset:56320
	global_load_lds_dwordx4 v[202:203], off
	s_add_i32 m0, s10, 0x2000
	s_add_u32 s10, s92, 0x20080
	v_lshl_add_u64 v[202:203], v[224:225], 0, s[70:71]
	s_addc_u32 s11, s93, 0
	s_add_i32 s61, s88, s56
	global_load_lds_dwordx4 v[202:203], off
	v_lshl_add_u64 v[202:203], s[10:11], 0, v[132:133]
	s_mov_b32 m0, s61
	s_nop 0
	global_load_lds_dwordx4 v[202:203], off
	v_lshl_add_u64 v[202:203], s[10:11], 0, v[136:137]
	s_add_i32 m0, s61, 0x2000
	s_nop 0
	global_load_lds_dwordx4 v[202:203], off
	v_lshl_add_u64 v[202:203], v[226:227], 0, s[70:71]
	s_mov_b32 m0, s66
	s_nop 0
	global_load_lds_dwordx4 v[202:203], off
	v_lshl_add_u64 v[202:203], v[228:229], 0, s[70:71]
	s_mov_b32 m0, s67
	s_nop 0
	global_load_lds_dwordx4 v[202:203], off
	s_waitcnt vmcnt(8)
	s_waitcnt lgkmcnt(0)
	s_barrier
	s_setprio 1
	s_waitcnt lgkmcnt(0)
	v_mfma_f32_16x16x32_bf16 v[62:65], v[142:145], v[178:181], v[62:65]
	v_mfma_f32_16x16x32_bf16 v[58:61], v[150:153], v[178:181], v[58:61]
	v_mfma_f32_16x16x32_bf16 v[42:45], v[150:153], v[186:189], v[42:45]
	v_mfma_f32_16x16x32_bf16 v[46:49], v[142:145], v[186:189], v[46:49]
	v_mfma_f32_16x16x32_bf16 v[30:33], v[142:145], v[198:201], v[30:33]
	v_mfma_f32_16x16x32_bf16 v[26:29], v[150:153], v[198:201], v[26:29]
	v_mfma_f32_16x16x32_bf16 v[10:13], v[150:153], v[216:219], v[10:13]
	v_mfma_f32_16x16x32_bf16 v[14:17], v[142:145], v[216:219], v[14:17]
	v_mfma_f32_16x16x32_bf16 v[62:65], v[146:149], v[182:185], v[62:65]
	v_mfma_f32_16x16x32_bf16 v[58:61], v[158:161], v[182:185], v[58:61]
	v_mfma_f32_16x16x32_bf16 v[42:45], v[158:161], v[190:193], v[42:45]
	v_mfma_f32_16x16x32_bf16 v[46:49], v[146:149], v[190:193], v[46:49]
	v_mfma_f32_16x16x32_bf16 v[30:33], v[146:149], v[212:215], v[30:33]
	v_mfma_f32_16x16x32_bf16 v[26:29], v[158:161], v[212:215], v[26:29]
	v_mfma_f32_16x16x32_bf16 v[10:13], v[158:161], v[220:223], v[10:13]
	v_mfma_f32_16x16x32_bf16 v[14:17], v[146:149], v[220:223], v[14:17]
	s_setprio 0
	s_setprio 1
	v_mfma_f32_16x16x32_bf16 v[54:57], v[162:165], v[178:181], v[54:57]
	v_mfma_f32_16x16x32_bf16 v[50:53], v[170:173], v[178:181], v[50:53]
	v_mfma_f32_16x16x32_bf16 v[34:37], v[170:173], v[186:189], v[34:37]
	v_mfma_f32_16x16x32_bf16 v[38:41], v[162:165], v[186:189], v[38:41]
	v_mfma_f32_16x16x32_bf16 v[22:25], v[162:165], v[198:201], v[22:25]
	v_mfma_f32_16x16x32_bf16 v[18:21], v[170:173], v[198:201], v[18:21]
	v_mfma_f32_16x16x32_bf16 v[2:5], v[170:173], v[216:219], v[2:5]
	v_mfma_f32_16x16x32_bf16 v[6:9], v[162:165], v[216:219], v[6:9]
	v_mfma_f32_16x16x32_bf16 v[54:57], v[166:169], v[182:185], v[54:57]
	v_mfma_f32_16x16x32_bf16 v[50:53], v[174:177], v[182:185], v[50:53]
	v_mfma_f32_16x16x32_bf16 v[34:37], v[174:177], v[190:193], v[34:37]
	v_mfma_f32_16x16x32_bf16 v[38:41], v[166:169], v[190:193], v[38:41]
	v_mfma_f32_16x16x32_bf16 v[22:25], v[166:169], v[212:215], v[22:25]
	v_mfma_f32_16x16x32_bf16 v[18:21], v[174:177], v[212:215], v[18:21]
	v_mfma_f32_16x16x32_bf16 v[2:5], v[174:177], v[220:223], v[2:5]
	v_mfma_f32_16x16x32_bf16 v[6:9], v[166:169], v[220:223], v[6:9]
	s_setprio 0
	s_barrier
	s_add_i32 s62, s62, 2
	s_add_u32 s31, s31, 0x100
	s_addc_u32 s60, s60, 0
	s_add_u32 s2, s2, 0x100
	s_addc_u32 s3, s3, 0
	s_cmp_gt_u32 s62, 5
	s_cbranch_scc0 .LBB0_109
	s_and_b64 vcc, exec, s[26:27]
	s_cbranch_vccz .LBB0_112
	s_barrier

; #define PG8_STAGE(bufoff, gbase, voff) do { _Pragma("unroll") for (int _i = 0; _i < 2; ++_i) \
;         __builtin_amdgcn_global_load_lds((const unsigned*)((const char*)(gbase) + (voff)[_i]), (PG8_LAS unsigned*)(lds + (bufoff) + ldsw + _i * 8192), 16, 0, 0); } while (0)
; #define PG8_LDA(dst, b, h) do { _Pragma("unroll") for (int m = 0; m < 4; ++m) _Pragma("unroll") for (int k = 0; k < 2; ++k) dst[m][k] = *(const PG8_LAS bf16x8*)(lds + PG8_SA(b, h) + aoff + m * 2048 + k * 1024); } while (0)
; #define PG8_LDB(dst, b, h) do { _Pragma("unroll") for (int n = 0; n < 2; ++n) _Pragma("unroll") for (int k = 0; k < 2; ++k) dst[n][k] = *(const PG8_LAS bf16x8*)(lds + PG8_SB(b, h) + boff + n * 2048 + k * 1024); } while (0)
; #define PG8_MMA(ai, bj, At, Bt) do { __builtin_amdgcn_s_setprio(1); _Pragma("unroll") for (int m = 0; m < 4; ++m) _Pragma("unroll") for (int n = 0; n < 2; ++n) _Pragma("unroll") for (int k = 0; k < 2; ++k) \
;         acc[ai][bj][m][n] = __builtin_amdgcn_mfma_f32_16x16x32_bf16(Bt[n][k], At[m][k], acc[ai][bj][m][n], 0, 0, 0); __builtin_amdgcn_s_setprio(0); } while (0)
; #define PG8_WAIT_V(n) asm volatile("s_waitcnt vmcnt(" #n ")" ::: "memory")
; #define PG8_WAIT_L(n) asm volatile("s_waitcnt lgkmcnt(" #n ")" ::: "memory")
; #define PG8_BAR __builtin_amdgcn_s_barrier()
; #define PG8_SCHED __builtin_amdgcn_sched_barrier(0)
; template <class Epi, class Sched, bool ALIGN_EPI = false, bool SP2 = false>
; __device__ __forceinline__ void gemm_phase(PG8_LAS unsigned char* lds, const Gemm g, const Sched& S, const Epi& E, const int tid) {
;     ...
;             PG8_LDB(B0, 0, 0); PG8_LDB(B1, 0, 1); PG8_SCHED; PG8_LDA(At, 0, 0); PG8_STAGE(PG8_SA(1, 1), a1 + hstepA, voffA);
;             PG8_WAIT_V(8); PG8_WAIT_L(0); PG8_BAR; PG8_MMA(0, 0, At, B0); PG8_MMA(0, 1, At, B1); PG8_BAR; PG8_SCHED;
;             PG8_LDA(At, 0, 1); PG8_STAGE(PG8_SB(0, 0), b2, voffB); PG8_STAGE(PG8_SB(0, 1), b2 + hstepB, voffB); PG8_STAGE(PG8_SA(0, 0), a2, voffA);
;             PG8_WAIT_V(8); PG8_WAIT_L(0); PG8_BAR; PG8_MMA(1, 0, At, B0); PG8_MMA(1, 1, At, B1); PG8_BAR; PG8_SCHED;
.LBB0_165:
	s_add_u32 s10, s2, 0xfffc0080
	s_addc_u32 s11, s3, -1
	s_add_i32 s61, 0, 0x10000
	s_cmp_eq_u32 s62, 4
	s_cselect_b32 s93, s21, s11
	s_cselect_b32 s92, s97, s10
	s_cselect_b32 s35, s25, s60
	s_cselect_b32 s34, vcc_lo, vcc_hi
	s_add_i32 s88, 0, 0x14000
	v_add_u32_e32 v158, s61, v147
	v_add_u32_e32 v174, s88, v147
	ds_read_b128 v[142:145], v158
	ds_read_b128 v[150:153], v158 offset:1024
	ds_read_b128 v[154:157], v158 offset:2048
	ds_read_b128 v[158:161], v158 offset:3072
	ds_read_b128 v[162:165], v174
	ds_read_b128 v[166:169], v174 offset:1024
	ds_read_b128 v[170:173], v174 offset:2048
	ds_read_b128 v[174:177], v174 offset:3072
	v_lshl_add_u64 v[202:203], s[2:3], 0, v[140:141]
	s_add_i32 m0, s63, 0xc000
	ds_read_b128 v[178:181], v149
	ds_read_b128 v[182:185], v149 offset:1024
	ds_read_b128 v[186:189], v149 offset:2048
	ds_read_b128 v[190:193], v149 offset:3072
	ds_read_b128 v[198:201], v149 offset:4096
	ds_read_b128 v[212:215], v149 offset:5120
	ds_read_b128 v[216:219], v149 offset:6144
	ds_read_b128 v[220:223], v149 offset:7168
	global_load_lds_dwordx4 v[202:203], off
	v_lshl_add_u64 v[202:203], s[2:3], 0, v[138:139]
	s_add_i32 m0, s63, 0xe000
	s_nop 0
	global_load_lds_dwordx4 v[202:203], off
	s_waitcnt vmcnt(8)
	s_waitcnt lgkmcnt(0)
	s_barrier
	s_setprio 1
	s_waitcnt lgkmcnt(0)
	v_mfma_f32_16x16x32_bf16 v[126:129], v[142:145], v[178:181], v[126:129]
	v_mfma_f32_16x16x32_bf16 v[122:125], v[154:157], v[178:181], v[122:125]
	v_mfma_f32_16x16x32_bf16 v[106:109], v[154:157], v[186:189], v[106:109]
	v_mfma_f32_16x16x32_bf16 v[110:113], v[142:145], v[186:189], v[110:113]
	v_mfma_f32_16x16x32_bf16 v[94:97], v[142:145], v[198:201], v[94:97]
	v_mfma_f32_16x16x32_bf16 v[90:93], v[154:157], v[198:201], v[90:93]
	v_mfma_f32_16x16x32_bf16 v[74:77], v[154:157], v[216:219], v[74:77]
	v_mfma_f32_16x16x32_bf16 v[78:81], v[142:145], v[216:219], v[78:81]
	v_mfma_f32_16x16x32_bf16 v[126:129], v[150:153], v[182:185], v[126:129]
	v_mfma_f32_16x16x32_bf16 v[122:125], v[158:161], v[182:185], v[122:125]
	v_mfma_f32_16x16x32_bf16 v[106:109], v[158:161], v[190:193], v[106:109]
	v_mfma_f32_16x16x32_bf16 v[110:113], v[150:153], v[190:193], v[110:113]
	v_mfma_f32_16x16x32_bf16 v[94:97], v[150:153], v[212:215], v[94:97]
	v_mfma_f32_16x16x32_bf16 v[90:93], v[158:161], v[212:215], v[90:93]
	v_mfma_f32_16x16x32_bf16 v[74:77], v[158:161], v[220:223], v[74:77]
	v_mfma_f32_16x16x32_bf16 v[78:81], v[150:153], v[220:223], v[78:81]
	s_setprio 0
	s_setprio 1
	v_mfma_f32_16x16x32_bf16 v[118:121], v[162:165], v[178:181], v[118:121]
	v_mfma_f32_16x16x32_bf16 v[114:117], v[170:173], v[178:181], v[114:117]
	v_mfma_f32_16x16x32_bf16 v[98:101], v[170:173], v[186:189], v[98:101]
	v_mfma_f32_16x16x32_bf16 v[102:105], v[162:165], v[186:189], v[102:105]
	v_mfma_f32_16x16x32_bf16 v[86:89], v[162:165], v[198:201], v[86:89]
	v_mfma_f32_16x16x32_bf16 v[82:85], v[170:173], v[198:201], v[82:85]
	v_mfma_f32_16x16x32_bf16 v[66:69], v[170:173], v[216:219], v[66:69]
	v_mfma_f32_16x16x32_bf16 v[70:73], v[162:165], v[216:219], v[70:73]
	v_mfma_f32_16x16x32_bf16 v[118:121], v[166:169], v[182:185], v[118:121]
	v_mfma_f32_16x16x32_bf16 v[114:117], v[174:177], v[182:185], v[114:117]
	v_mfma_f32_16x16x32_bf16 v[98:101], v[174:177], v[190:193], v[98:101]
	v_mfma_f32_16x16x32_bf16 v[102:105], v[166:169], v[190:193], v[102:105]
	v_mfma_f32_16x16x32_bf16 v[86:89], v[166:169], v[212:215], v[86:89]
	v_mfma_f32_16x16x32_bf16 v[82:85], v[174:177], v[212:215], v[82:85]
	v_mfma_f32_16x16x32_bf16 v[66:69], v[174:177], v[220:223], v[66:69]
	v_mfma_f32_16x16x32_bf16 v[70:73], v[166:169], v[220:223], v[70:73]
	s_setprio 0
	s_barrier
	s_add_i32 s10, s61, s56
	v_lshl_add_u64 v[202:203], s[34:35], 0, v[132:133]
	s_mov_b32 m0, s10
	ds_read_b128 v[178:181], v149 offset:16384
	ds_read_b128 v[182:185], v149 offset:17408
	ds_read_b128 v[186:189], v149 offset:18432
	ds_read_b128 v[190:193], v149 offset:19456
	ds_read_b128 v[198:201], v149 offset:20480
	ds_read_b128 v[212:215], v149 offset:21504
	ds_read_b128 v[216:219], v149 offset:22528
	ds_read_b128 v[220:223], v149 offset:23552
	global_load_lds_dwordx4 v[202:203], off
	s_add_i32 m0, s10, 0x2000
	s_add_u32 s10, s34, 0x20000
	v_lshl_add_u64 v[224:225], s[34:35], 0, v[136:137]
	s_addc_u32 s11, s35, 0
	s_add_i32 s61, s88, s56
	global_load_lds_dwordx4 v[224:225], off
	v_lshl_add_u64 v[226:227], s[10:11], 0, v[132:133]
	s_mov_b32 m0, s61
	v_lshl_add_u64 v[228:229], s[92:93], 0, v[134:135]
	global_load_lds_dwordx4 v[226:227], off
	v_lshl_add_u64 v[226:227], s[10:11], 0, v[136:137]
	s_add_i32 m0, s61, 0x2000
	s_nop 0
	global_load_lds_dwordx4 v[226:227], off
	v_lshl_add_u64 v[226:227], s[92:93], 0, v[130:131]
	s_mov_b32 m0, s63
	s_nop 0
	global_load_lds_dwordx4 v[226:227], off
	s_mov_b32 m0, s64
	s_nop 0
	global_load_lds_dwordx4 v[228:229], off
	s_waitcnt vmcnt(8)
	s_waitcnt lgkmcnt(0)
	s_barrier
; #define PG8_STAGE(bufoff, gbase, voff) do { _Pragma("unroll") for (int _i = 0; _i < 2; ++_i) \
;         __builtin_amdgcn_global_load_lds((const unsigned*)((const char*)(gbase) + (voff)[_i]), (PG8_LAS unsigned*)(lds + (bufoff) + ldsw + _i * 8192), 16, 0, 0); } while (0)
; #define PG8_LDA(dst, b, h) do { _Pragma("unroll") for (int m = 0; m < 4; ++m) _Pragma("unroll") for (int k = 0; k < 2; ++k) dst[m][k] = *(const PG8_LAS bf16x8*)(lds + PG8_SA(b, h) + aoff + m * 2048 + k * 1024); } while (0)
; #define PG8_LDB(dst, b, h) do { _Pragma("unroll") for (int n = 0; n < 2; ++n) _Pragma("unroll") for (int k = 0; k < 2; ++k) dst[n][k] = *(const PG8_LAS bf16x8*)(lds + PG8_SB(b, h) + boff + n * 2048 + k * 1024); } while (0)
; #define PG8_MMA(ai, bj, At, Bt) do { __builtin_amdgcn_s_setprio(1); _Pragma("unroll") for (int m = 0; m < 4; ++m) _Pragma("unroll") for (int n = 0; n < 2; ++n) _Pragma("unroll") for (int k = 0; k < 2; ++k) \
;         acc[ai][bj][m][n] = __builtin_amdgcn_mfma_f32_16x16x32_bf16(Bt[n][k], At[m][k], acc[ai][bj][m][n], 0, 0, 0); __builtin_amdgcn_s_setprio(0); } while (0)
; #define PG8_WAIT_V(n) asm volatile("s_waitcnt vmcnt(" #n ")" ::: "memory")
; #define PG8_WAIT_L(n) asm volatile("s_waitcnt lgkmcnt(" #n ")" ::: "memory")
; #define PG8_BAR __builtin_amdgcn_s_barrier()
; #define PG8_SCHED __builtin_amdgcn_sched_barrier(0)
; template <class Epi, class Sched, bool ALIGN_EPI = false, bool SP2 = false>
; __device__ __forceinline__ void gemm_phase(PG8_LAS unsigned char* lds, const Gemm g, const Sched& S, const Epi& E, const int tid) {
;     ...
;             PG8_WAIT_V(8); PG8_WAIT_L(0); PG8_BAR; PG8_MMA(1, 0, At, B0); PG8_MMA(1, 1, At, B1); PG8_BAR; PG8_SCHED;
;             PG8_LDB(B0, 1, 0); PG8_LDB(B1, 1, 1); PG8_SCHED; PG8_LDA(At, 1, 0); PG8_STAGE(PG8_SA(0, 1), a2 + hstepA, voffA);
;             PG8_WAIT_V(8); PG8_WAIT_L(0); PG8_BAR; PG8_MMA(0, 0, At, B0); PG8_MMA(0, 1, At, B1); PG8_BAR; PG8_SCHED;
	s_setprio 1
	s_waitcnt lgkmcnt(0)
	v_mfma_f32_16x16x32_bf16 v[62:65], v[142:145], v[178:181], v[62:65]
	v_mfma_f32_16x16x32_bf16 v[58:61], v[154:157], v[178:181], v[58:61]
	v_mfma_f32_16x16x32_bf16 v[42:45], v[154:157], v[186:189], v[42:45]
	v_mfma_f32_16x16x32_bf16 v[46:49], v[142:145], v[186:189], v[46:49]
	v_mfma_f32_16x16x32_bf16 v[30:33], v[142:145], v[198:201], v[30:33]
	v_mfma_f32_16x16x32_bf16 v[26:29], v[154:157], v[198:201], v[26:29]
	v_mfma_f32_16x16x32_bf16 v[10:13], v[154:157], v[216:219], v[10:13]
	v_mfma_f32_16x16x32_bf16 v[14:17], v[142:145], v[216:219], v[14:17]
	v_mfma_f32_16x16x32_bf16 v[62:65], v[150:153], v[182:185], v[62:65]
	v_mfma_f32_16x16x32_bf16 v[58:61], v[158:161], v[182:185], v[58:61]
	v_mfma_f32_16x16x32_bf16 v[42:45], v[158:161], v[190:193], v[42:45]
	v_mfma_f32_16x16x32_bf16 v[46:49], v[150:153], v[190:193], v[46:49]
	v_mfma_f32_16x16x32_bf16 v[30:33], v[150:153], v[212:215], v[30:33]
	v_mfma_f32_16x16x32_bf16 v[26:29], v[158:161], v[212:215], v[26:29]
	v_mfma_f32_16x16x32_bf16 v[10:13], v[158:161], v[220:223], v[10:13]
	v_mfma_f32_16x16x32_bf16 v[14:17], v[150:153], v[220:223], v[14:17]
	s_setprio 0
	s_setprio 1
	v_mfma_f32_16x16x32_bf16 v[54:57], v[162:165], v[178:181], v[54:57]
	v_mfma_f32_16x16x32_bf16 v[50:53], v[170:173], v[178:181], v[50:53]
	v_mfma_f32_16x16x32_bf16 v[34:37], v[170:173], v[186:189], v[34:37]
	v_mfma_f32_16x16x32_bf16 v[38:41], v[162:165], v[186:189], v[38:41]
	v_mfma_f32_16x16x32_bf16 v[22:25], v[162:165], v[198:201], v[22:25]
	v_mfma_f32_16x16x32_bf16 v[18:21], v[170:173], v[198:201], v[18:21]
	v_mfma_f32_16x16x32_bf16 v[2:5], v[170:173], v[216:219], v[2:5]
	v_mfma_f32_16x16x32_bf16 v[6:9], v[162:165], v[216:219], v[6:9]
	v_mfma_f32_16x16x32_bf16 v[54:57], v[166:169], v[182:185], v[54:57]
	v_mfma_f32_16x16x32_bf16 v[50:53], v[174:177], v[182:185], v[50:53]
	v_mfma_f32_16x16x32_bf16 v[34:37], v[174:177], v[190:193], v[34:37]
	v_mfma_f32_16x16x32_bf16 v[38:41], v[166:169], v[190:193], v[38:41]
	v_mfma_f32_16x16x32_bf16 v[22:25], v[166:169], v[212:215], v[22:25]
	v_mfma_f32_16x16x32_bf16 v[18:21], v[174:177], v[212:215], v[18:21]
	v_mfma_f32_16x16x32_bf16 v[2:5], v[174:177], v[220:223], v[2:5]
	v_mfma_f32_16x16x32_bf16 v[6:9], v[166:169], v[220:223], v[6:9]
	s_setprio 0
	s_barrier
	s_add_i32 s61, 0, 0x18000
	s_add_i32 s88, 0, 0x1c000
	v_add_u32_e32 v158, s61, v147
	v_add_u32_e32 v174, s88, v147
	ds_read_b128 v[142:145], v158
	ds_read_b128 v[150:153], v158 offset:1024
	ds_read_b128 v[154:157], v158 offset:2048
	ds_read_b128 v[158:161], v158 offset:3072
	ds_read_b128 v[162:165], v174
	ds_read_b128 v[166:169], v174 offset:1024
	ds_read_b128 v[170:173], v174 offset:2048
	ds_read_b128 v[174:177], v174 offset:3072
	s_add_u32 s10, s92, 0x40000
	s_addc_u32 s11, s93, 0
	s_mov_b32 m0, s65
	v_lshl_add_u64 v[230:231], s[10:11], 0, v[130:131]
	ds_read_b128 v[178:181], v149 offset:32768
	ds_read_b128 v[182:185], v149 offset:33792
	ds_read_b128 v[186:189], v149 offset:34816
	ds_read_b128 v[190:193], v149 offset:35840
	ds_read_b128 v[198:201], v149 offset:36864
	ds_read_b128 v[212:215], v149 offset:37888
	ds_read_b128 v[216:219], v149 offset:38912
	ds_read_b128 v[220:223], v149 offset:39936
	global_load_lds_dwordx4 v[230:231], off
	v_lshl_add_u64 v[230:231], s[10:11], 0, v[134:135]
	s_mov_b32 m0, s66
	s_nop 0
	global_load_lds_dwordx4 v[230:231], off
	s_waitcnt vmcnt(8)
	s_waitcnt lgkmcnt(0)
	s_barrier
	s_setprio 1
	s_waitcnt lgkmcnt(0)
	v_mfma_f32_16x16x32_bf16 v[126:129], v[142:145], v[178:181], v[126:129]
	v_mfma_f32_16x16x32_bf16 v[122:125], v[154:157], v[178:181], v[122:125]
	v_mfma_f32_16x16x32_bf16 v[106:109], v[154:157], v[186:189], v[106:109]
	v_mfma_f32_16x16x32_bf16 v[110:113], v[142:145], v[186:189], v[110:113]
	v_mfma_f32_16x16x32_bf16 v[94:97], v[142:145], v[198:201], v[94:97]
	v_mfma_f32_16x16x32_bf16 v[90:93], v[154:157], v[198:201], v[90:93]
	v_mfma_f32_16x16x32_bf16 v[74:77], v[154:157], v[216:219], v[74:77]
	v_mfma_f32_16x16x32_bf16 v[78:81], v[142:145], v[216:219], v[78:81]
	v_mfma_f32_16x16x32_bf16 v[126:129], v[150:153], v[182:185], v[126:129]
	v_mfma_f32_16x16x32_bf16 v[122:125], v[158:161], v[182:185], v[122:125]
	v_mfma_f32_16x16x32_bf16 v[106:109], v[158:161], v[190:193], v[106:109]
	v_mfma_f32_16x16x32_bf16 v[110:113], v[150:153], v[190:193], v[110:113]
	v_mfma_f32_16x16x32_bf16 v[94:97], v[150:153], v[212:215], v[94:97]
	v_mfma_f32_16x16x32_bf16 v[90:93], v[158:161], v[212:215], v[90:93]
	v_mfma_f32_16x16x32_bf16 v[74:77], v[158:161], v[220:223], v[74:77]
	v_mfma_f32_16x16x32_bf16 v[78:81], v[150:153], v[220:223], v[78:81]
	s_setprio 0
	s_setprio 1
	v_mfma_f32_16x16x32_bf16 v[118:121], v[162:165], v[178:181], v[118:121]
	v_mfma_f32_16x16x32_bf16 v[114:117], v[170:173], v[178:181], v[114:117]
	v_mfma_f32_16x16x32_bf16 v[98:101], v[170:173], v[186:189], v[98:101]
	v_mfma_f32_16x16x32_bf16 v[102:105], v[162:165], v[186:189], v[102:105]
	v_mfma_f32_16x16x32_bf16 v[86:89], v[162:165], v[198:201], v[86:89]
	v_mfma_f32_16x16x32_bf16 v[82:85], v[170:173], v[198:201], v[82:85]
	v_mfma_f32_16x16x32_bf16 v[66:69], v[170:173], v[216:219], v[66:69]
	v_mfma_f32_16x16x32_bf16 v[70:73], v[162:165], v[216:219], v[70:73]
	v_mfma_f32_16x16x32_bf16 v[118:121], v[166:169], v[182:185], v[118:121]
	v_mfma_f32_16x16x32_bf16 v[114:117], v[174:177], v[182:185], v[114:117]
	v_mfma_f32_16x16x32_bf16 v[98:101], v[174:177], v[190:193], v[98:101]
	v_mfma_f32_16x16x32_bf16 v[102:105], v[166:169], v[190:193], v[102:105]
	v_mfma_f32_16x16x32_bf16 v[86:89], v[166:169], v[212:215], v[86:89]
	v_mfma_f32_16x16x32_bf16 v[82:85], v[174:177], v[212:215], v[82:85]
	v_mfma_f32_16x16x32_bf16 v[66:69], v[174:177], v[220:223], v[66:69]
	v_mfma_f32_16x16x32_bf16 v[70:73], v[166:169], v[220:223], v[70:73]
	s_setprio 0
	s_barrier
; #define PG8_STAGE(bufoff, gbase, voff) do { _Pragma("unroll") for (int _i = 0; _i < 2; ++_i) \
;         __builtin_amdgcn_global_load_lds((const unsigned*)((const char*)(gbase) + (voff)[_i]), (PG8_LAS unsigned*)(lds + (bufoff) + ldsw + _i * 8192), 16, 0, 0); } while (0)
; #define PG8_LDA(dst, b, h) do { _Pragma("unroll") for (int m = 0; m < 4; ++m) _Pragma("unroll") for (int k = 0; k < 2; ++k) dst[m][k] = *(const PG8_LAS bf16x8*)(lds + PG8_SA(b, h) + aoff + m * 2048 + k * 1024); } while (0)
; #define PG8_MMA(ai, bj, At, Bt) do { __builtin_amdgcn_s_setprio(1); _Pragma("unroll") for (int m = 0; m < 4; ++m) _Pragma("unroll") for (int n = 0; n < 2; ++n) _Pragma("unroll") for (int k = 0; k < 2; ++k) \
;         acc[ai][bj][m][n] = __builtin_amdgcn_mfma_f32_16x16x32_bf16(Bt[n][k], At[m][k], acc[ai][bj][m][n], 0, 0, 0); __builtin_amdgcn_s_setprio(0); } while (0)
; #define PG8_WAIT_V(n) asm volatile("s_waitcnt vmcnt(" #n ")" ::: "memory")
; #define PG8_WAIT_L(n) asm volatile("s_waitcnt lgkmcnt(" #n ")" ::: "memory")
; #define PG8_BAR __builtin_amdgcn_s_barrier()
; #define PG8_SCHED __builtin_amdgcn_sched_barrier(0)
; template <class Epi, class Sched, bool ALIGN_EPI = false, bool SP2 = false>
; __device__ __forceinline__ void gemm_phase(PG8_LAS unsigned char* lds, const Gemm g, const Sched& S, const Epi& E, const int tid) {
;     ...
;         for (int t = 0; t < nt; t += 2) {
;             const bool last = (t == nt - 2);
;             const char* a1 = cA + (size_t)(t + 1) * kstep;
;             const char* a2 = last ? nA : cA + (size_t)(t + 2) * kstep; const char* b2 = last ? nB : cB + (size_t)(t + 2) * kstep;
;             const char* a3 = a2 + kstep; const char* b3 = b2 + kstep;
;             if (last && has_next) S.a_ready(nxt);
;     ...
;             PG8_LDA(At, 1, 1); PG8_STAGE(PG8_SB(1, 0), b3, voffB); PG8_STAGE(PG8_SB(1, 1), b3 + hstepB, voffB); PG8_STAGE(PG8_SA(1, 0), a3, voffA);
;             PG8_WAIT_V(8); PG8_WAIT_L(0); PG8_BAR; PG8_MMA(1, 0, At, B0); PG8_MMA(1, 1, At, B1); PG8_BAR; PG8_SCHED;
	s_add_i32 s10, s61, s56
	v_lshl_add_u64 v[202:203], v[202:203], 0, s[70:71]
	s_mov_b32 m0, s10
	ds_read_b128 v[178:181], v149 offset:49152
	ds_read_b128 v[182:185], v149 offset:50176
	ds_read_b128 v[186:189], v149 offset:51200
	ds_read_b128 v[190:193], v149 offset:52224
	ds_read_b128 v[198:201], v149 offset:53248
	ds_read_b128 v[212:215], v149 offset:54272
	ds_read_b128 v[216:219], v149 offset:55296
	ds_read_b128 v[220:223], v149 offset:56320
	global_load_lds_dwordx4 v[202:203], off
	s_add_i32 m0, s10, 0x2000
	s_add_u32 s10, s34, 0x20080
	v_lshl_add_u64 v[202:203], v[224:225], 0, s[70:71]
	s_addc_u32 s11, s35, 0
	s_add_i32 s34, s88, s56
	global_load_lds_dwordx4 v[202:203], off
	v_lshl_add_u64 v[202:203], s[10:11], 0, v[132:133]
	s_mov_b32 m0, s34
	s_nop 0
	global_load_lds_dwordx4 v[202:203], off
	v_lshl_add_u64 v[202:203], s[10:11], 0, v[136:137]
	s_add_i32 m0, s34, 0x2000
	s_nop 0
	global_load_lds_dwordx4 v[202:203], off
	v_lshl_add_u64 v[202:203], v[226:227], 0, s[70:71]
	s_mov_b32 m0, s23
	s_nop 0
	global_load_lds_dwordx4 v[202:203], off
	v_lshl_add_u64 v[202:203], v[228:229], 0, s[70:71]
	s_mov_b32 m0, s67
	s_nop 0
	global_load_lds_dwordx4 v[202:203], off
	s_waitcnt vmcnt(8)
	s_waitcnt lgkmcnt(0)
	s_barrier
	s_setprio 1
	s_waitcnt lgkmcnt(0)
	v_mfma_f32_16x16x32_bf16 v[62:65], v[142:145], v[178:181], v[62:65]
	v_mfma_f32_16x16x32_bf16 v[58:61], v[154:157], v[178:181], v[58:61]
	v_mfma_f32_16x16x32_bf16 v[42:45], v[154:157], v[186:189], v[42:45]
	v_mfma_f32_16x16x32_bf16 v[46:49], v[142:145], v[186:189], v[46:49]
	v_mfma_f32_16x16x32_bf16 v[30:33], v[142:145], v[198:201], v[30:33]
	v_mfma_f32_16x16x32_bf16 v[26:29], v[154:157], v[198:201], v[26:29]
	v_mfma_f32_16x16x32_bf16 v[10:13], v[154:157], v[216:219], v[10:13]
	v_mfma_f32_16x16x32_bf16 v[14:17], v[142:145], v[216:219], v[14:17]
	v_mfma_f32_16x16x32_bf16 v[62:65], v[150:153], v[182:185], v[62:65]
	v_mfma_f32_16x16x32_bf16 v[58:61], v[158:161], v[182:185], v[58:61]
	v_mfma_f32_16x16x32_bf16 v[42:45], v[158:161], v[190:193], v[42:45]
	v_mfma_f32_16x16x32_bf16 v[46:49], v[150:153], v[190:193], v[46:49]
	v_mfma_f32_16x16x32_bf16 v[30:33], v[150:153], v[212:215], v[30:33]
	v_mfma_f32_16x16x32_bf16 v[26:29], v[158:161], v[212:215], v[26:29]
	v_mfma_f32_16x16x32_bf16 v[10:13], v[158:161], v[220:223], v[10:13]
	v_mfma_f32_16x16x32_bf16 v[14:17], v[150:153], v[220:223], v[14:17]
	s_setprio 0
	s_setprio 1
	v_mfma_f32_16x16x32_bf16 v[54:57], v[162:165], v[178:181], v[54:57]
	v_mfma_f32_16x16x32_bf16 v[50:53], v[170:173], v[178:181], v[50:53]
	v_mfma_f32_16x16x32_bf16 v[34:37], v[170:173], v[186:189], v[34:37]
	v_mfma_f32_16x16x32_bf16 v[38:41], v[162:165], v[186:189], v[38:41]
	v_mfma_f32_16x16x32_bf16 v[22:25], v[162:165], v[198:201], v[22:25]
	v_mfma_f32_16x16x32_bf16 v[18:21], v[170:173], v[198:201], v[18:21]
	v_mfma_f32_16x16x32_bf16 v[2:5], v[170:173], v[216:219], v[2:5]
	v_mfma_f32_16x16x32_bf16 v[6:9], v[162:165], v[216:219], v[6:9]
	v_mfma_f32_16x16x32_bf16 v[54:57], v[166:169], v[182:185], v[54:57]
	v_mfma_f32_16x16x32_bf16 v[50:53], v[174:177], v[182:185], v[50:53]
	v_mfma_f32_16x16x32_bf16 v[34:37], v[174:177], v[190:193], v[34:37]
	v_mfma_f32_16x16x32_bf16 v[38:41], v[166:169], v[190:193], v[38:41]
	v_mfma_f32_16x16x32_bf16 v[22:25], v[166:169], v[212:215], v[22:25]
	v_mfma_f32_16x16x32_bf16 v[18:21], v[174:177], v[212:215], v[18:21]
	v_mfma_f32_16x16x32_bf16 v[2:5], v[174:177], v[220:223], v[2:5]
	v_mfma_f32_16x16x32_bf16 v[6:9], v[166:169], v[220:223], v[6:9]
	s_setprio 0
	s_barrier
	s_add_i32 s62, s62, 2
	s_add_u32 vcc_hi, vcc_hi, 0x100
	s_addc_u32 s60, s60, 0
	s_add_u32 s2, s2, 0x100
	s_addc_u32 s3, s3, 0
	s_cmp_gt_u32 s62, 5
	s_cbranch_scc0 .LBB0_165
	s_and_b64 vcc, exec, s[18:19]
	s_cbranch_vccz .LBB0_168
	s_barrier

; #define PG8_STAGE(bufoff, gbase, voff) do { _Pragma("unroll") for (int _i = 0; _i < 2; ++_i) \
;         __builtin_amdgcn_global_load_lds((const unsigned*)((const char*)(gbase) + (voff)[_i]), (PG8_LAS unsigned*)(lds + (bufoff) + ldsw + _i * 8192), 16, 0, 0); } while (0)
; #define PG8_LDA(dst, b, h) do { _Pragma("unroll") for (int m = 0; m < 4; ++m) _Pragma("unroll") for (int k = 0; k < 2; ++k) dst[m][k] = *(const PG8_LAS bf16x8*)(lds + PG8_SA(b, h) + aoff + m * 2048 + k * 1024); } while (0)
; #define PG8_LDB(dst, b, h) do { _Pragma("unroll") for (int n = 0; n < 2; ++n) _Pragma("unroll") for (int k = 0; k < 2; ++k) dst[n][k] = *(const PG8_LAS bf16x8*)(lds + PG8_SB(b, h) + boff + n * 2048 + k * 1024); } while (0)
; #define PG8_MMA(ai, bj, At, Bt) do { __builtin_amdgcn_s_setprio(1); _Pragma("unroll") for (int m = 0; m < 4; ++m) _Pragma("unroll") for (int n = 0; n < 2; ++n) _Pragma("unroll") for (int k = 0; k < 2; ++k) \
;         acc[ai][bj][m][n] = __builtin_amdgcn_mfma_f32_16x16x32_bf16(Bt[n][k], At[m][k], acc[ai][bj][m][n], 0, 0, 0); __builtin_amdgcn_s_setprio(0); } while (0)
; #define PG8_WAIT_V(n) asm volatile("s_waitcnt vmcnt(" #n ")" ::: "memory")
; #define PG8_WAIT_L(n) asm volatile("s_waitcnt lgkmcnt(" #n ")" ::: "memory")
; #define PG8_BAR __builtin_amdgcn_s_barrier()
; #define PG8_SCHED __builtin_amdgcn_sched_barrier(0)
; template <class Epi, class Sched, bool ALIGN_EPI = false, bool SP2 = false>
; __device__ __forceinline__ void gemm_phase(PG8_LAS unsigned char* lds, const Gemm g, const Sched& S, const Epi& E, const int tid) {
;     ...
;             PG8_LDB(B0, 0, 0); PG8_LDB(B1, 0, 1); PG8_SCHED; PG8_LDA(At, 0, 0); PG8_STAGE(PG8_SA(1, 1), a1 + hstepA, voffA);
;             PG8_WAIT_V(8); PG8_WAIT_L(0); PG8_BAR; PG8_MMA(0, 0, At, B0); PG8_MMA(0, 1, At, B1); PG8_BAR; PG8_SCHED;
;             PG8_LDA(At, 0, 1); PG8_STAGE(PG8_SB(0, 0), b2, voffB); PG8_STAGE(PG8_SB(0, 1), b2 + hstepB, voffB); PG8_STAGE(PG8_SA(0, 0), a2, voffA);
;             PG8_WAIT_V(8); PG8_WAIT_L(0); PG8_BAR; PG8_MMA(1, 0, At, B0); PG8_MMA(1, 1, At, B1); PG8_BAR; PG8_SCHED;
.LBB0_189:
	s_add_u32 s10, s2, 0xfffe0080
	s_addc_u32 s11, s3, -1
	s_add_i32 s61, 0, 0x10000
	s_cmp_eq_u32 s62, 4
	s_cselect_b32 s35, s19, s11
	s_cselect_b32 s34, s93, s10
	s_cselect_b32 s31, s21, s60
	s_cselect_b32 s30, s94, s97
	s_add_i32 s88, 0, 0x14000
	v_add_u32_e32 v118, s61, v174
	v_add_u32_e32 v159, s88, v174
	ds_read_b128 v[106:109], v118
	ds_read_b128 v[110:113], v118 offset:1024
	ds_read_b128 v[114:117], v118 offset:2048
	ds_read_b128 v[118:121], v118 offset:3072
	ds_read_b128 v[178:181], v159
	ds_read_b128 v[182:185], v159 offset:1024
	ds_read_b128 v[186:189], v159 offset:2048
	ds_read_b128 v[190:193], v159 offset:3072
	v_lshl_add_u64 v[202:203], s[2:3], 0, v[156:157]
	s_add_i32 m0, s9, 0xc000
	ds_read_b128 v[198:201], v176
	ds_read_b128 v[212:215], v176 offset:1024
	ds_read_b128 v[216:219], v176 offset:2048
	ds_read_b128 v[220:223], v176 offset:3072
	ds_read_b128 v[224:227], v176 offset:4096
	ds_read_b128 v[228:231], v176 offset:5120
	ds_read_b128 v[232:235], v176 offset:6144
	ds_read_b128 v[236:239], v176 offset:7168
	global_load_lds_dwordx4 v[202:203], off
	v_lshl_add_u64 v[202:203], s[2:3], 0, v[154:155]
	s_add_i32 m0, s9, 0xe000
	s_nop 0
	global_load_lds_dwordx4 v[202:203], off
	s_waitcnt vmcnt(8)
	s_waitcnt lgkmcnt(0)
	s_barrier
	s_setprio 1
	s_waitcnt lgkmcnt(0)
	v_mfma_f32_16x16x32_bf16 v[142:145], v[106:109], v[198:201], v[142:145]
	v_mfma_f32_16x16x32_bf16 v[138:141], v[114:117], v[198:201], v[138:141]
	v_mfma_f32_16x16x32_bf16 v[126:129], v[114:117], v[216:219], v[126:129]
	v_mfma_f32_16x16x32_bf16 v[134:137], v[106:109], v[216:219], v[134:137]
	v_mfma_f32_16x16x32_bf16 v[94:97], v[106:109], v[224:227], v[94:97]
	v_mfma_f32_16x16x32_bf16 v[90:93], v[114:117], v[224:227], v[90:93]
	v_mfma_f32_16x16x32_bf16 v[78:81], v[114:117], v[232:235], v[78:81]
	v_mfma_f32_16x16x32_bf16 v[86:89], v[106:109], v[232:235], v[86:89]
	v_mfma_f32_16x16x32_bf16 v[142:145], v[110:113], v[212:215], v[142:145]
	v_mfma_f32_16x16x32_bf16 v[138:141], v[118:121], v[212:215], v[138:141]
	v_mfma_f32_16x16x32_bf16 v[126:129], v[118:121], v[220:223], v[126:129]
	v_mfma_f32_16x16x32_bf16 v[134:137], v[110:113], v[220:223], v[134:137]
	v_mfma_f32_16x16x32_bf16 v[94:97], v[110:113], v[228:231], v[94:97]
	v_mfma_f32_16x16x32_bf16 v[90:93], v[118:121], v[228:231], v[90:93]
	v_mfma_f32_16x16x32_bf16 v[78:81], v[118:121], v[236:239], v[78:81]
	v_mfma_f32_16x16x32_bf16 v[86:89], v[110:113], v[236:239], v[86:89]
	s_setprio 0
	s_setprio 1
	v_mfma_f32_16x16x32_bf16 v[130:133], v[178:181], v[198:201], v[130:133]
	v_mfma_f32_16x16x32_bf16 v[122:125], v[186:189], v[198:201], v[122:125]
	v_mfma_f32_16x16x32_bf16 v[98:101], v[186:189], v[216:219], v[98:101]
	v_mfma_f32_16x16x32_bf16 v[102:105], v[178:181], v[216:219], v[102:105]
	v_mfma_f32_16x16x32_bf16 v[82:85], v[178:181], v[224:227], v[82:85]
	v_mfma_f32_16x16x32_bf16 v[74:77], v[186:189], v[224:227], v[74:77]
	v_mfma_f32_16x16x32_bf16 v[66:69], v[186:189], v[232:235], v[66:69]
	v_mfma_f32_16x16x32_bf16 v[70:73], v[178:181], v[232:235], v[70:73]
	v_mfma_f32_16x16x32_bf16 v[130:133], v[182:185], v[212:215], v[130:133]
	v_mfma_f32_16x16x32_bf16 v[122:125], v[190:193], v[212:215], v[122:125]
	v_mfma_f32_16x16x32_bf16 v[98:101], v[190:193], v[220:223], v[98:101]
	v_mfma_f32_16x16x32_bf16 v[102:105], v[182:185], v[220:223], v[102:105]
	v_mfma_f32_16x16x32_bf16 v[82:85], v[182:185], v[228:231], v[82:85]
	v_mfma_f32_16x16x32_bf16 v[74:77], v[190:193], v[228:231], v[74:77]
	v_mfma_f32_16x16x32_bf16 v[66:69], v[190:193], v[236:239], v[66:69]
	v_mfma_f32_16x16x32_bf16 v[70:73], v[182:185], v[236:239], v[70:73]
	s_setprio 0
	s_barrier
	s_add_i32 s10, s61, s54
	v_lshl_add_u64 v[202:203], s[30:31], 0, v[148:149]
	s_mov_b32 m0, s10
	ds_read_b128 v[198:201], v176 offset:16384
	ds_read_b128 v[212:215], v176 offset:17408
	ds_read_b128 v[216:219], v176 offset:18432
	ds_read_b128 v[220:223], v176 offset:19456
	ds_read_b128 v[224:227], v176 offset:20480
	ds_read_b128 v[228:231], v176 offset:21504
	ds_read_b128 v[232:235], v176 offset:22528
	ds_read_b128 v[236:239], v176 offset:23552
	global_load_lds_dwordx4 v[202:203], off
	s_add_i32 m0, s10, 0x2000
	s_add_u32 s10, s30, 0x40000
	v_lshl_add_u64 v[240:241], s[30:31], 0, v[152:153]
	s_addc_u32 s11, s31, 0
	s_add_i32 s61, s88, s54
	global_load_lds_dwordx4 v[240:241], off
	v_lshl_add_u64 v[242:243], s[10:11], 0, v[148:149]
	s_mov_b32 m0, s61
	v_lshl_add_u64 v[244:245], s[34:35], 0, v[150:151]
	global_load_lds_dwordx4 v[242:243], off
	v_lshl_add_u64 v[242:243], s[10:11], 0, v[152:153]
	s_add_i32 m0, s61, 0x2000
	s_nop 0
	global_load_lds_dwordx4 v[242:243], off
	v_lshl_add_u64 v[242:243], s[34:35], 0, v[146:147]
	s_mov_b32 m0, s9
	s_nop 0
	global_load_lds_dwordx4 v[242:243], off
	s_mov_b32 m0, s55
	s_nop 0
	global_load_lds_dwordx4 v[244:245], off
	s_waitcnt vmcnt(8)
	s_waitcnt lgkmcnt(0)
	s_barrier
; #define PG8_STAGE(bufoff, gbase, voff) do { _Pragma("unroll") for (int _i = 0; _i < 2; ++_i) \
;         __builtin_amdgcn_global_load_lds((const unsigned*)((const char*)(gbase) + (voff)[_i]), (PG8_LAS unsigned*)(lds + (bufoff) + ldsw + _i * 8192), 16, 0, 0); } while (0)
; #define PG8_LDA(dst, b, h) do { _Pragma("unroll") for (int m = 0; m < 4; ++m) _Pragma("unroll") for (int k = 0; k < 2; ++k) dst[m][k] = *(const PG8_LAS bf16x8*)(lds + PG8_SA(b, h) + aoff + m * 2048 + k * 1024); } while (0)
; #define PG8_LDB(dst, b, h) do { _Pragma("unroll") for (int n = 0; n < 2; ++n) _Pragma("unroll") for (int k = 0; k < 2; ++k) dst[n][k] = *(const PG8_LAS bf16x8*)(lds + PG8_SB(b, h) + boff + n * 2048 + k * 1024); } while (0)
; #define PG8_MMA(ai, bj, At, Bt) do { __builtin_amdgcn_s_setprio(1); _Pragma("unroll") for (int m = 0; m < 4; ++m) _Pragma("unroll") for (int n = 0; n < 2; ++n) _Pragma("unroll") for (int k = 0; k < 2; ++k) \
;         acc[ai][bj][m][n] = __builtin_amdgcn_mfma_f32_16x16x32_bf16(Bt[n][k], At[m][k], acc[ai][bj][m][n], 0, 0, 0); __builtin_amdgcn_s_setprio(0); } while (0)
; #define PG8_WAIT_V(n) asm volatile("s_waitcnt vmcnt(" #n ")" ::: "memory")
; #define PG8_WAIT_L(n) asm volatile("s_waitcnt lgkmcnt(" #n ")" ::: "memory")
; #define PG8_BAR __builtin_amdgcn_s_barrier()
; #define PG8_SCHED __builtin_amdgcn_sched_barrier(0)
; template <class Epi, class Sched, bool ALIGN_EPI = false, bool SP2 = false>
; __device__ __forceinline__ void gemm_phase(PG8_LAS unsigned char* lds, const Gemm g, const Sched& S, const Epi& E, const int tid) {
;     ...
;             PG8_WAIT_V(8); PG8_WAIT_L(0); PG8_BAR; PG8_MMA(1, 0, At, B0); PG8_MMA(1, 1, At, B1); PG8_BAR; PG8_SCHED;
;             PG8_LDB(B0, 1, 0); PG8_LDB(B1, 1, 1); PG8_SCHED; PG8_LDA(At, 1, 0); PG8_STAGE(PG8_SA(0, 1), a2 + hstepA, voffA);
;             PG8_WAIT_V(8); PG8_WAIT_L(0); PG8_BAR; PG8_MMA(0, 0, At, B0); PG8_MMA(0, 1, At, B1); PG8_BAR; PG8_SCHED;
	s_setprio 1
	s_waitcnt lgkmcnt(0)
	v_mfma_f32_16x16x32_bf16 v[62:65], v[106:109], v[198:201], v[62:65]
	v_mfma_f32_16x16x32_bf16 v[58:61], v[114:117], v[198:201], v[58:61]
	v_mfma_f32_16x16x32_bf16 v[42:45], v[114:117], v[216:219], v[42:45]
	v_mfma_f32_16x16x32_bf16 v[50:53], v[106:109], v[216:219], v[50:53]
	v_mfma_f32_16x16x32_bf16 v[38:41], v[106:109], v[224:227], v[38:41]
	v_mfma_f32_16x16x32_bf16 v[30:33], v[114:117], v[224:227], v[30:33]
	v_mfma_f32_16x16x32_bf16 v[14:17], v[114:117], v[232:235], v[14:17]
	v_mfma_f32_16x16x32_bf16 v[22:25], v[106:109], v[232:235], v[22:25]
	v_mfma_f32_16x16x32_bf16 v[62:65], v[110:113], v[212:215], v[62:65]
	v_mfma_f32_16x16x32_bf16 v[58:61], v[118:121], v[212:215], v[58:61]
	v_mfma_f32_16x16x32_bf16 v[42:45], v[118:121], v[220:223], v[42:45]
	v_mfma_f32_16x16x32_bf16 v[50:53], v[110:113], v[220:223], v[50:53]
	v_mfma_f32_16x16x32_bf16 v[38:41], v[110:113], v[228:231], v[38:41]
	v_mfma_f32_16x16x32_bf16 v[30:33], v[118:121], v[228:231], v[30:33]
	v_mfma_f32_16x16x32_bf16 v[14:17], v[118:121], v[236:239], v[14:17]
	v_mfma_f32_16x16x32_bf16 v[22:25], v[110:113], v[236:239], v[22:25]
	s_setprio 0
	s_setprio 1
	v_mfma_f32_16x16x32_bf16 v[54:57], v[178:181], v[198:201], v[54:57]
	v_mfma_f32_16x16x32_bf16 v[46:49], v[186:189], v[198:201], v[46:49]
	v_mfma_f32_16x16x32_bf16 v[26:29], v[186:189], v[216:219], v[26:29]
	v_mfma_f32_16x16x32_bf16 v[34:37], v[178:181], v[216:219], v[34:37]
	v_mfma_f32_16x16x32_bf16 v[18:21], v[178:181], v[224:227], v[18:21]
	v_mfma_f32_16x16x32_bf16 v[10:13], v[186:189], v[224:227], v[10:13]
	v_mfma_f32_16x16x32_bf16 v[2:5], v[186:189], v[232:235], v[2:5]
	v_mfma_f32_16x16x32_bf16 v[6:9], v[178:181], v[232:235], v[6:9]
	v_mfma_f32_16x16x32_bf16 v[54:57], v[182:185], v[212:215], v[54:57]
	v_mfma_f32_16x16x32_bf16 v[46:49], v[190:193], v[212:215], v[46:49]
	v_mfma_f32_16x16x32_bf16 v[26:29], v[190:193], v[220:223], v[26:29]
	v_mfma_f32_16x16x32_bf16 v[34:37], v[182:185], v[220:223], v[34:37]
	v_mfma_f32_16x16x32_bf16 v[18:21], v[182:185], v[228:231], v[18:21]
	v_mfma_f32_16x16x32_bf16 v[10:13], v[190:193], v[228:231], v[10:13]
	v_mfma_f32_16x16x32_bf16 v[2:5], v[190:193], v[236:239], v[2:5]
	v_mfma_f32_16x16x32_bf16 v[6:9], v[182:185], v[236:239], v[6:9]
	s_setprio 0
	s_barrier
	s_add_i32 s61, 0, 0x18000
	s_add_i32 s88, 0, 0x1c000
	v_add_u32_e32 v118, s61, v174
	v_add_u32_e32 v159, s88, v174
	ds_read_b128 v[106:109], v118
	ds_read_b128 v[110:113], v118 offset:1024
	ds_read_b128 v[114:117], v118 offset:2048
	ds_read_b128 v[118:121], v118 offset:3072
	ds_read_b128 v[178:181], v159
	ds_read_b128 v[182:185], v159 offset:1024
	ds_read_b128 v[186:189], v159 offset:2048
	ds_read_b128 v[190:193], v159 offset:3072
	s_add_u32 s10, s34, 0x20000
	s_addc_u32 s11, s35, 0
	s_mov_b32 m0, s56
	v_lshl_add_u64 v[246:247], s[10:11], 0, v[146:147]
	ds_read_b128 v[198:201], v176 offset:32768
	ds_read_b128 v[212:215], v176 offset:33792
	ds_read_b128 v[216:219], v176 offset:34816
	ds_read_b128 v[220:223], v176 offset:35840
	ds_read_b128 v[224:227], v176 offset:36864
	ds_read_b128 v[228:231], v176 offset:37888
	ds_read_b128 v[232:235], v176 offset:38912
	ds_read_b128 v[236:239], v176 offset:39936
	global_load_lds_dwordx4 v[246:247], off
	v_lshl_add_u64 v[246:247], s[10:11], 0, v[150:151]
	s_mov_b32 m0, s63
	s_nop 0
	global_load_lds_dwordx4 v[246:247], off
	s_waitcnt vmcnt(8)
	s_waitcnt lgkmcnt(0)
	s_barrier
	s_setprio 1
	s_waitcnt lgkmcnt(0)
	v_mfma_f32_16x16x32_bf16 v[142:145], v[106:109], v[198:201], v[142:145]
	v_mfma_f32_16x16x32_bf16 v[138:141], v[114:117], v[198:201], v[138:141]
	v_mfma_f32_16x16x32_bf16 v[126:129], v[114:117], v[216:219], v[126:129]
	v_mfma_f32_16x16x32_bf16 v[134:137], v[106:109], v[216:219], v[134:137]
	v_mfma_f32_16x16x32_bf16 v[94:97], v[106:109], v[224:227], v[94:97]
	v_mfma_f32_16x16x32_bf16 v[90:93], v[114:117], v[224:227], v[90:93]
	v_mfma_f32_16x16x32_bf16 v[78:81], v[114:117], v[232:235], v[78:81]
	v_mfma_f32_16x16x32_bf16 v[86:89], v[106:109], v[232:235], v[86:89]
	v_mfma_f32_16x16x32_bf16 v[142:145], v[110:113], v[212:215], v[142:145]
	v_mfma_f32_16x16x32_bf16 v[138:141], v[118:121], v[212:215], v[138:141]
	v_mfma_f32_16x16x32_bf16 v[126:129], v[118:121], v[220:223], v[126:129]
	v_mfma_f32_16x16x32_bf16 v[134:137], v[110:113], v[220:223], v[134:137]
	v_mfma_f32_16x16x32_bf16 v[94:97], v[110:113], v[228:231], v[94:97]
	v_mfma_f32_16x16x32_bf16 v[90:93], v[118:121], v[228:231], v[90:93]
	v_mfma_f32_16x16x32_bf16 v[78:81], v[118:121], v[236:239], v[78:81]
	v_mfma_f32_16x16x32_bf16 v[86:89], v[110:113], v[236:239], v[86:89]
	s_setprio 0
	s_setprio 1
	v_mfma_f32_16x16x32_bf16 v[130:133], v[178:181], v[198:201], v[130:133]
	v_mfma_f32_16x16x32_bf16 v[122:125], v[186:189], v[198:201], v[122:125]
	v_mfma_f32_16x16x32_bf16 v[98:101], v[186:189], v[216:219], v[98:101]
	v_mfma_f32_16x16x32_bf16 v[102:105], v[178:181], v[216:219], v[102:105]
	v_mfma_f32_16x16x32_bf16 v[82:85], v[178:181], v[224:227], v[82:85]
	v_mfma_f32_16x16x32_bf16 v[74:77], v[186:189], v[224:227], v[74:77]
	v_mfma_f32_16x16x32_bf16 v[66:69], v[186:189], v[232:235], v[66:69]
	v_mfma_f32_16x16x32_bf16 v[70:73], v[178:181], v[232:235], v[70:73]
	v_mfma_f32_16x16x32_bf16 v[130:133], v[182:185], v[212:215], v[130:133]
	v_mfma_f32_16x16x32_bf16 v[122:125], v[190:193], v[212:215], v[122:125]
	v_mfma_f32_16x16x32_bf16 v[98:101], v[190:193], v[220:223], v[98:101]
	v_mfma_f32_16x16x32_bf16 v[102:105], v[182:185], v[220:223], v[102:105]
	v_mfma_f32_16x16x32_bf16 v[82:85], v[182:185], v[228:231], v[82:85]
	v_mfma_f32_16x16x32_bf16 v[74:77], v[190:193], v[228:231], v[74:77]
	v_mfma_f32_16x16x32_bf16 v[66:69], v[190:193], v[236:239], v[66:69]
	v_mfma_f32_16x16x32_bf16 v[70:73], v[182:185], v[236:239], v[70:73]
	s_setprio 0
	s_barrier
; #define PG8_STAGE(bufoff, gbase, voff) do { _Pragma("unroll") for (int _i = 0; _i < 2; ++_i) \
;         __builtin_amdgcn_global_load_lds((const unsigned*)((const char*)(gbase) + (voff)[_i]), (PG8_LAS unsigned*)(lds + (bufoff) + ldsw + _i * 8192), 16, 0, 0); } while (0)
; #define PG8_LDA(dst, b, h) do { _Pragma("unroll") for (int m = 0; m < 4; ++m) _Pragma("unroll") for (int k = 0; k < 2; ++k) dst[m][k] = *(const PG8_LAS bf16x8*)(lds + PG8_SA(b, h) + aoff + m * 2048 + k * 1024); } while (0)
; #define PG8_MMA(ai, bj, At, Bt) do { __builtin_amdgcn_s_setprio(1); _Pragma("unroll") for (int m = 0; m < 4; ++m) _Pragma("unroll") for (int n = 0; n < 2; ++n) _Pragma("unroll") for (int k = 0; k < 2; ++k) \
;         acc[ai][bj][m][n] = __builtin_amdgcn_mfma_f32_16x16x32_bf16(Bt[n][k], At[m][k], acc[ai][bj][m][n], 0, 0, 0); __builtin_amdgcn_s_setprio(0); } while (0)
; #define PG8_WAIT_V(n) asm volatile("s_waitcnt vmcnt(" #n ")" ::: "memory")
; #define PG8_WAIT_L(n) asm volatile("s_waitcnt lgkmcnt(" #n ")" ::: "memory")
; #define PG8_BAR __builtin_amdgcn_s_barrier()
; #define PG8_SCHED __builtin_amdgcn_sched_barrier(0)
; template <class Epi, class Sched, bool ALIGN_EPI = false, bool SP2 = false>
; __device__ __forceinline__ void gemm_phase(PG8_LAS unsigned char* lds, const Gemm g, const Sched& S, const Epi& E, const int tid) {
;     ...
;         for (int t = 0; t < nt; t += 2) {
;             const bool last = (t == nt - 2);
;             const char* a1 = cA + (size_t)(t + 1) * kstep;
;             const char* a2 = last ? nA : cA + (size_t)(t + 2) * kstep; const char* b2 = last ? nB : cB + (size_t)(t + 2) * kstep;
;             const char* a3 = a2 + kstep; const char* b3 = b2 + kstep;
;             if (last && has_next) S.a_ready(nxt);
;     ...
;             PG8_LDA(At, 1, 1); PG8_STAGE(PG8_SB(1, 0), b3, voffB); PG8_STAGE(PG8_SB(1, 1), b3 + hstepB, voffB); PG8_STAGE(PG8_SA(1, 0), a3, voffA);
;             PG8_WAIT_V(8); PG8_WAIT_L(0); PG8_BAR; PG8_MMA(1, 0, At, B0); PG8_MMA(1, 1, At, B1); PG8_BAR; PG8_SCHED;
	s_add_i32 s10, s61, s54
	v_lshl_add_u64 v[202:203], v[202:203], 0, s[70:71]
	s_mov_b32 m0, s10
	ds_read_b128 v[198:201], v176 offset:49152
	ds_read_b128 v[212:215], v176 offset:50176
	ds_read_b128 v[216:219], v176 offset:51200
	ds_read_b128 v[220:223], v176 offset:52224
	ds_read_b128 v[224:227], v176 offset:53248
	ds_read_b128 v[228:231], v176 offset:54272
	ds_read_b128 v[232:235], v176 offset:55296
	ds_read_b128 v[236:239], v176 offset:56320
	global_load_lds_dwordx4 v[202:203], off
	s_add_i32 m0, s10, 0x2000
	s_add_u32 s10, s30, 0x40080
	v_lshl_add_u64 v[202:203], v[240:241], 0, s[70:71]
	s_addc_u32 s11, s31, 0
	s_add_i32 s30, s88, s54
	global_load_lds_dwordx4 v[202:203], off
	v_lshl_add_u64 v[202:203], s[10:11], 0, v[148:149]
	s_mov_b32 m0, s30
	s_nop 0
	global_load_lds_dwordx4 v[202:203], off
	v_lshl_add_u64 v[202:203], s[10:11], 0, v[152:153]
	s_add_i32 m0, s30, 0x2000
	s_nop 0
	global_load_lds_dwordx4 v[202:203], off
	v_lshl_add_u64 v[202:203], v[242:243], 0, s[70:71]
	s_mov_b32 m0, s65
	s_nop 0
	global_load_lds_dwordx4 v[202:203], off
	v_lshl_add_u64 v[202:203], v[244:245], 0, s[70:71]
	s_mov_b32 m0, s66
	s_nop 0
	global_load_lds_dwordx4 v[202:203], off
	s_waitcnt vmcnt(8)
	s_waitcnt lgkmcnt(0)
	s_barrier
	s_setprio 1
	s_waitcnt lgkmcnt(0)
	v_mfma_f32_16x16x32_bf16 v[62:65], v[106:109], v[198:201], v[62:65]
	v_mfma_f32_16x16x32_bf16 v[58:61], v[114:117], v[198:201], v[58:61]
	v_mfma_f32_16x16x32_bf16 v[42:45], v[114:117], v[216:219], v[42:45]
	v_mfma_f32_16x16x32_bf16 v[50:53], v[106:109], v[216:219], v[50:53]
	v_mfma_f32_16x16x32_bf16 v[38:41], v[106:109], v[224:227], v[38:41]
	v_mfma_f32_16x16x32_bf16 v[30:33], v[114:117], v[224:227], v[30:33]
	v_mfma_f32_16x16x32_bf16 v[14:17], v[114:117], v[232:235], v[14:17]
	v_mfma_f32_16x16x32_bf16 v[22:25], v[106:109], v[232:235], v[22:25]
	v_mfma_f32_16x16x32_bf16 v[62:65], v[110:113], v[212:215], v[62:65]
	v_mfma_f32_16x16x32_bf16 v[58:61], v[118:121], v[212:215], v[58:61]
	v_mfma_f32_16x16x32_bf16 v[42:45], v[118:121], v[220:223], v[42:45]
	v_mfma_f32_16x16x32_bf16 v[50:53], v[110:113], v[220:223], v[50:53]
	v_mfma_f32_16x16x32_bf16 v[38:41], v[110:113], v[228:231], v[38:41]
	v_mfma_f32_16x16x32_bf16 v[30:33], v[118:121], v[228:231], v[30:33]
	v_mfma_f32_16x16x32_bf16 v[14:17], v[118:121], v[236:239], v[14:17]
	v_mfma_f32_16x16x32_bf16 v[22:25], v[110:113], v[236:239], v[22:25]
	s_setprio 0
	s_setprio 1
	v_mfma_f32_16x16x32_bf16 v[54:57], v[178:181], v[198:201], v[54:57]
	v_mfma_f32_16x16x32_bf16 v[46:49], v[186:189], v[198:201], v[46:49]
	v_mfma_f32_16x16x32_bf16 v[26:29], v[186:189], v[216:219], v[26:29]
	v_mfma_f32_16x16x32_bf16 v[34:37], v[178:181], v[216:219], v[34:37]
	v_mfma_f32_16x16x32_bf16 v[18:21], v[178:181], v[224:227], v[18:21]
	v_mfma_f32_16x16x32_bf16 v[10:13], v[186:189], v[224:227], v[10:13]
	v_mfma_f32_16x16x32_bf16 v[2:5], v[186:189], v[232:235], v[2:5]
	v_mfma_f32_16x16x32_bf16 v[6:9], v[178:181], v[232:235], v[6:9]
	v_mfma_f32_16x16x32_bf16 v[54:57], v[182:185], v[212:215], v[54:57]
	v_mfma_f32_16x16x32_bf16 v[46:49], v[190:193], v[212:215], v[46:49]
	v_mfma_f32_16x16x32_bf16 v[26:29], v[190:193], v[220:223], v[26:29]
	v_mfma_f32_16x16x32_bf16 v[34:37], v[182:185], v[220:223], v[34:37]
	v_mfma_f32_16x16x32_bf16 v[18:21], v[182:185], v[228:231], v[18:21]
	v_mfma_f32_16x16x32_bf16 v[10:13], v[190:193], v[228:231], v[10:13]
	v_mfma_f32_16x16x32_bf16 v[2:5], v[190:193], v[236:239], v[2:5]
	v_mfma_f32_16x16x32_bf16 v[6:9], v[182:185], v[236:239], v[6:9]
	s_setprio 0
	s_barrier
	s_add_i32 s62, s62, 2
	s_add_u32 s97, s97, 0x100
	s_addc_u32 s60, s60, 0
	s_add_u32 s2, s2, 0x100
	s_addc_u32 s3, s3, 0
	s_cmp_gt_u32 s62, 5
	s_cbranch_scc0 .LBB0_189
	s_and_b64 vcc, exec, s[16:17]
	s_cbranch_vccz .LBB0_192
	s_barrier

; #define PG8_STAGE(bufoff, gbase, voff) do { _Pragma("unroll") for (int _i = 0; _i < 2; ++_i) \
;         __builtin_amdgcn_global_load_lds((const unsigned*)((const char*)(gbase) + (voff)[_i]), (PG8_LAS unsigned*)(lds + (bufoff) + ldsw + _i * 8192), 16, 0, 0); } while (0)
; #define PG8_LDA(dst, b, h) do { _Pragma("unroll") for (int m = 0; m < 4; ++m) _Pragma("unroll") for (int k = 0; k < 2; ++k) dst[m][k] = *(const PG8_LAS bf16x8*)(lds + PG8_SA(b, h) + aoff + m * 2048 + k * 1024); } while (0)
; #define PG8_LDB(dst, b, h) do { _Pragma("unroll") for (int n = 0; n < 2; ++n) _Pragma("unroll") for (int k = 0; k < 2; ++k) dst[n][k] = *(const PG8_LAS bf16x8*)(lds + PG8_SB(b, h) + boff + n * 2048 + k * 1024); } while (0)
; #define PG8_MMA(ai, bj, At, Bt) do { __builtin_amdgcn_s_setprio(1); _Pragma("unroll") for (int m = 0; m < 4; ++m) _Pragma("unroll") for (int n = 0; n < 2; ++n) _Pragma("unroll") for (int k = 0; k < 2; ++k) \
;         acc[ai][bj][m][n] = __builtin_amdgcn_mfma_f32_16x16x32_bf16(Bt[n][k], At[m][k], acc[ai][bj][m][n], 0, 0, 0); __builtin_amdgcn_s_setprio(0); } while (0)
; #define PG8_WAIT_V(n) asm volatile("s_waitcnt vmcnt(" #n ")" ::: "memory")
; #define PG8_WAIT_L(n) asm volatile("s_waitcnt lgkmcnt(" #n ")" ::: "memory")
; #define PG8_BAR __builtin_amdgcn_s_barrier()
; #define PG8_SCHED __builtin_amdgcn_sched_barrier(0)
; template <class Epi, class Sched, bool ALIGN_EPI = false, bool SP2 = false>
; __device__ __forceinline__ void gemm_phase(PG8_LAS unsigned char* lds, const Gemm g, const Sched& S, const Epi& E, const int tid) {
;     ...
;             PG8_LDB(B0, 0, 0); PG8_LDB(B1, 0, 1); PG8_SCHED; PG8_LDA(At, 0, 0); PG8_STAGE(PG8_SA(1, 1), a1 + hstepA, voffA);
;             PG8_WAIT_V(8); PG8_WAIT_L(0); PG8_BAR; PG8_MMA(0, 0, At, B0); PG8_MMA(0, 1, At, B1); PG8_BAR; PG8_SCHED;
;             PG8_LDA(At, 0, 1); PG8_STAGE(PG8_SB(0, 0), b2, voffB); PG8_STAGE(PG8_SB(0, 1), b2 + hstepB, voffB); PG8_STAGE(PG8_SA(0, 0), a2, voffA);
;             PG8_WAIT_V(8); PG8_WAIT_L(0); PG8_BAR; PG8_MMA(1, 0, At, B0); PG8_MMA(1, 1, At, B1); PG8_BAR; PG8_SCHED;
.LBB0_230:
	s_add_u32 s34, s2, 0xfff80080
	s_addc_u32 s35, s3, -1
	s_add_i32 s61, 0, 0x10000
	s_cmp_eq_u32 s62, 28
	s_cselect_b32 s93, s9, s35
	s_cselect_b32 s92, s21, s34
	s_cselect_b32 s35, s25, s60
	s_cselect_b32 s34, s94, s97
	s_add_i32 s88, 0, 0x14000
	v_add_u32_e32 v156, s61, v145
	v_add_u32_e32 v172, s88, v145
	ds_read_b128 v[140:143], v156
	ds_read_b128 v[148:151], v156 offset:1024
	ds_read_b128 v[152:155], v156 offset:2048
	ds_read_b128 v[156:159], v156 offset:3072
	ds_read_b128 v[160:163], v172
	ds_read_b128 v[164:167], v172 offset:1024
	ds_read_b128 v[168:171], v172 offset:2048
	ds_read_b128 v[172:175], v172 offset:3072
	v_lshl_add_u64 v[192:193], s[2:3], 0, v[138:139]
	s_add_i32 m0, s31, 0xc000
	ds_read_b128 v[176:179], v147
	ds_read_b128 v[180:183], v147 offset:1024
	ds_read_b128 v[184:187], v147 offset:2048
	ds_read_b128 v[188:191], v147 offset:3072
	ds_read_b128 v[198:201], v147 offset:4096
	ds_read_b128 v[212:215], v147 offset:5120
	ds_read_b128 v[216:219], v147 offset:6144
	ds_read_b128 v[220:223], v147 offset:7168
	global_load_lds_dwordx4 v[192:193], off
	v_lshl_add_u64 v[192:193], s[2:3], 0, v[136:137]
	s_add_i32 m0, s31, 0xe000
	s_nop 0
	global_load_lds_dwordx4 v[192:193], off
	s_waitcnt vmcnt(8)
	s_waitcnt lgkmcnt(0)
	s_barrier
	s_setprio 1
	s_waitcnt lgkmcnt(0)
	v_mfma_f32_16x16x32_bf16 v[126:129], v[140:143], v[176:179], v[126:129]
	v_mfma_f32_16x16x32_bf16 v[122:125], v[152:155], v[176:179], v[122:125]
	v_mfma_f32_16x16x32_bf16 v[106:109], v[152:155], v[184:187], v[106:109]
	v_mfma_f32_16x16x32_bf16 v[110:113], v[140:143], v[184:187], v[110:113]
	v_mfma_f32_16x16x32_bf16 v[94:97], v[140:143], v[198:201], v[94:97]
	v_mfma_f32_16x16x32_bf16 v[90:93], v[152:155], v[198:201], v[90:93]
	v_mfma_f32_16x16x32_bf16 v[74:77], v[152:155], v[216:219], v[74:77]
	v_mfma_f32_16x16x32_bf16 v[78:81], v[140:143], v[216:219], v[78:81]
	v_mfma_f32_16x16x32_bf16 v[126:129], v[148:151], v[180:183], v[126:129]
	v_mfma_f32_16x16x32_bf16 v[122:125], v[156:159], v[180:183], v[122:125]
	v_mfma_f32_16x16x32_bf16 v[106:109], v[156:159], v[188:191], v[106:109]
	v_mfma_f32_16x16x32_bf16 v[110:113], v[148:151], v[188:191], v[110:113]
	v_mfma_f32_16x16x32_bf16 v[94:97], v[148:151], v[212:215], v[94:97]
	v_mfma_f32_16x16x32_bf16 v[90:93], v[156:159], v[212:215], v[90:93]
	v_mfma_f32_16x16x32_bf16 v[74:77], v[156:159], v[220:223], v[74:77]
	v_mfma_f32_16x16x32_bf16 v[78:81], v[148:151], v[220:223], v[78:81]
	s_setprio 0
	s_setprio 1
	v_mfma_f32_16x16x32_bf16 v[118:121], v[160:163], v[176:179], v[118:121]
	v_mfma_f32_16x16x32_bf16 v[114:117], v[168:171], v[176:179], v[114:117]
	v_mfma_f32_16x16x32_bf16 v[98:101], v[168:171], v[184:187], v[98:101]
	v_mfma_f32_16x16x32_bf16 v[102:105], v[160:163], v[184:187], v[102:105]
	v_mfma_f32_16x16x32_bf16 v[86:89], v[160:163], v[198:201], v[86:89]
	v_mfma_f32_16x16x32_bf16 v[82:85], v[168:171], v[198:201], v[82:85]
	v_mfma_f32_16x16x32_bf16 v[66:69], v[168:171], v[216:219], v[66:69]
	v_mfma_f32_16x16x32_bf16 v[70:73], v[160:163], v[216:219], v[70:73]
	v_mfma_f32_16x16x32_bf16 v[118:121], v[164:167], v[180:183], v[118:121]
	v_mfma_f32_16x16x32_bf16 v[114:117], v[172:175], v[180:183], v[114:117]
	v_mfma_f32_16x16x32_bf16 v[98:101], v[172:175], v[188:191], v[98:101]
	v_mfma_f32_16x16x32_bf16 v[102:105], v[164:167], v[188:191], v[102:105]
	v_mfma_f32_16x16x32_bf16 v[86:89], v[164:167], v[212:215], v[86:89]
	v_mfma_f32_16x16x32_bf16 v[82:85], v[172:175], v[212:215], v[82:85]
	v_mfma_f32_16x16x32_bf16 v[66:69], v[172:175], v[220:223], v[66:69]
	v_mfma_f32_16x16x32_bf16 v[70:73], v[164:167], v[220:223], v[70:73]
	s_setprio 0
	s_barrier
	s_add_i32 s61, s61, s54
	v_lshl_add_u64 v[192:193], s[34:35], 0, v[0:1]
	s_mov_b32 m0, s61
	ds_read_b128 v[176:179], v147 offset:16384
	ds_read_b128 v[180:183], v147 offset:17408
	ds_read_b128 v[184:187], v147 offset:18432
	ds_read_b128 v[188:191], v147 offset:19456
	ds_read_b128 v[198:201], v147 offset:20480
	ds_read_b128 v[212:215], v147 offset:21504
	ds_read_b128 v[216:219], v147 offset:22528
	ds_read_b128 v[220:223], v147 offset:23552
	global_load_lds_dwordx4 v[192:193], off
	s_add_i32 m0, s61, 0x2000
	s_add_u32 vcc_lo, s34, 0x80000
	v_lshl_add_u64 v[202:203], s[34:35], 0, v[134:135]
	s_addc_u32 vcc_hi, s35, 0
	s_add_i32 s61, s88, s54
	global_load_lds_dwordx4 v[202:203], off
	v_lshl_add_u64 v[224:225], vcc, 0, v[0:1]
	s_mov_b32 m0, s61
	v_lshl_add_u64 v[226:227], s[92:93], 0, v[132:133]
	global_load_lds_dwordx4 v[224:225], off
	v_lshl_add_u64 v[224:225], vcc, 0, v[134:135]
	s_add_i32 m0, s61, 0x2000
	s_nop 0
	global_load_lds_dwordx4 v[224:225], off
	v_lshl_add_u64 v[224:225], s[92:93], 0, v[130:131]
	s_mov_b32 m0, s31
	s_nop 0
	global_load_lds_dwordx4 v[224:225], off
	s_mov_b32 m0, s55
	s_nop 0
	global_load_lds_dwordx4 v[226:227], off
	s_waitcnt vmcnt(8)
	s_waitcnt lgkmcnt(0)
	s_barrier
; #define PG8_STAGE(bufoff, gbase, voff) do { _Pragma("unroll") for (int _i = 0; _i < 2; ++_i) \
;         __builtin_amdgcn_global_load_lds((const unsigned*)((const char*)(gbase) + (voff)[_i]), (PG8_LAS unsigned*)(lds + (bufoff) + ldsw + _i * 8192), 16, 0, 0); } while (0)
; #define PG8_LDA(dst, b, h) do { _Pragma("unroll") for (int m = 0; m < 4; ++m) _Pragma("unroll") for (int k = 0; k < 2; ++k) dst[m][k] = *(const PG8_LAS bf16x8*)(lds + PG8_SA(b, h) + aoff + m * 2048 + k * 1024); } while (0)
; #define PG8_LDB(dst, b, h) do { _Pragma("unroll") for (int n = 0; n < 2; ++n) _Pragma("unroll") for (int k = 0; k < 2; ++k) dst[n][k] = *(const PG8_LAS bf16x8*)(lds + PG8_SB(b, h) + boff + n * 2048 + k * 1024); } while (0)
; #define PG8_MMA(ai, bj, At, Bt) do { __builtin_amdgcn_s_setprio(1); _Pragma("unroll") for (int m = 0; m < 4; ++m) _Pragma("unroll") for (int n = 0; n < 2; ++n) _Pragma("unroll") for (int k = 0; k < 2; ++k) \
;         acc[ai][bj][m][n] = __builtin_amdgcn_mfma_f32_16x16x32_bf16(Bt[n][k], At[m][k], acc[ai][bj][m][n], 0, 0, 0); __builtin_amdgcn_s_setprio(0); } while (0)
; #define PG8_WAIT_V(n) asm volatile("s_waitcnt vmcnt(" #n ")" ::: "memory")
; #define PG8_WAIT_L(n) asm volatile("s_waitcnt lgkmcnt(" #n ")" ::: "memory")
; #define PG8_BAR __builtin_amdgcn_s_barrier()
; #define PG8_SCHED __builtin_amdgcn_sched_barrier(0)
; template <class Epi, class Sched, bool ALIGN_EPI = false, bool SP2 = false>
; __device__ __forceinline__ void gemm_phase(PG8_LAS unsigned char* lds, const Gemm g, const Sched& S, const Epi& E, const int tid) {
;     ...
;             PG8_WAIT_V(8); PG8_WAIT_L(0); PG8_BAR; PG8_MMA(1, 0, At, B0); PG8_MMA(1, 1, At, B1); PG8_BAR; PG8_SCHED;
;             PG8_LDB(B0, 1, 0); PG8_LDB(B1, 1, 1); PG8_SCHED; PG8_LDA(At, 1, 0); PG8_STAGE(PG8_SA(0, 1), a2 + hstepA, voffA);
;             PG8_WAIT_V(8); PG8_WAIT_L(0); PG8_BAR; PG8_MMA(0, 0, At, B0); PG8_MMA(0, 1, At, B1); PG8_BAR; PG8_SCHED;
	s_setprio 1
	s_waitcnt lgkmcnt(0)
	v_mfma_f32_16x16x32_bf16 v[62:65], v[140:143], v[176:179], v[62:65]
	v_mfma_f32_16x16x32_bf16 v[58:61], v[152:155], v[176:179], v[58:61]
	v_mfma_f32_16x16x32_bf16 v[42:45], v[152:155], v[184:187], v[42:45]
	v_mfma_f32_16x16x32_bf16 v[46:49], v[140:143], v[184:187], v[46:49]
	v_mfma_f32_16x16x32_bf16 v[30:33], v[140:143], v[198:201], v[30:33]
	v_mfma_f32_16x16x32_bf16 v[26:29], v[152:155], v[198:201], v[26:29]
	v_mfma_f32_16x16x32_bf16 v[10:13], v[152:155], v[216:219], v[10:13]
	v_mfma_f32_16x16x32_bf16 v[14:17], v[140:143], v[216:219], v[14:17]
	v_mfma_f32_16x16x32_bf16 v[62:65], v[148:151], v[180:183], v[62:65]
	v_mfma_f32_16x16x32_bf16 v[58:61], v[156:159], v[180:183], v[58:61]
	v_mfma_f32_16x16x32_bf16 v[42:45], v[156:159], v[188:191], v[42:45]
	v_mfma_f32_16x16x32_bf16 v[46:49], v[148:151], v[188:191], v[46:49]
	v_mfma_f32_16x16x32_bf16 v[30:33], v[148:151], v[212:215], v[30:33]
	v_mfma_f32_16x16x32_bf16 v[26:29], v[156:159], v[212:215], v[26:29]
	v_mfma_f32_16x16x32_bf16 v[10:13], v[156:159], v[220:223], v[10:13]
	v_mfma_f32_16x16x32_bf16 v[14:17], v[148:151], v[220:223], v[14:17]
	s_setprio 0
	s_setprio 1
	v_mfma_f32_16x16x32_bf16 v[54:57], v[160:163], v[176:179], v[54:57]
	v_mfma_f32_16x16x32_bf16 v[50:53], v[168:171], v[176:179], v[50:53]
	v_mfma_f32_16x16x32_bf16 v[34:37], v[168:171], v[184:187], v[34:37]
	v_mfma_f32_16x16x32_bf16 v[38:41], v[160:163], v[184:187], v[38:41]
	v_mfma_f32_16x16x32_bf16 v[22:25], v[160:163], v[198:201], v[22:25]
	v_mfma_f32_16x16x32_bf16 v[18:21], v[168:171], v[198:201], v[18:21]
	v_mfma_f32_16x16x32_bf16 v[2:5], v[168:171], v[216:219], v[2:5]
	v_mfma_f32_16x16x32_bf16 v[6:9], v[160:163], v[216:219], v[6:9]
	v_mfma_f32_16x16x32_bf16 v[54:57], v[164:167], v[180:183], v[54:57]
	v_mfma_f32_16x16x32_bf16 v[50:53], v[172:175], v[180:183], v[50:53]
	v_mfma_f32_16x16x32_bf16 v[34:37], v[172:175], v[188:191], v[34:37]
	v_mfma_f32_16x16x32_bf16 v[38:41], v[164:167], v[188:191], v[38:41]
	v_mfma_f32_16x16x32_bf16 v[22:25], v[164:167], v[212:215], v[22:25]
	v_mfma_f32_16x16x32_bf16 v[18:21], v[172:175], v[212:215], v[18:21]
	v_mfma_f32_16x16x32_bf16 v[2:5], v[172:175], v[220:223], v[2:5]
	v_mfma_f32_16x16x32_bf16 v[6:9], v[164:167], v[220:223], v[6:9]
	s_setprio 0
	s_barrier
	s_add_i32 s61, 0, 0x18000
	s_add_i32 s88, 0, 0x1c000
	v_add_u32_e32 v156, s61, v145
	v_add_u32_e32 v172, s88, v145
	ds_read_b128 v[140:143], v156
	ds_read_b128 v[148:151], v156 offset:1024
	ds_read_b128 v[152:155], v156 offset:2048
	ds_read_b128 v[156:159], v156 offset:3072
	ds_read_b128 v[160:163], v172
	ds_read_b128 v[164:167], v172 offset:1024
	ds_read_b128 v[168:171], v172 offset:2048
	ds_read_b128 v[172:175], v172 offset:3072
	s_add_u32 s92, s92, 0x80000
	s_addc_u32 s93, s93, 0
	s_mov_b32 m0, s56
	v_lshl_add_u64 v[228:229], s[92:93], 0, v[130:131]
	ds_read_b128 v[176:179], v147 offset:32768
	ds_read_b128 v[180:183], v147 offset:33792
	ds_read_b128 v[184:187], v147 offset:34816
	ds_read_b128 v[188:191], v147 offset:35840
	ds_read_b128 v[198:201], v147 offset:36864
	ds_read_b128 v[212:215], v147 offset:37888
	ds_read_b128 v[216:219], v147 offset:38912
	ds_read_b128 v[220:223], v147 offset:39936
	global_load_lds_dwordx4 v[228:229], off
	v_lshl_add_u64 v[228:229], s[92:93], 0, v[132:133]
	s_mov_b32 m0, s63
	s_nop 0
	global_load_lds_dwordx4 v[228:229], off
	s_waitcnt vmcnt(8)
	s_waitcnt lgkmcnt(0)
	s_barrier
	s_setprio 1
	s_waitcnt lgkmcnt(0)
	v_mfma_f32_16x16x32_bf16 v[126:129], v[140:143], v[176:179], v[126:129]
	v_mfma_f32_16x16x32_bf16 v[122:125], v[152:155], v[176:179], v[122:125]
	v_mfma_f32_16x16x32_bf16 v[106:109], v[152:155], v[184:187], v[106:109]
	v_mfma_f32_16x16x32_bf16 v[110:113], v[140:143], v[184:187], v[110:113]
	v_mfma_f32_16x16x32_bf16 v[94:97], v[140:143], v[198:201], v[94:97]
	v_mfma_f32_16x16x32_bf16 v[90:93], v[152:155], v[198:201], v[90:93]
	v_mfma_f32_16x16x32_bf16 v[74:77], v[152:155], v[216:219], v[74:77]
	v_mfma_f32_16x16x32_bf16 v[78:81], v[140:143], v[216:219], v[78:81]
	v_mfma_f32_16x16x32_bf16 v[126:129], v[148:151], v[180:183], v[126:129]
	v_mfma_f32_16x16x32_bf16 v[122:125], v[156:159], v[180:183], v[122:125]
	v_mfma_f32_16x16x32_bf16 v[106:109], v[156:159], v[188:191], v[106:109]
	v_mfma_f32_16x16x32_bf16 v[110:113], v[148:151], v[188:191], v[110:113]
	v_mfma_f32_16x16x32_bf16 v[94:97], v[148:151], v[212:215], v[94:97]
	v_mfma_f32_16x16x32_bf16 v[90:93], v[156:159], v[212:215], v[90:93]
	v_mfma_f32_16x16x32_bf16 v[74:77], v[156:159], v[220:223], v[74:77]
	v_mfma_f32_16x16x32_bf16 v[78:81], v[148:151], v[220:223], v[78:81]
	s_setprio 0
	s_setprio 1
	v_mfma_f32_16x16x32_bf16 v[118:121], v[160:163], v[176:179], v[118:121]
	v_mfma_f32_16x16x32_bf16 v[114:117], v[168:171], v[176:179], v[114:117]
	v_mfma_f32_16x16x32_bf16 v[98:101], v[168:171], v[184:187], v[98:101]
	v_mfma_f32_16x16x32_bf16 v[102:105], v[160:163], v[184:187], v[102:105]
	v_mfma_f32_16x16x32_bf16 v[86:89], v[160:163], v[198:201], v[86:89]
	v_mfma_f32_16x16x32_bf16 v[82:85], v[168:171], v[198:201], v[82:85]
	v_mfma_f32_16x16x32_bf16 v[66:69], v[168:171], v[216:219], v[66:69]
	v_mfma_f32_16x16x32_bf16 v[70:73], v[160:163], v[216:219], v[70:73]
	v_mfma_f32_16x16x32_bf16 v[118:121], v[164:167], v[180:183], v[118:121]
	v_mfma_f32_16x16x32_bf16 v[114:117], v[172:175], v[180:183], v[114:117]
	v_mfma_f32_16x16x32_bf16 v[98:101], v[172:175], v[188:191], v[98:101]
	v_mfma_f32_16x16x32_bf16 v[102:105], v[164:167], v[188:191], v[102:105]
	v_mfma_f32_16x16x32_bf16 v[86:89], v[164:167], v[212:215], v[86:89]
	v_mfma_f32_16x16x32_bf16 v[82:85], v[172:175], v[212:215], v[82:85]
	v_mfma_f32_16x16x32_bf16 v[66:69], v[172:175], v[220:223], v[66:69]
	v_mfma_f32_16x16x32_bf16 v[70:73], v[164:167], v[220:223], v[70:73]
	s_setprio 0
	s_barrier
; #define PG8_STAGE(bufoff, gbase, voff) do { _Pragma("unroll") for (int _i = 0; _i < 2; ++_i) \
;         __builtin_amdgcn_global_load_lds((const unsigned*)((const char*)(gbase) + (voff)[_i]), (PG8_LAS unsigned*)(lds + (bufoff) + ldsw + _i * 8192), 16, 0, 0); } while (0)
; #define PG8_LDA(dst, b, h) do { _Pragma("unroll") for (int m = 0; m < 4; ++m) _Pragma("unroll") for (int k = 0; k < 2; ++k) dst[m][k] = *(const PG8_LAS bf16x8*)(lds + PG8_SA(b, h) + aoff + m * 2048 + k * 1024); } while (0)
; #define PG8_MMA(ai, bj, At, Bt) do { __builtin_amdgcn_s_setprio(1); _Pragma("unroll") for (int m = 0; m < 4; ++m) _Pragma("unroll") for (int n = 0; n < 2; ++n) _Pragma("unroll") for (int k = 0; k < 2; ++k) \
;         acc[ai][bj][m][n] = __builtin_amdgcn_mfma_f32_16x16x32_bf16(Bt[n][k], At[m][k], acc[ai][bj][m][n], 0, 0, 0); __builtin_amdgcn_s_setprio(0); } while (0)
; #define PG8_WAIT_V(n) asm volatile("s_waitcnt vmcnt(" #n ")" ::: "memory")
; #define PG8_WAIT_L(n) asm volatile("s_waitcnt lgkmcnt(" #n ")" ::: "memory")
; #define PG8_BAR __builtin_amdgcn_s_barrier()
; #define PG8_SCHED __builtin_amdgcn_sched_barrier(0)
; template <class Epi, class Sched, bool ALIGN_EPI = false, bool SP2 = false>
; __device__ __forceinline__ void gemm_phase(PG8_LAS unsigned char* lds, const Gemm g, const Sched& S, const Epi& E, const int tid) {
;     ...
;         for (int t = 0; t < nt; t += 2) {
;             const bool last = (t == nt - 2);
;             const char* a1 = cA + (size_t)(t + 1) * kstep;
;             const char* a2 = last ? nA : cA + (size_t)(t + 2) * kstep; const char* b2 = last ? nB : cB + (size_t)(t + 2) * kstep;
;             const char* a3 = a2 + kstep; const char* b3 = b2 + kstep;
;             if (last && has_next) S.a_ready(nxt);
;     ...
;             PG8_LDA(At, 1, 1); PG8_STAGE(PG8_SB(1, 0), b3, voffB); PG8_STAGE(PG8_SB(1, 1), b3 + hstepB, voffB); PG8_STAGE(PG8_SA(1, 0), a3, voffA);
;             PG8_WAIT_V(8); PG8_WAIT_L(0); PG8_BAR; PG8_MMA(1, 0, At, B0); PG8_MMA(1, 1, At, B1); PG8_BAR; PG8_SCHED;
	s_add_i32 s61, s61, s54
	v_lshl_add_u64 v[192:193], v[192:193], 0, s[70:71]
	s_mov_b32 m0, s61
	ds_read_b128 v[176:179], v147 offset:49152
	ds_read_b128 v[180:183], v147 offset:50176
	ds_read_b128 v[184:187], v147 offset:51200
	ds_read_b128 v[188:191], v147 offset:52224
	ds_read_b128 v[198:201], v147 offset:53248
	ds_read_b128 v[212:215], v147 offset:54272
	ds_read_b128 v[216:219], v147 offset:55296
	ds_read_b128 v[220:223], v147 offset:56320
	global_load_lds_dwordx4 v[192:193], off
	s_add_i32 m0, s61, 0x2000
	s_add_u32 s34, s34, 0x80080
	v_lshl_add_u64 v[192:193], v[202:203], 0, s[70:71]
	s_addc_u32 s35, s35, 0
	s_add_i32 s61, s88, s54
	global_load_lds_dwordx4 v[192:193], off
	v_lshl_add_u64 v[192:193], s[34:35], 0, v[0:1]
	s_mov_b32 m0, s61
	s_nop 0
	global_load_lds_dwordx4 v[192:193], off
	v_lshl_add_u64 v[192:193], s[34:35], 0, v[134:135]
	s_add_i32 m0, s61, 0x2000
	s_nop 0
	global_load_lds_dwordx4 v[192:193], off
	v_lshl_add_u64 v[192:193], v[224:225], 0, s[70:71]
	s_mov_b32 m0, s65
	s_nop 0
	global_load_lds_dwordx4 v[192:193], off
	v_lshl_add_u64 v[192:193], v[226:227], 0, s[70:71]
	s_mov_b32 m0, s66
	s_nop 0
	global_load_lds_dwordx4 v[192:193], off
	s_waitcnt vmcnt(8)
	s_waitcnt lgkmcnt(0)
	s_barrier
	s_setprio 1
	s_waitcnt lgkmcnt(0)
	v_mfma_f32_16x16x32_bf16 v[62:65], v[140:143], v[176:179], v[62:65]
	v_mfma_f32_16x16x32_bf16 v[58:61], v[152:155], v[176:179], v[58:61]
	v_mfma_f32_16x16x32_bf16 v[42:45], v[152:155], v[184:187], v[42:45]
	v_mfma_f32_16x16x32_bf16 v[46:49], v[140:143], v[184:187], v[46:49]
	v_mfma_f32_16x16x32_bf16 v[30:33], v[140:143], v[198:201], v[30:33]
	v_mfma_f32_16x16x32_bf16 v[26:29], v[152:155], v[198:201], v[26:29]
	v_mfma_f32_16x16x32_bf16 v[10:13], v[152:155], v[216:219], v[10:13]
	v_mfma_f32_16x16x32_bf16 v[14:17], v[140:143], v[216:219], v[14:17]
	v_mfma_f32_16x16x32_bf16 v[62:65], v[148:151], v[180:183], v[62:65]
	v_mfma_f32_16x16x32_bf16 v[58:61], v[156:159], v[180:183], v[58:61]
	v_mfma_f32_16x16x32_bf16 v[42:45], v[156:159], v[188:191], v[42:45]
	v_mfma_f32_16x16x32_bf16 v[46:49], v[148:151], v[188:191], v[46:49]
	v_mfma_f32_16x16x32_bf16 v[30:33], v[148:151], v[212:215], v[30:33]
	v_mfma_f32_16x16x32_bf16 v[26:29], v[156:159], v[212:215], v[26:29]
	v_mfma_f32_16x16x32_bf16 v[10:13], v[156:159], v[220:223], v[10:13]
	v_mfma_f32_16x16x32_bf16 v[14:17], v[148:151], v[220:223], v[14:17]
	s_setprio 0
	s_setprio 1
	v_mfma_f32_16x16x32_bf16 v[54:57], v[160:163], v[176:179], v[54:57]
	v_mfma_f32_16x16x32_bf16 v[50:53], v[168:171], v[176:179], v[50:53]
	v_mfma_f32_16x16x32_bf16 v[34:37], v[168:171], v[184:187], v[34:37]
	v_mfma_f32_16x16x32_bf16 v[38:41], v[160:163], v[184:187], v[38:41]
	v_mfma_f32_16x16x32_bf16 v[22:25], v[160:163], v[198:201], v[22:25]
	v_mfma_f32_16x16x32_bf16 v[18:21], v[168:171], v[198:201], v[18:21]
	v_mfma_f32_16x16x32_bf16 v[2:5], v[168:171], v[216:219], v[2:5]
	v_mfma_f32_16x16x32_bf16 v[6:9], v[160:163], v[216:219], v[6:9]
	v_mfma_f32_16x16x32_bf16 v[54:57], v[164:167], v[180:183], v[54:57]
	v_mfma_f32_16x16x32_bf16 v[50:53], v[172:175], v[180:183], v[50:53]
	v_mfma_f32_16x16x32_bf16 v[34:37], v[172:175], v[188:191], v[34:37]
	v_mfma_f32_16x16x32_bf16 v[38:41], v[164:167], v[188:191], v[38:41]
	v_mfma_f32_16x16x32_bf16 v[22:25], v[164:167], v[212:215], v[22:25]
	v_mfma_f32_16x16x32_bf16 v[18:21], v[172:175], v[212:215], v[18:21]
	v_mfma_f32_16x16x32_bf16 v[2:5], v[172:175], v[220:223], v[2:5]
	v_mfma_f32_16x16x32_bf16 v[6:9], v[164:167], v[220:223], v[6:9]
	s_setprio 0
	s_barrier
	s_add_i32 s62, s62, 2
	s_add_u32 s97, s97, 0x100
	s_addc_u32 s60, s60, 0
	s_add_u32 s2, s2, 0x100
	s_addc_u32 s3, s3, 0
	s_cmp_gt_u32 s62, 29
	s_cbranch_scc0 .LBB0_230
	s_and_b64 vcc, exec, s[16:17]
	s_cbranch_vccz .LBB0_233
	s_barrier

; #define PG8_STAGE(bufoff, gbase, voff) do { _Pragma("unroll") for (int _i = 0; _i < 2; ++_i) \
;         __builtin_amdgcn_global_load_lds((const unsigned*)((const char*)(gbase) + (voff)[_i]), (PG8_LAS unsigned*)(lds + (bufoff) + ldsw + _i * 8192), 16, 0, 0); } while (0)
; #define PG8_LDA(dst, b, h) do { _Pragma("unroll") for (int m = 0; m < 4; ++m) _Pragma("unroll") for (int k = 0; k < 2; ++k) dst[m][k] = *(const PG8_LAS bf16x8*)(lds + PG8_SA(b, h) + aoff + m * 2048 + k * 1024); } while (0)
; #define PG8_LDB(dst, b, h) do { _Pragma("unroll") for (int n = 0; n < 2; ++n) _Pragma("unroll") for (int k = 0; k < 2; ++k) dst[n][k] = *(const PG8_LAS bf16x8*)(lds + PG8_SB(b, h) + boff + n * 2048 + k * 1024); } while (0)
; #define PG8_MMA(ai, bj, At, Bt) do { __builtin_amdgcn_s_setprio(1); _Pragma("unroll") for (int m = 0; m < 4; ++m) _Pragma("unroll") for (int n = 0; n < 2; ++n) _Pragma("unroll") for (int k = 0; k < 2; ++k) \
;         acc[ai][bj][m][n] = __builtin_amdgcn_mfma_f32_16x16x32_bf16(Bt[n][k], At[m][k], acc[ai][bj][m][n], 0, 0, 0); __builtin_amdgcn_s_setprio(0); } while (0)
; #define PG8_WAIT_V(n) asm volatile("s_waitcnt vmcnt(" #n ")" ::: "memory")
; #define PG8_WAIT_L(n) asm volatile("s_waitcnt lgkmcnt(" #n ")" ::: "memory")
; #define PG8_BAR __builtin_amdgcn_s_barrier()
; #define PG8_SCHED __builtin_amdgcn_sched_barrier(0)
; template <class Epi, class Sched, bool ALIGN_EPI = false, bool SP2 = false>
; __device__ __forceinline__ void gemm_phase(PG8_LAS unsigned char* lds, const Gemm g, const Sched& S, const Epi& E, const int tid) {
;     ...
;             PG8_LDB(B0, 0, 0); PG8_LDB(B1, 0, 1); PG8_SCHED; PG8_LDA(At, 0, 0); PG8_STAGE(PG8_SA(1, 1), a1 + hstepA, voffA);
;             PG8_WAIT_V(8); PG8_WAIT_L(0); PG8_BAR; PG8_MMA(0, 0, At, B0); PG8_MMA(0, 1, At, B1); PG8_BAR; PG8_SCHED;
;             PG8_LDA(At, 0, 1); PG8_STAGE(PG8_SB(0, 0), b2, voffB); PG8_STAGE(PG8_SB(0, 1), b2 + hstepB, voffB); PG8_STAGE(PG8_SA(0, 0), a2, voffA);
;             PG8_WAIT_V(8); PG8_WAIT_L(0); PG8_BAR; PG8_MMA(1, 0, At, B0); PG8_MMA(1, 1, At, B1); PG8_BAR; PG8_SCHED;
.LBB0_265:
	s_add_u32 s4, s2, 0xfff80080
	s_addc_u32 s5, s3, -1
	s_add_i32 s61, 0, 0x10000
	s_cmp_eq_u32 s62, 28
	s_cselect_b32 vcc_hi, s9, s5
	s_cselect_b32 vcc_lo, s21, s4
	v_add_u32_e32 v152, s61, v155
	s_cselect_b32 s93, s23, s60
	s_cselect_b32 s92, s25, s94
	s_add_i32 s88, 0, 0x14000
	ds_read_b128 v[140:143], v152
	ds_read_b128 v[144:147], v152 offset:1024
	ds_read_b128 v[148:151], v152 offset:2048
	ds_read_b128 v[158:161], v152 offset:3072
	v_add_u32_e32 v152, s88, v155
	ds_read_b128 v[162:165], v152
	ds_read_b128 v[166:169], v152 offset:1024
	ds_read_b128 v[170:173], v152 offset:2048
	ds_read_b128 v[174:177], v152 offset:3072
	v_lshl_add_u64 v[152:153], s[2:3], 0, v[138:139]
	s_add_i32 m0, s35, 0xc000
	ds_read_b128 v[178:181], v157
	ds_read_b128 v[182:185], v157 offset:1024
	ds_read_b128 v[186:189], v157 offset:2048
	ds_read_b128 v[190:193], v157 offset:3072
	ds_read_b128 v[198:201], v157 offset:4096
	ds_read_b128 v[212:215], v157 offset:5120
	ds_read_b128 v[216:219], v157 offset:6144
	ds_read_b128 v[220:223], v157 offset:7168
	global_load_lds_dwordx4 v[152:153], off
	v_lshl_add_u64 v[152:153], s[2:3], 0, v[136:137]
	s_add_i32 m0, s35, 0xe000
	s_nop 0
	global_load_lds_dwordx4 v[152:153], off
	s_waitcnt vmcnt(8)
	s_waitcnt lgkmcnt(0)
	s_barrier
	s_setprio 1
	s_waitcnt lgkmcnt(0)
	v_mfma_f32_16x16x32_bf16 v[126:129], v[140:143], v[178:181], v[126:129]
	v_mfma_f32_16x16x32_bf16 v[122:125], v[148:151], v[178:181], v[122:125]
	v_mfma_f32_16x16x32_bf16 v[106:109], v[148:151], v[186:189], v[106:109]
	v_mfma_f32_16x16x32_bf16 v[110:113], v[140:143], v[186:189], v[110:113]
	v_mfma_f32_16x16x32_bf16 v[94:97], v[140:143], v[198:201], v[94:97]
	v_mfma_f32_16x16x32_bf16 v[90:93], v[148:151], v[198:201], v[90:93]
	v_mfma_f32_16x16x32_bf16 v[74:77], v[148:151], v[216:219], v[74:77]
	v_mfma_f32_16x16x32_bf16 v[78:81], v[140:143], v[216:219], v[78:81]
	v_mfma_f32_16x16x32_bf16 v[126:129], v[144:147], v[182:185], v[126:129]
	v_mfma_f32_16x16x32_bf16 v[122:125], v[158:161], v[182:185], v[122:125]
	v_mfma_f32_16x16x32_bf16 v[106:109], v[158:161], v[190:193], v[106:109]
	v_mfma_f32_16x16x32_bf16 v[110:113], v[144:147], v[190:193], v[110:113]
	v_mfma_f32_16x16x32_bf16 v[94:97], v[144:147], v[212:215], v[94:97]
	v_mfma_f32_16x16x32_bf16 v[90:93], v[158:161], v[212:215], v[90:93]
	v_mfma_f32_16x16x32_bf16 v[74:77], v[158:161], v[220:223], v[74:77]
	v_mfma_f32_16x16x32_bf16 v[78:81], v[144:147], v[220:223], v[78:81]
	s_setprio 0
	s_setprio 1
	v_mfma_f32_16x16x32_bf16 v[118:121], v[162:165], v[178:181], v[118:121]
	v_mfma_f32_16x16x32_bf16 v[114:117], v[170:173], v[178:181], v[114:117]
	v_mfma_f32_16x16x32_bf16 v[98:101], v[170:173], v[186:189], v[98:101]
	v_mfma_f32_16x16x32_bf16 v[102:105], v[162:165], v[186:189], v[102:105]
	v_mfma_f32_16x16x32_bf16 v[86:89], v[162:165], v[198:201], v[86:89]
	v_mfma_f32_16x16x32_bf16 v[82:85], v[170:173], v[198:201], v[82:85]
	v_mfma_f32_16x16x32_bf16 v[66:69], v[170:173], v[216:219], v[66:69]
	v_mfma_f32_16x16x32_bf16 v[70:73], v[162:165], v[216:219], v[70:73]
	v_mfma_f32_16x16x32_bf16 v[118:121], v[166:169], v[182:185], v[118:121]
	v_mfma_f32_16x16x32_bf16 v[114:117], v[174:177], v[182:185], v[114:117]
	v_mfma_f32_16x16x32_bf16 v[98:101], v[174:177], v[190:193], v[98:101]
	v_mfma_f32_16x16x32_bf16 v[102:105], v[166:169], v[190:193], v[102:105]
	v_mfma_f32_16x16x32_bf16 v[86:89], v[166:169], v[212:215], v[86:89]
	v_mfma_f32_16x16x32_bf16 v[82:85], v[174:177], v[212:215], v[82:85]
	v_mfma_f32_16x16x32_bf16 v[66:69], v[174:177], v[220:223], v[66:69]
	v_mfma_f32_16x16x32_bf16 v[70:73], v[166:169], v[220:223], v[70:73]
	s_setprio 0
	s_barrier
	s_add_i32 s4, s61, s56
	v_lshl_add_u64 v[152:153], s[92:93], 0, v[0:1]
	s_mov_b32 m0, s4
	ds_read_b128 v[178:181], v157 offset:16384
	ds_read_b128 v[182:185], v157 offset:17408
	ds_read_b128 v[186:189], v157 offset:18432
	ds_read_b128 v[190:193], v157 offset:19456
	ds_read_b128 v[198:201], v157 offset:20480
	ds_read_b128 v[212:215], v157 offset:21504
	ds_read_b128 v[216:219], v157 offset:22528
	ds_read_b128 v[220:223], v157 offset:23552
	global_load_lds_dwordx4 v[152:153], off
	s_add_i32 m0, s4, 0x2000
	s_add_u32 s4, s92, 0x80000
	v_lshl_add_u64 v[202:203], s[92:93], 0, v[134:135]
	s_addc_u32 s5, s93, 0
	s_add_i32 s61, s88, s56
	global_load_lds_dwordx4 v[202:203], off
	v_lshl_add_u64 v[224:225], s[4:5], 0, v[0:1]
	s_mov_b32 m0, s61
	v_lshl_add_u64 v[226:227], vcc, 0, v[132:133]
	global_load_lds_dwordx4 v[224:225], off
	v_lshl_add_u64 v[224:225], s[4:5], 0, v[134:135]
	s_add_i32 m0, s61, 0x2000
	s_nop 0
	global_load_lds_dwordx4 v[224:225], off
	v_lshl_add_u64 v[224:225], vcc, 0, v[130:131]
	s_mov_b32 m0, s35
	s_nop 0
	global_load_lds_dwordx4 v[224:225], off
	s_mov_b32 m0, s63
	s_nop 0
	global_load_lds_dwordx4 v[226:227], off
	s_waitcnt vmcnt(8)
	s_waitcnt lgkmcnt(0)
	s_barrier
; #define PG8_STAGE(bufoff, gbase, voff) do { _Pragma("unroll") for (int _i = 0; _i < 2; ++_i) \
;         __builtin_amdgcn_global_load_lds((const unsigned*)((const char*)(gbase) + (voff)[_i]), (PG8_LAS unsigned*)(lds + (bufoff) + ldsw + _i * 8192), 16, 0, 0); } while (0)
; #define PG8_LDA(dst, b, h) do { _Pragma("unroll") for (int m = 0; m < 4; ++m) _Pragma("unroll") for (int k = 0; k < 2; ++k) dst[m][k] = *(const PG8_LAS bf16x8*)(lds + PG8_SA(b, h) + aoff + m * 2048 + k * 1024); } while (0)
; #define PG8_LDB(dst, b, h) do { _Pragma("unroll") for (int n = 0; n < 2; ++n) _Pragma("unroll") for (int k = 0; k < 2; ++k) dst[n][k] = *(const PG8_LAS bf16x8*)(lds + PG8_SB(b, h) + boff + n * 2048 + k * 1024); } while (0)
; #define PG8_MMA(ai, bj, At, Bt) do { __builtin_amdgcn_s_setprio(1); _Pragma("unroll") for (int m = 0; m < 4; ++m) _Pragma("unroll") for (int n = 0; n < 2; ++n) _Pragma("unroll") for (int k = 0; k < 2; ++k) \
;         acc[ai][bj][m][n] = __builtin_amdgcn_mfma_f32_16x16x32_bf16(Bt[n][k], At[m][k], acc[ai][bj][m][n], 0, 0, 0); __builtin_amdgcn_s_setprio(0); } while (0)
; #define PG8_WAIT_V(n) asm volatile("s_waitcnt vmcnt(" #n ")" ::: "memory")
; #define PG8_WAIT_L(n) asm volatile("s_waitcnt lgkmcnt(" #n ")" ::: "memory")
; #define PG8_BAR __builtin_amdgcn_s_barrier()
; #define PG8_SCHED __builtin_amdgcn_sched_barrier(0)
; template <class Epi, class Sched, bool ALIGN_EPI = false, bool SP2 = false>
; __device__ __forceinline__ void gemm_phase(PG8_LAS unsigned char* lds, const Gemm g, const Sched& S, const Epi& E, const int tid) {
;     ...
;             PG8_WAIT_V(8); PG8_WAIT_L(0); PG8_BAR; PG8_MMA(1, 0, At, B0); PG8_MMA(1, 1, At, B1); PG8_BAR; PG8_SCHED;
;             PG8_LDB(B0, 1, 0); PG8_LDB(B1, 1, 1); PG8_SCHED; PG8_LDA(At, 1, 0); PG8_STAGE(PG8_SA(0, 1), a2 + hstepA, voffA);
;             PG8_WAIT_V(8); PG8_WAIT_L(0); PG8_BAR; PG8_MMA(0, 0, At, B0); PG8_MMA(0, 1, At, B1); PG8_BAR; PG8_SCHED;
	s_setprio 1
	s_waitcnt lgkmcnt(0)
	v_mfma_f32_16x16x32_bf16 v[62:65], v[140:143], v[178:181], v[62:65]
	v_mfma_f32_16x16x32_bf16 v[58:61], v[148:151], v[178:181], v[58:61]
	v_mfma_f32_16x16x32_bf16 v[42:45], v[148:151], v[186:189], v[42:45]
	v_mfma_f32_16x16x32_bf16 v[46:49], v[140:143], v[186:189], v[46:49]
	v_mfma_f32_16x16x32_bf16 v[30:33], v[140:143], v[198:201], v[30:33]
	v_mfma_f32_16x16x32_bf16 v[26:29], v[148:151], v[198:201], v[26:29]
	v_mfma_f32_16x16x32_bf16 v[10:13], v[148:151], v[216:219], v[10:13]
	v_mfma_f32_16x16x32_bf16 v[14:17], v[140:143], v[216:219], v[14:17]
	v_mfma_f32_16x16x32_bf16 v[62:65], v[144:147], v[182:185], v[62:65]
	v_mfma_f32_16x16x32_bf16 v[58:61], v[158:161], v[182:185], v[58:61]
	v_mfma_f32_16x16x32_bf16 v[42:45], v[158:161], v[190:193], v[42:45]
	v_mfma_f32_16x16x32_bf16 v[46:49], v[144:147], v[190:193], v[46:49]
	v_mfma_f32_16x16x32_bf16 v[30:33], v[144:147], v[212:215], v[30:33]
	v_mfma_f32_16x16x32_bf16 v[26:29], v[158:161], v[212:215], v[26:29]
	v_mfma_f32_16x16x32_bf16 v[10:13], v[158:161], v[220:223], v[10:13]
	v_mfma_f32_16x16x32_bf16 v[14:17], v[144:147], v[220:223], v[14:17]
	s_setprio 0
	s_setprio 1
	v_mfma_f32_16x16x32_bf16 v[54:57], v[162:165], v[178:181], v[54:57]
	v_mfma_f32_16x16x32_bf16 v[50:53], v[170:173], v[178:181], v[50:53]
	v_mfma_f32_16x16x32_bf16 v[34:37], v[170:173], v[186:189], v[34:37]
	v_mfma_f32_16x16x32_bf16 v[38:41], v[162:165], v[186:189], v[38:41]
	v_mfma_f32_16x16x32_bf16 v[22:25], v[162:165], v[198:201], v[22:25]
	v_mfma_f32_16x16x32_bf16 v[18:21], v[170:173], v[198:201], v[18:21]
	v_mfma_f32_16x16x32_bf16 v[2:5], v[170:173], v[216:219], v[2:5]
	v_mfma_f32_16x16x32_bf16 v[6:9], v[162:165], v[216:219], v[6:9]
	v_mfma_f32_16x16x32_bf16 v[54:57], v[166:169], v[182:185], v[54:57]
	v_mfma_f32_16x16x32_bf16 v[50:53], v[174:177], v[182:185], v[50:53]
	v_mfma_f32_16x16x32_bf16 v[34:37], v[174:177], v[190:193], v[34:37]
	v_mfma_f32_16x16x32_bf16 v[38:41], v[166:169], v[190:193], v[38:41]
	v_mfma_f32_16x16x32_bf16 v[22:25], v[166:169], v[212:215], v[22:25]
	v_mfma_f32_16x16x32_bf16 v[18:21], v[174:177], v[212:215], v[18:21]
	v_mfma_f32_16x16x32_bf16 v[2:5], v[174:177], v[220:223], v[2:5]
	v_mfma_f32_16x16x32_bf16 v[6:9], v[166:169], v[220:223], v[6:9]
	s_setprio 0
	s_barrier
	s_add_i32 s61, 0, 0x18000
	s_add_i32 s88, 0, 0x1c000
	v_add_u32_e32 v158, s61, v155
	v_add_u32_e32 v174, s88, v155
	ds_read_b128 v[140:143], v158
	ds_read_b128 v[144:147], v158 offset:1024
	ds_read_b128 v[148:151], v158 offset:2048
	ds_read_b128 v[158:161], v158 offset:3072
	ds_read_b128 v[162:165], v174
	ds_read_b128 v[166:169], v174 offset:1024
	ds_read_b128 v[170:173], v174 offset:2048
	ds_read_b128 v[174:177], v174 offset:3072
	s_add_u32 s4, vcc_lo, 0x80000
	s_addc_u32 s5, vcc_hi, 0
	s_mov_b32 m0, s64
	v_lshl_add_u64 v[228:229], s[4:5], 0, v[130:131]
	ds_read_b128 v[178:181], v157 offset:32768
	ds_read_b128 v[182:185], v157 offset:33792
	ds_read_b128 v[186:189], v157 offset:34816
	ds_read_b128 v[190:193], v157 offset:35840
	ds_read_b128 v[198:201], v157 offset:36864
	ds_read_b128 v[212:215], v157 offset:37888
	ds_read_b128 v[216:219], v157 offset:38912
	ds_read_b128 v[220:223], v157 offset:39936
	global_load_lds_dwordx4 v[228:229], off
	v_lshl_add_u64 v[228:229], s[4:5], 0, v[132:133]
	s_mov_b32 m0, s65
	s_nop 0
	global_load_lds_dwordx4 v[228:229], off
	s_waitcnt vmcnt(8)
	s_waitcnt lgkmcnt(0)
	s_barrier
	s_setprio 1
	s_waitcnt lgkmcnt(0)
	v_mfma_f32_16x16x32_bf16 v[126:129], v[140:143], v[178:181], v[126:129]
	v_mfma_f32_16x16x32_bf16 v[122:125], v[148:151], v[178:181], v[122:125]
	v_mfma_f32_16x16x32_bf16 v[106:109], v[148:151], v[186:189], v[106:109]
	v_mfma_f32_16x16x32_bf16 v[110:113], v[140:143], v[186:189], v[110:113]
	v_mfma_f32_16x16x32_bf16 v[94:97], v[140:143], v[198:201], v[94:97]
	v_mfma_f32_16x16x32_bf16 v[90:93], v[148:151], v[198:201], v[90:93]
	v_mfma_f32_16x16x32_bf16 v[74:77], v[148:151], v[216:219], v[74:77]
	v_mfma_f32_16x16x32_bf16 v[78:81], v[140:143], v[216:219], v[78:81]
	v_mfma_f32_16x16x32_bf16 v[126:129], v[144:147], v[182:185], v[126:129]
	v_mfma_f32_16x16x32_bf16 v[122:125], v[158:161], v[182:185], v[122:125]
	v_mfma_f32_16x16x32_bf16 v[106:109], v[158:161], v[190:193], v[106:109]
	v_mfma_f32_16x16x32_bf16 v[110:113], v[144:147], v[190:193], v[110:113]
	v_mfma_f32_16x16x32_bf16 v[94:97], v[144:147], v[212:215], v[94:97]
	v_mfma_f32_16x16x32_bf16 v[90:93], v[158:161], v[212:215], v[90:93]
	v_mfma_f32_16x16x32_bf16 v[74:77], v[158:161], v[220:223], v[74:77]
	v_mfma_f32_16x16x32_bf16 v[78:81], v[144:147], v[220:223], v[78:81]
	s_setprio 0
	s_setprio 1
	v_mfma_f32_16x16x32_bf16 v[118:121], v[162:165], v[178:181], v[118:121]
	v_mfma_f32_16x16x32_bf16 v[114:117], v[170:173], v[178:181], v[114:117]
	v_mfma_f32_16x16x32_bf16 v[98:101], v[170:173], v[186:189], v[98:101]
	v_mfma_f32_16x16x32_bf16 v[102:105], v[162:165], v[186:189], v[102:105]
	v_mfma_f32_16x16x32_bf16 v[86:89], v[162:165], v[198:201], v[86:89]
	v_mfma_f32_16x16x32_bf16 v[82:85], v[170:173], v[198:201], v[82:85]
	v_mfma_f32_16x16x32_bf16 v[66:69], v[170:173], v[216:219], v[66:69]
	v_mfma_f32_16x16x32_bf16 v[70:73], v[162:165], v[216:219], v[70:73]
	v_mfma_f32_16x16x32_bf16 v[118:121], v[166:169], v[182:185], v[118:121]
	v_mfma_f32_16x16x32_bf16 v[114:117], v[174:177], v[182:185], v[114:117]
	v_mfma_f32_16x16x32_bf16 v[98:101], v[174:177], v[190:193], v[98:101]
	v_mfma_f32_16x16x32_bf16 v[102:105], v[166:169], v[190:193], v[102:105]
	v_mfma_f32_16x16x32_bf16 v[86:89], v[166:169], v[212:215], v[86:89]
	v_mfma_f32_16x16x32_bf16 v[82:85], v[174:177], v[212:215], v[82:85]
	v_mfma_f32_16x16x32_bf16 v[66:69], v[174:177], v[220:223], v[66:69]
	v_mfma_f32_16x16x32_bf16 v[70:73], v[166:169], v[220:223], v[70:73]
	s_setprio 0
	s_barrier
; #define PG8_STAGE(bufoff, gbase, voff) do { _Pragma("unroll") for (int _i = 0; _i < 2; ++_i) \
;         __builtin_amdgcn_global_load_lds((const unsigned*)((const char*)(gbase) + (voff)[_i]), (PG8_LAS unsigned*)(lds + (bufoff) + ldsw + _i * 8192), 16, 0, 0); } while (0)
; #define PG8_LDA(dst, b, h) do { _Pragma("unroll") for (int m = 0; m < 4; ++m) _Pragma("unroll") for (int k = 0; k < 2; ++k) dst[m][k] = *(const PG8_LAS bf16x8*)(lds + PG8_SA(b, h) + aoff + m * 2048 + k * 1024); } while (0)
; #define PG8_MMA(ai, bj, At, Bt) do { __builtin_amdgcn_s_setprio(1); _Pragma("unroll") for (int m = 0; m < 4; ++m) _Pragma("unroll") for (int n = 0; n < 2; ++n) _Pragma("unroll") for (int k = 0; k < 2; ++k) \
;         acc[ai][bj][m][n] = __builtin_amdgcn_mfma_f32_16x16x32_bf16(Bt[n][k], At[m][k], acc[ai][bj][m][n], 0, 0, 0); __builtin_amdgcn_s_setprio(0); } while (0)
; #define PG8_WAIT_V(n) asm volatile("s_waitcnt vmcnt(" #n ")" ::: "memory")
; #define PG8_WAIT_L(n) asm volatile("s_waitcnt lgkmcnt(" #n ")" ::: "memory")
; #define PG8_BAR __builtin_amdgcn_s_barrier()
; #define PG8_SCHED __builtin_amdgcn_sched_barrier(0)
; template <class Epi, class Sched, bool ALIGN_EPI = false, bool SP2 = false>
; __device__ __forceinline__ void gemm_phase(PG8_LAS unsigned char* lds, const Gemm g, const Sched& S, const Epi& E, const int tid) {
;     ...
;         for (int t = 0; t < nt; t += 2) {
;             const bool last = (t == nt - 2);
;             const char* a1 = cA + (size_t)(t + 1) * kstep;
;             const char* a2 = last ? nA : cA + (size_t)(t + 2) * kstep; const char* b2 = last ? nB : cB + (size_t)(t + 2) * kstep;
;             const char* a3 = a2 + kstep; const char* b3 = b2 + kstep;
;             if (last && has_next) S.a_ready(nxt);
;     ...
;             PG8_LDA(At, 1, 1); PG8_STAGE(PG8_SB(1, 0), b3, voffB); PG8_STAGE(PG8_SB(1, 1), b3 + hstepB, voffB); PG8_STAGE(PG8_SA(1, 0), a3, voffA);
;             PG8_WAIT_V(8); PG8_WAIT_L(0); PG8_BAR; PG8_MMA(1, 0, At, B0); PG8_MMA(1, 1, At, B1); PG8_BAR; PG8_SCHED;
	s_add_i32 s4, s61, s56
	v_lshl_add_u64 v[152:153], v[152:153], 0, s[70:71]
	s_mov_b32 m0, s4
	ds_read_b128 v[178:181], v157 offset:49152
	ds_read_b128 v[182:185], v157 offset:50176
	ds_read_b128 v[186:189], v157 offset:51200
	ds_read_b128 v[190:193], v157 offset:52224
	ds_read_b128 v[198:201], v157 offset:53248
	ds_read_b128 v[212:215], v157 offset:54272
	ds_read_b128 v[216:219], v157 offset:55296
	ds_read_b128 v[220:223], v157 offset:56320
	global_load_lds_dwordx4 v[152:153], off
	s_add_i32 m0, s4, 0x2000
	s_add_u32 s4, s92, 0x80080
	v_lshl_add_u64 v[152:153], v[202:203], 0, s[70:71]
	s_addc_u32 s5, s93, 0
	s_add_i32 s61, s88, s56
	global_load_lds_dwordx4 v[152:153], off
	v_lshl_add_u64 v[152:153], s[4:5], 0, v[0:1]
	s_mov_b32 m0, s61
	s_nop 0
	global_load_lds_dwordx4 v[152:153], off
	v_lshl_add_u64 v[152:153], s[4:5], 0, v[134:135]
	s_add_i32 m0, s61, 0x2000
	s_nop 0
	global_load_lds_dwordx4 v[152:153], off
	v_lshl_add_u64 v[152:153], v[224:225], 0, s[70:71]
	s_mov_b32 m0, s67
	s_nop 0
	global_load_lds_dwordx4 v[152:153], off
	v_lshl_add_u64 v[152:153], v[226:227], 0, s[70:71]
	s_mov_b32 m0, s97
	s_nop 0
	global_load_lds_dwordx4 v[152:153], off
	s_waitcnt vmcnt(8)
	s_waitcnt lgkmcnt(0)
	s_barrier
	s_setprio 1
	s_waitcnt lgkmcnt(0)
	v_mfma_f32_16x16x32_bf16 v[62:65], v[140:143], v[178:181], v[62:65]
	v_mfma_f32_16x16x32_bf16 v[58:61], v[148:151], v[178:181], v[58:61]
	v_mfma_f32_16x16x32_bf16 v[42:45], v[148:151], v[186:189], v[42:45]
	v_mfma_f32_16x16x32_bf16 v[46:49], v[140:143], v[186:189], v[46:49]
	v_mfma_f32_16x16x32_bf16 v[30:33], v[140:143], v[198:201], v[30:33]
	v_mfma_f32_16x16x32_bf16 v[26:29], v[148:151], v[198:201], v[26:29]
	v_mfma_f32_16x16x32_bf16 v[10:13], v[148:151], v[216:219], v[10:13]
	v_mfma_f32_16x16x32_bf16 v[14:17], v[140:143], v[216:219], v[14:17]
	v_mfma_f32_16x16x32_bf16 v[62:65], v[144:147], v[182:185], v[62:65]
	v_mfma_f32_16x16x32_bf16 v[58:61], v[158:161], v[182:185], v[58:61]
	v_mfma_f32_16x16x32_bf16 v[42:45], v[158:161], v[190:193], v[42:45]
	v_mfma_f32_16x16x32_bf16 v[46:49], v[144:147], v[190:193], v[46:49]
	v_mfma_f32_16x16x32_bf16 v[30:33], v[144:147], v[212:215], v[30:33]
	v_mfma_f32_16x16x32_bf16 v[26:29], v[158:161], v[212:215], v[26:29]
	v_mfma_f32_16x16x32_bf16 v[10:13], v[158:161], v[220:223], v[10:13]
	v_mfma_f32_16x16x32_bf16 v[14:17], v[144:147], v[220:223], v[14:17]
	s_setprio 0
	s_setprio 1
	v_mfma_f32_16x16x32_bf16 v[54:57], v[162:165], v[178:181], v[54:57]
	v_mfma_f32_16x16x32_bf16 v[50:53], v[170:173], v[178:181], v[50:53]
	v_mfma_f32_16x16x32_bf16 v[34:37], v[170:173], v[186:189], v[34:37]
	v_mfma_f32_16x16x32_bf16 v[38:41], v[162:165], v[186:189], v[38:41]
	v_mfma_f32_16x16x32_bf16 v[22:25], v[162:165], v[198:201], v[22:25]
	v_mfma_f32_16x16x32_bf16 v[18:21], v[170:173], v[198:201], v[18:21]
	v_mfma_f32_16x16x32_bf16 v[2:5], v[170:173], v[216:219], v[2:5]
	v_mfma_f32_16x16x32_bf16 v[6:9], v[162:165], v[216:219], v[6:9]
	v_mfma_f32_16x16x32_bf16 v[54:57], v[166:169], v[182:185], v[54:57]
	v_mfma_f32_16x16x32_bf16 v[50:53], v[174:177], v[182:185], v[50:53]
	v_mfma_f32_16x16x32_bf16 v[34:37], v[174:177], v[190:193], v[34:37]
	v_mfma_f32_16x16x32_bf16 v[38:41], v[166:169], v[190:193], v[38:41]
	v_mfma_f32_16x16x32_bf16 v[22:25], v[166:169], v[212:215], v[22:25]
	v_mfma_f32_16x16x32_bf16 v[18:21], v[174:177], v[212:215], v[18:21]
	v_mfma_f32_16x16x32_bf16 v[2:5], v[174:177], v[220:223], v[2:5]
	v_mfma_f32_16x16x32_bf16 v[6:9], v[166:169], v[220:223], v[6:9]
	s_setprio 0
	s_barrier
	s_add_i32 s62, s62, 2
	s_add_u32 s94, s94, 0x100
	s_addc_u32 s60, s60, 0
	s_add_u32 s2, s2, 0x100
	s_addc_u32 s3, s3, 0
	s_cmp_gt_u32 s62, 29
	s_cbranch_scc0 .LBB0_265
	s_and_b64 vcc, exec, s[18:19]
	s_cbranch_vccz .LBB0_268
	s_barrier

; #define PG8_STAGE(bufoff, gbase, voff) do { _Pragma("unroll") for (int _i = 0; _i < 2; ++_i) \
;         __builtin_amdgcn_global_load_lds((const unsigned*)((const char*)(gbase) + (voff)[_i]), (PG8_LAS unsigned*)(lds + (bufoff) + ldsw + _i * 8192), 16, 0, 0); } while (0)
; #define PG8_LDA(dst, b, h) do { _Pragma("unroll") for (int m = 0; m < 4; ++m) _Pragma("unroll") for (int k = 0; k < 2; ++k) dst[m][k] = *(const PG8_LAS bf16x8*)(lds + PG8_SA(b, h) + aoff + m * 2048 + k * 1024); } while (0)
; #define PG8_LDB(dst, b, h) do { _Pragma("unroll") for (int n = 0; n < 2; ++n) _Pragma("unroll") for (int k = 0; k < 2; ++k) dst[n][k] = *(const PG8_LAS bf16x8*)(lds + PG8_SB(b, h) + boff + n * 2048 + k * 1024); } while (0)
; #define PG8_MMA(ai, bj, At, Bt) do { __builtin_amdgcn_s_setprio(1); _Pragma("unroll") for (int m = 0; m < 4; ++m) _Pragma("unroll") for (int n = 0; n < 2; ++n) _Pragma("unroll") for (int k = 0; k < 2; ++k) \
;         acc[ai][bj][m][n] = __builtin_amdgcn_mfma_f32_16x16x32_bf16(Bt[n][k], At[m][k], acc[ai][bj][m][n], 0, 0, 0); __builtin_amdgcn_s_setprio(0); } while (0)
; #define PG8_WAIT_V(n) asm volatile("s_waitcnt vmcnt(" #n ")" ::: "memory")
; #define PG8_WAIT_L(n) asm volatile("s_waitcnt lgkmcnt(" #n ")" ::: "memory")
; #define PG8_BAR __builtin_amdgcn_s_barrier()
; #define PG8_SCHED __builtin_amdgcn_sched_barrier(0)
; template <class Epi, class Sched, bool ALIGN_EPI = false, bool SP2 = false>
; __device__ __forceinline__ void gemm_phase(PG8_LAS unsigned char* lds, const Gemm g, const Sched& S, const Epi& E, const int tid) {
;     ...
;             PG8_LDB(B0, 0, 0); PG8_LDB(B1, 0, 1); PG8_SCHED; PG8_LDA(At, 0, 0); PG8_STAGE(PG8_SA(1, 1), a1 + hstepA, voffA);
;             PG8_WAIT_V(8); PG8_WAIT_L(0); PG8_BAR; PG8_MMA(0, 0, At, B0); PG8_MMA(0, 1, At, B1); PG8_BAR; PG8_SCHED;
;             PG8_LDA(At, 0, 1); PG8_STAGE(PG8_SB(0, 0), b2, voffB); PG8_STAGE(PG8_SB(0, 1), b2 + hstepB, voffB); PG8_STAGE(PG8_SA(0, 0), a2, voffA);
;             PG8_WAIT_V(8); PG8_WAIT_L(0); PG8_BAR; PG8_MMA(1, 0, At, B0); PG8_MMA(1, 1, At, B1); PG8_BAR; PG8_SCHED;
.LBB0_346:
	s_add_u32 s34, s2, 0xfff00080
	s_addc_u32 s35, s3, -1
	s_add_i32 vcc_lo, 0, 0x10000
	s_cmp_eq_u32 s60, 60
	s_cselect_b32 s93, s9, s35
	s_cselect_b32 s92, s21, s34
	s_cselect_b32 s35, s25, s97
	s_cselect_b32 s34, s67, s94
	s_add_i32 s61, 0, 0x14000
	v_add_u32_e32 v156, vcc_lo, v145
	v_add_u32_e32 v172, s61, v145
	ds_read_b128 v[140:143], v156
	ds_read_b128 v[148:151], v156 offset:1024
	ds_read_b128 v[152:155], v156 offset:2048
	ds_read_b128 v[156:159], v156 offset:3072
	ds_read_b128 v[160:163], v172
	ds_read_b128 v[164:167], v172 offset:1024
	ds_read_b128 v[168:171], v172 offset:2048
	ds_read_b128 v[172:175], v172 offset:3072
	v_lshl_add_u64 v[192:193], s[2:3], 0, v[138:139]
	s_add_i32 m0, s31, 0xc000
	ds_read_b128 v[176:179], v147
	ds_read_b128 v[180:183], v147 offset:1024
	ds_read_b128 v[184:187], v147 offset:2048
	ds_read_b128 v[188:191], v147 offset:3072
	ds_read_b128 v[198:201], v147 offset:4096
	ds_read_b128 v[212:215], v147 offset:5120
	ds_read_b128 v[216:219], v147 offset:6144
	ds_read_b128 v[220:223], v147 offset:7168
	global_load_lds_dwordx4 v[192:193], off
	v_lshl_add_u64 v[192:193], s[2:3], 0, v[136:137]
	s_add_i32 m0, s31, 0xe000
	s_nop 0
	global_load_lds_dwordx4 v[192:193], off
	s_waitcnt vmcnt(8)
	s_waitcnt lgkmcnt(0)
	s_barrier
	s_setprio 1
	s_waitcnt lgkmcnt(0)
	v_mfma_f32_16x16x32_bf16 v[126:129], v[140:143], v[176:179], v[126:129]
	v_mfma_f32_16x16x32_bf16 v[122:125], v[152:155], v[176:179], v[122:125]
	v_mfma_f32_16x16x32_bf16 v[106:109], v[152:155], v[184:187], v[106:109]
	v_mfma_f32_16x16x32_bf16 v[110:113], v[140:143], v[184:187], v[110:113]
	v_mfma_f32_16x16x32_bf16 v[94:97], v[140:143], v[198:201], v[94:97]
	v_mfma_f32_16x16x32_bf16 v[90:93], v[152:155], v[198:201], v[90:93]
	v_mfma_f32_16x16x32_bf16 v[74:77], v[152:155], v[216:219], v[74:77]
	v_mfma_f32_16x16x32_bf16 v[78:81], v[140:143], v[216:219], v[78:81]
	v_mfma_f32_16x16x32_bf16 v[126:129], v[148:151], v[180:183], v[126:129]
	v_mfma_f32_16x16x32_bf16 v[122:125], v[156:159], v[180:183], v[122:125]
	v_mfma_f32_16x16x32_bf16 v[106:109], v[156:159], v[188:191], v[106:109]
	v_mfma_f32_16x16x32_bf16 v[110:113], v[148:151], v[188:191], v[110:113]
	v_mfma_f32_16x16x32_bf16 v[94:97], v[148:151], v[212:215], v[94:97]
	v_mfma_f32_16x16x32_bf16 v[90:93], v[156:159], v[212:215], v[90:93]
	v_mfma_f32_16x16x32_bf16 v[74:77], v[156:159], v[220:223], v[74:77]
	v_mfma_f32_16x16x32_bf16 v[78:81], v[148:151], v[220:223], v[78:81]
	s_setprio 0
	s_setprio 1
	v_mfma_f32_16x16x32_bf16 v[118:121], v[160:163], v[176:179], v[118:121]
	v_mfma_f32_16x16x32_bf16 v[114:117], v[168:171], v[176:179], v[114:117]
	v_mfma_f32_16x16x32_bf16 v[98:101], v[168:171], v[184:187], v[98:101]
	v_mfma_f32_16x16x32_bf16 v[102:105], v[160:163], v[184:187], v[102:105]
	v_mfma_f32_16x16x32_bf16 v[86:89], v[160:163], v[198:201], v[86:89]
	v_mfma_f32_16x16x32_bf16 v[82:85], v[168:171], v[198:201], v[82:85]
	v_mfma_f32_16x16x32_bf16 v[66:69], v[168:171], v[216:219], v[66:69]
	v_mfma_f32_16x16x32_bf16 v[70:73], v[160:163], v[216:219], v[70:73]
	v_mfma_f32_16x16x32_bf16 v[118:121], v[164:167], v[180:183], v[118:121]
	v_mfma_f32_16x16x32_bf16 v[114:117], v[172:175], v[180:183], v[114:117]
	v_mfma_f32_16x16x32_bf16 v[98:101], v[172:175], v[188:191], v[98:101]
	v_mfma_f32_16x16x32_bf16 v[102:105], v[164:167], v[188:191], v[102:105]
	v_mfma_f32_16x16x32_bf16 v[86:89], v[164:167], v[212:215], v[86:89]
	v_mfma_f32_16x16x32_bf16 v[82:85], v[172:175], v[212:215], v[82:85]
	v_mfma_f32_16x16x32_bf16 v[66:69], v[172:175], v[220:223], v[66:69]
	v_mfma_f32_16x16x32_bf16 v[70:73], v[164:167], v[220:223], v[70:73]
	s_setprio 0
	s_barrier
	s_add_i32 vcc_lo, vcc_lo, s54
	v_lshl_add_u64 v[192:193], s[34:35], 0, v[0:1]
	s_mov_b32 m0, vcc_lo
	ds_read_b128 v[176:179], v147 offset:16384
	ds_read_b128 v[180:183], v147 offset:17408
	ds_read_b128 v[184:187], v147 offset:18432
	ds_read_b128 v[188:191], v147 offset:19456
	ds_read_b128 v[198:201], v147 offset:20480
	ds_read_b128 v[212:215], v147 offset:21504
	ds_read_b128 v[216:219], v147 offset:22528
	ds_read_b128 v[220:223], v147 offset:23552
	global_load_lds_dwordx4 v[192:193], off
	s_add_i32 m0, vcc_lo, 0x2000
	s_add_u32 vcc_lo, s34, 0x100000
	v_lshl_add_u64 v[202:203], s[34:35], 0, v[134:135]
	s_addc_u32 vcc_hi, s35, 0
	s_add_i32 s61, s61, s54
	global_load_lds_dwordx4 v[202:203], off
	v_lshl_add_u64 v[224:225], vcc, 0, v[0:1]
	s_mov_b32 m0, s61
	v_lshl_add_u64 v[226:227], s[92:93], 0, v[132:133]
	global_load_lds_dwordx4 v[224:225], off
	v_lshl_add_u64 v[224:225], vcc, 0, v[134:135]
	s_add_i32 m0, s61, 0x2000
	s_nop 0
	global_load_lds_dwordx4 v[224:225], off
	v_lshl_add_u64 v[224:225], s[92:93], 0, v[130:131]
	s_mov_b32 m0, s31
	s_nop 0
	global_load_lds_dwordx4 v[224:225], off
	s_mov_b32 m0, s55
	s_nop 0
	global_load_lds_dwordx4 v[226:227], off
	s_waitcnt vmcnt(8)
	s_waitcnt lgkmcnt(0)
	s_barrier
; #define PG8_STAGE(bufoff, gbase, voff) do { _Pragma("unroll") for (int _i = 0; _i < 2; ++_i) \
;         __builtin_amdgcn_global_load_lds((const unsigned*)((const char*)(gbase) + (voff)[_i]), (PG8_LAS unsigned*)(lds + (bufoff) + ldsw + _i * 8192), 16, 0, 0); } while (0)
; #define PG8_LDA(dst, b, h) do { _Pragma("unroll") for (int m = 0; m < 4; ++m) _Pragma("unroll") for (int k = 0; k < 2; ++k) dst[m][k] = *(const PG8_LAS bf16x8*)(lds + PG8_SA(b, h) + aoff + m * 2048 + k * 1024); } while (0)
; #define PG8_LDB(dst, b, h) do { _Pragma("unroll") for (int n = 0; n < 2; ++n) _Pragma("unroll") for (int k = 0; k < 2; ++k) dst[n][k] = *(const PG8_LAS bf16x8*)(lds + PG8_SB(b, h) + boff + n * 2048 + k * 1024); } while (0)
; #define PG8_MMA(ai, bj, At, Bt) do { __builtin_amdgcn_s_setprio(1); _Pragma("unroll") for (int m = 0; m < 4; ++m) _Pragma("unroll") for (int n = 0; n < 2; ++n) _Pragma("unroll") for (int k = 0; k < 2; ++k) \
;         acc[ai][bj][m][n] = __builtin_amdgcn_mfma_f32_16x16x32_bf16(Bt[n][k], At[m][k], acc[ai][bj][m][n], 0, 0, 0); __builtin_amdgcn_s_setprio(0); } while (0)
; #define PG8_WAIT_V(n) asm volatile("s_waitcnt vmcnt(" #n ")" ::: "memory")
; #define PG8_WAIT_L(n) asm volatile("s_waitcnt lgkmcnt(" #n ")" ::: "memory")
; #define PG8_BAR __builtin_amdgcn_s_barrier()
; #define PG8_SCHED __builtin_amdgcn_sched_barrier(0)
; template <class Epi, class Sched, bool ALIGN_EPI = false, bool SP2 = false>
; __device__ __forceinline__ void gemm_phase(PG8_LAS unsigned char* lds, const Gemm g, const Sched& S, const Epi& E, const int tid) {
;     ...
;             PG8_WAIT_V(8); PG8_WAIT_L(0); PG8_BAR; PG8_MMA(1, 0, At, B0); PG8_MMA(1, 1, At, B1); PG8_BAR; PG8_SCHED;
;             PG8_LDB(B0, 1, 0); PG8_LDB(B1, 1, 1); PG8_SCHED; PG8_LDA(At, 1, 0); PG8_STAGE(PG8_SA(0, 1), a2 + hstepA, voffA);
;             PG8_WAIT_V(8); PG8_WAIT_L(0); PG8_BAR; PG8_MMA(0, 0, At, B0); PG8_MMA(0, 1, At, B1); PG8_BAR; PG8_SCHED;
	s_setprio 1
	s_waitcnt lgkmcnt(0)
	v_mfma_f32_16x16x32_bf16 v[62:65], v[140:143], v[176:179], v[62:65]
	v_mfma_f32_16x16x32_bf16 v[58:61], v[152:155], v[176:179], v[58:61]
	v_mfma_f32_16x16x32_bf16 v[42:45], v[152:155], v[184:187], v[42:45]
	v_mfma_f32_16x16x32_bf16 v[46:49], v[140:143], v[184:187], v[46:49]
	v_mfma_f32_16x16x32_bf16 v[30:33], v[140:143], v[198:201], v[30:33]
	v_mfma_f32_16x16x32_bf16 v[26:29], v[152:155], v[198:201], v[26:29]
	v_mfma_f32_16x16x32_bf16 v[10:13], v[152:155], v[216:219], v[10:13]
	v_mfma_f32_16x16x32_bf16 v[14:17], v[140:143], v[216:219], v[14:17]
	v_mfma_f32_16x16x32_bf16 v[62:65], v[148:151], v[180:183], v[62:65]
	v_mfma_f32_16x16x32_bf16 v[58:61], v[156:159], v[180:183], v[58:61]
	v_mfma_f32_16x16x32_bf16 v[42:45], v[156:159], v[188:191], v[42:45]
	v_mfma_f32_16x16x32_bf16 v[46:49], v[148:151], v[188:191], v[46:49]
	v_mfma_f32_16x16x32_bf16 v[30:33], v[148:151], v[212:215], v[30:33]
	v_mfma_f32_16x16x32_bf16 v[26:29], v[156:159], v[212:215], v[26:29]
	v_mfma_f32_16x16x32_bf16 v[10:13], v[156:159], v[220:223], v[10:13]
	v_mfma_f32_16x16x32_bf16 v[14:17], v[148:151], v[220:223], v[14:17]
	s_setprio 0
	s_setprio 1
	v_mfma_f32_16x16x32_bf16 v[54:57], v[160:163], v[176:179], v[54:57]
	v_mfma_f32_16x16x32_bf16 v[50:53], v[168:171], v[176:179], v[50:53]
	v_mfma_f32_16x16x32_bf16 v[34:37], v[168:171], v[184:187], v[34:37]
	v_mfma_f32_16x16x32_bf16 v[38:41], v[160:163], v[184:187], v[38:41]
	v_mfma_f32_16x16x32_bf16 v[22:25], v[160:163], v[198:201], v[22:25]
	v_mfma_f32_16x16x32_bf16 v[18:21], v[168:171], v[198:201], v[18:21]
	v_mfma_f32_16x16x32_bf16 v[2:5], v[168:171], v[216:219], v[2:5]
	v_mfma_f32_16x16x32_bf16 v[6:9], v[160:163], v[216:219], v[6:9]
	v_mfma_f32_16x16x32_bf16 v[54:57], v[164:167], v[180:183], v[54:57]
	v_mfma_f32_16x16x32_bf16 v[50:53], v[172:175], v[180:183], v[50:53]
	v_mfma_f32_16x16x32_bf16 v[34:37], v[172:175], v[188:191], v[34:37]
	v_mfma_f32_16x16x32_bf16 v[38:41], v[164:167], v[188:191], v[38:41]
	v_mfma_f32_16x16x32_bf16 v[22:25], v[164:167], v[212:215], v[22:25]
	v_mfma_f32_16x16x32_bf16 v[18:21], v[172:175], v[212:215], v[18:21]
	v_mfma_f32_16x16x32_bf16 v[2:5], v[172:175], v[220:223], v[2:5]
	v_mfma_f32_16x16x32_bf16 v[6:9], v[164:167], v[220:223], v[6:9]
	s_setprio 0
	s_barrier
	s_add_i32 s61, 0, 0x18000
	s_add_i32 vcc_lo, 0, 0x1c000
	v_add_u32_e32 v156, s61, v145
	v_add_u32_e32 v172, vcc_lo, v145
	ds_read_b128 v[140:143], v156
	ds_read_b128 v[148:151], v156 offset:1024
	ds_read_b128 v[152:155], v156 offset:2048
	ds_read_b128 v[156:159], v156 offset:3072
	ds_read_b128 v[160:163], v172
	ds_read_b128 v[164:167], v172 offset:1024
	ds_read_b128 v[168:171], v172 offset:2048
	ds_read_b128 v[172:175], v172 offset:3072
	s_add_u32 s92, s92, 0x100000
	s_addc_u32 s93, s93, 0
	s_mov_b32 m0, s56
	v_lshl_add_u64 v[228:229], s[92:93], 0, v[130:131]
	ds_read_b128 v[176:179], v147 offset:32768
	ds_read_b128 v[180:183], v147 offset:33792
	ds_read_b128 v[184:187], v147 offset:34816
	ds_read_b128 v[188:191], v147 offset:35840
	ds_read_b128 v[198:201], v147 offset:36864
	ds_read_b128 v[212:215], v147 offset:37888
	ds_read_b128 v[216:219], v147 offset:38912
	ds_read_b128 v[220:223], v147 offset:39936
	global_load_lds_dwordx4 v[228:229], off
	v_lshl_add_u64 v[228:229], s[92:93], 0, v[132:133]
	s_mov_b32 m0, s62
	s_nop 0
	global_load_lds_dwordx4 v[228:229], off
	s_waitcnt vmcnt(8)
	s_waitcnt lgkmcnt(0)
	s_barrier
	s_setprio 1
	s_waitcnt lgkmcnt(0)
	v_mfma_f32_16x16x32_bf16 v[126:129], v[140:143], v[176:179], v[126:129]
	v_mfma_f32_16x16x32_bf16 v[122:125], v[152:155], v[176:179], v[122:125]
	v_mfma_f32_16x16x32_bf16 v[106:109], v[152:155], v[184:187], v[106:109]
	v_mfma_f32_16x16x32_bf16 v[110:113], v[140:143], v[184:187], v[110:113]
	v_mfma_f32_16x16x32_bf16 v[94:97], v[140:143], v[198:201], v[94:97]
	v_mfma_f32_16x16x32_bf16 v[90:93], v[152:155], v[198:201], v[90:93]
	v_mfma_f32_16x16x32_bf16 v[74:77], v[152:155], v[216:219], v[74:77]
	v_mfma_f32_16x16x32_bf16 v[78:81], v[140:143], v[216:219], v[78:81]
	v_mfma_f32_16x16x32_bf16 v[126:129], v[148:151], v[180:183], v[126:129]
	v_mfma_f32_16x16x32_bf16 v[122:125], v[156:159], v[180:183], v[122:125]
	v_mfma_f32_16x16x32_bf16 v[106:109], v[156:159], v[188:191], v[106:109]
	v_mfma_f32_16x16x32_bf16 v[110:113], v[148:151], v[188:191], v[110:113]
	v_mfma_f32_16x16x32_bf16 v[94:97], v[148:151], v[212:215], v[94:97]
	v_mfma_f32_16x16x32_bf16 v[90:93], v[156:159], v[212:215], v[90:93]
	v_mfma_f32_16x16x32_bf16 v[74:77], v[156:159], v[220:223], v[74:77]
	v_mfma_f32_16x16x32_bf16 v[78:81], v[148:151], v[220:223], v[78:81]
	s_setprio 0
	s_setprio 1
	v_mfma_f32_16x16x32_bf16 v[118:121], v[160:163], v[176:179], v[118:121]
	v_mfma_f32_16x16x32_bf16 v[114:117], v[168:171], v[176:179], v[114:117]
	v_mfma_f32_16x16x32_bf16 v[98:101], v[168:171], v[184:187], v[98:101]
	v_mfma_f32_16x16x32_bf16 v[102:105], v[160:163], v[184:187], v[102:105]
	v_mfma_f32_16x16x32_bf16 v[86:89], v[160:163], v[198:201], v[86:89]
	v_mfma_f32_16x16x32_bf16 v[82:85], v[168:171], v[198:201], v[82:85]
	v_mfma_f32_16x16x32_bf16 v[66:69], v[168:171], v[216:219], v[66:69]
	v_mfma_f32_16x16x32_bf16 v[70:73], v[160:163], v[216:219], v[70:73]
	v_mfma_f32_16x16x32_bf16 v[118:121], v[164:167], v[180:183], v[118:121]
	v_mfma_f32_16x16x32_bf16 v[114:117], v[172:175], v[180:183], v[114:117]
	v_mfma_f32_16x16x32_bf16 v[98:101], v[172:175], v[188:191], v[98:101]
	v_mfma_f32_16x16x32_bf16 v[102:105], v[164:167], v[188:191], v[102:105]
	v_mfma_f32_16x16x32_bf16 v[86:89], v[164:167], v[212:215], v[86:89]
	v_mfma_f32_16x16x32_bf16 v[82:85], v[172:175], v[212:215], v[82:85]
	v_mfma_f32_16x16x32_bf16 v[66:69], v[172:175], v[220:223], v[66:69]
	v_mfma_f32_16x16x32_bf16 v[70:73], v[164:167], v[220:223], v[70:73]
	s_setprio 0
	s_barrier
; #define PG8_STAGE(bufoff, gbase, voff) do { _Pragma("unroll") for (int _i = 0; _i < 2; ++_i) \
;         __builtin_amdgcn_global_load_lds((const unsigned*)((const char*)(gbase) + (voff)[_i]), (PG8_LAS unsigned*)(lds + (bufoff) + ldsw + _i * 8192), 16, 0, 0); } while (0)
; #define PG8_LDA(dst, b, h) do { _Pragma("unroll") for (int m = 0; m < 4; ++m) _Pragma("unroll") for (int k = 0; k < 2; ++k) dst[m][k] = *(const PG8_LAS bf16x8*)(lds + PG8_SA(b, h) + aoff + m * 2048 + k * 1024); } while (0)
; #define PG8_MMA(ai, bj, At, Bt) do { __builtin_amdgcn_s_setprio(1); _Pragma("unroll") for (int m = 0; m < 4; ++m) _Pragma("unroll") for (int n = 0; n < 2; ++n) _Pragma("unroll") for (int k = 0; k < 2; ++k) \
;         acc[ai][bj][m][n] = __builtin_amdgcn_mfma_f32_16x16x32_bf16(Bt[n][k], At[m][k], acc[ai][bj][m][n], 0, 0, 0); __builtin_amdgcn_s_setprio(0); } while (0)
; #define PG8_WAIT_V(n) asm volatile("s_waitcnt vmcnt(" #n ")" ::: "memory")
; #define PG8_WAIT_L(n) asm volatile("s_waitcnt lgkmcnt(" #n ")" ::: "memory")
; #define PG8_BAR __builtin_amdgcn_s_barrier()
; #define PG8_SCHED __builtin_amdgcn_sched_barrier(0)
; template <class Epi, class Sched, bool ALIGN_EPI = false, bool SP2 = false>
; __device__ __forceinline__ void gemm_phase(PG8_LAS unsigned char* lds, const Gemm g, const Sched& S, const Epi& E, const int tid) {
;     ...
;             PG8_LDA(At, 1, 1); PG8_STAGE(PG8_SB(1, 0), b3, voffB); PG8_STAGE(PG8_SB(1, 1), b3 + hstepB, voffB); PG8_STAGE(PG8_SA(1, 0), a3, voffA);
;             PG8_WAIT_V(8); PG8_WAIT_L(0); PG8_BAR; PG8_MMA(1, 0, At, B0); PG8_MMA(1, 1, At, B1); PG8_BAR; PG8_SCHED;
	s_add_i32 s61, s61, s54
	v_lshl_add_u64 v[192:193], v[192:193], 0, s[70:71]
	s_mov_b32 m0, s61
	ds_read_b128 v[176:179], v147 offset:49152
	ds_read_b128 v[180:183], v147 offset:50176
	ds_read_b128 v[184:187], v147 offset:51200
	ds_read_b128 v[188:191], v147 offset:52224
	ds_read_b128 v[198:201], v147 offset:53248
	ds_read_b128 v[212:215], v147 offset:54272
	ds_read_b128 v[216:219], v147 offset:55296
	ds_read_b128 v[220:223], v147 offset:56320
	global_load_lds_dwordx4 v[192:193], off
	s_add_i32 m0, s61, 0x2000
	s_add_u32 s34, s34, 0x100080
	v_lshl_add_u64 v[192:193], v[202:203], 0, s[70:71]
	s_addc_u32 s35, s35, 0
	s_add_i32 s61, vcc_lo, s54
	global_load_lds_dwordx4 v[192:193], off
	v_lshl_add_u64 v[192:193], s[34:35], 0, v[0:1]
	s_mov_b32 m0, s61
	s_nop 0
	global_load_lds_dwordx4 v[192:193], off
	v_lshl_add_u64 v[192:193], s[34:35], 0, v[134:135]
	s_add_i32 m0, s61, 0x2000
	s_nop 0
	global_load_lds_dwordx4 v[192:193], off
	v_lshl_add_u64 v[192:193], v[224:225], 0, s[70:71]
	s_mov_b32 m0, s64
	s_nop 0
	global_load_lds_dwordx4 v[192:193], off
	v_lshl_add_u64 v[192:193], v[226:227], 0, s[70:71]
	s_mov_b32 m0, s65
	s_nop 0
	global_load_lds_dwordx4 v[192:193], off
	s_waitcnt vmcnt(8)
	s_waitcnt lgkmcnt(0)
	s_barrier
	s_setprio 1
	s_waitcnt lgkmcnt(0)
	v_mfma_f32_16x16x32_bf16 v[62:65], v[140:143], v[176:179], v[62:65]
	v_mfma_f32_16x16x32_bf16 v[58:61], v[152:155], v[176:179], v[58:61]
	v_mfma_f32_16x16x32_bf16 v[42:45], v[152:155], v[184:187], v[42:45]
	v_mfma_f32_16x16x32_bf16 v[46:49], v[140:143], v[184:187], v[46:49]
	v_mfma_f32_16x16x32_bf16 v[30:33], v[140:143], v[198:201], v[30:33]
	v_mfma_f32_16x16x32_bf16 v[26:29], v[152:155], v[198:201], v[26:29]
	v_mfma_f32_16x16x32_bf16 v[10:13], v[152:155], v[216:219], v[10:13]
	v_mfma_f32_16x16x32_bf16 v[14:17], v[140:143], v[216:219], v[14:17]
	v_mfma_f32_16x16x32_bf16 v[62:65], v[148:151], v[180:183], v[62:65]
	v_mfma_f32_16x16x32_bf16 v[58:61], v[156:159], v[180:183], v[58:61]
	v_mfma_f32_16x16x32_bf16 v[42:45], v[156:159], v[188:191], v[42:45]
	v_mfma_f32_16x16x32_bf16 v[46:49], v[148:151], v[188:191], v[46:49]
	v_mfma_f32_16x16x32_bf16 v[30:33], v[148:151], v[212:215], v[30:33]
	v_mfma_f32_16x16x32_bf16 v[26:29], v[156:159], v[212:215], v[26:29]
	v_mfma_f32_16x16x32_bf16 v[10:13], v[156:159], v[220:223], v[10:13]
	v_mfma_f32_16x16x32_bf16 v[14:17], v[148:151], v[220:223], v[14:17]
	s_setprio 0
	s_setprio 1
	v_mfma_f32_16x16x32_bf16 v[54:57], v[160:163], v[176:179], v[54:57]
	v_mfma_f32_16x16x32_bf16 v[50:53], v[168:171], v[176:179], v[50:53]
	v_mfma_f32_16x16x32_bf16 v[34:37], v[168:171], v[184:187], v[34:37]
	v_mfma_f32_16x16x32_bf16 v[38:41], v[160:163], v[184:187], v[38:41]
	v_mfma_f32_16x16x32_bf16 v[22:25], v[160:163], v[198:201], v[22:25]
	v_mfma_f32_16x16x32_bf16 v[18:21], v[168:171], v[198:201], v[18:21]
	v_mfma_f32_16x16x32_bf16 v[2:5], v[168:171], v[216:219], v[2:5]
	v_mfma_f32_16x16x32_bf16 v[6:9], v[160:163], v[216:219], v[6:9]
	v_mfma_f32_16x16x32_bf16 v[54:57], v[164:167], v[180:183], v[54:57]
	v_mfma_f32_16x16x32_bf16 v[50:53], v[172:175], v[180:183], v[50:53]
	v_mfma_f32_16x16x32_bf16 v[34:37], v[172:175], v[188:191], v[34:37]
	v_mfma_f32_16x16x32_bf16 v[38:41], v[164:167], v[188:191], v[38:41]
	v_mfma_f32_16x16x32_bf16 v[22:25], v[164:167], v[212:215], v[22:25]
	v_mfma_f32_16x16x32_bf16 v[18:21], v[172:175], v[212:215], v[18:21]
	v_mfma_f32_16x16x32_bf16 v[2:5], v[172:175], v[220:223], v[2:5]
	v_mfma_f32_16x16x32_bf16 v[6:9], v[164:167], v[220:223], v[6:9]
	s_setprio 0
	s_barrier
	s_add_i32 s60, s60, 2
	s_add_u32 s94, s94, 0x100
	s_addc_u32 s97, s97, 0
	s_add_u32 s2, s2, 0x100
	s_addc_u32 s3, s3, 0
	s_cmp_gt_u32 s60, 61
	s_cbranch_scc0 .LBB0_346
	s_and_b64 vcc, exec, s[16:17]
	s_cbranch_vccz .LBB0_349
	s_barrier

; #define PG8_STAGE(bufoff, gbase, voff) do { _Pragma("unroll") for (int _i = 0; _i < 2; ++_i) \
;         __builtin_amdgcn_global_load_lds((const unsigned*)((const char*)(gbase) + (voff)[_i]), (PG8_LAS unsigned*)(lds + (bufoff) + ldsw + _i * 8192), 16, 0, 0); } while (0)
; #define PG8_LDA(dst, b, h) do { _Pragma("unroll") for (int m = 0; m < 4; ++m) _Pragma("unroll") for (int k = 0; k < 2; ++k) dst[m][k] = *(const PG8_LAS bf16x8*)(lds + PG8_SA(b, h) + aoff + m * 2048 + k * 1024); } while (0)
; #define PG8_LDB(dst, b, h) do { _Pragma("unroll") for (int n = 0; n < 2; ++n) _Pragma("unroll") for (int k = 0; k < 2; ++k) dst[n][k] = *(const PG8_LAS bf16x8*)(lds + PG8_SB(b, h) + boff + n * 2048 + k * 1024); } while (0)
; #define PG8_MMA(ai, bj, At, Bt) do { __builtin_amdgcn_s_setprio(1); _Pragma("unroll") for (int m = 0; m < 4; ++m) _Pragma("unroll") for (int n = 0; n < 2; ++n) _Pragma("unroll") for (int k = 0; k < 2; ++k) \
;         acc[ai][bj][m][n] = __builtin_amdgcn_mfma_f32_16x16x32_bf16(Bt[n][k], At[m][k], acc[ai][bj][m][n], 0, 0, 0); __builtin_amdgcn_s_setprio(0); } while (0)
; #define PG8_WAIT_V(n) asm volatile("s_waitcnt vmcnt(" #n ")" ::: "memory")
; #define PG8_BAR __builtin_amdgcn_s_barrier()
; template <class Epi, class Sched, bool ALIGN_EPI = false, bool SP2 = false>
; __device__ __forceinline__ void gemm_phase(PG8_LAS unsigned char* lds, const Gemm g, const Sched& S, const Epi& E, const int tid) {
;     ...
;         for (int t = 0; t < nt; t += 2) {
;             const bool last = (t == nt - 2);
;             const char* a1 = cA + (size_t)(t + 1) * kstep;
;             const char* a2 = last ? nA : cA + (size_t)(t + 2) * kstep; const char* b2 = last ? nB : cB + (size_t)(t + 2) * kstep;
;             const char* a3 = a2 + kstep; const char* b3 = b2 + kstep;
;             if (last && has_next) S.a_ready(nxt);
;             if constexpr (SP2) {
;             PG8_LDB(B0, 0, 0); PG8_LDB(B1, 0, 1); PG8_SCHED; PG8_LDA(At, 0, 0); PG8_STAGE(PG8_SA(1, 1), a1 + hstepA, voffA);
;             PG8_WAIT_V(8); PG8_WAIT_L(0); PG8_BAR; PG8_MMA(0, 0, At, B0); PG8_MMA(0, 1, At, B1); PG8_BAR; PG8_SCHED;
;             PG8_LDA(At, 0, 1); PG8_STAGE(PG8_SB(0, 0), b2, voffB); PG8_STAGE(PG8_SB(0, 1), b2 + hstepB, voffB); PG8_STAGE(PG8_SA(0, 0), a2, voffA);
;             PG8_WAIT_V(8); PG8_WAIT_L(0); PG8_BAR; PG8_MMA(1, 0, At, B0); PG8_MMA(1, 1, At, B1); PG8_BAR; PG8_SCHED;
.LBB0_387:
	s_add_u32 s26, s2, 0xfff80080
	s_addc_u32 s27, s3, -1
	s_add_i32 s67, 0, 0x10000
	s_cmp_eq_u32 s60, 28
	s_cselect_b32 s29, s17, s27
	s_cselect_b32 s28, s56, s26
	s_cselect_b32 s27, s19, s66
	s_cselect_b32 s26, s64, s65
	s_add_i32 s94, 0, 0x14000
	v_add_u32_e32 v156, s67, v149
	v_add_u32_e32 v172, s94, v149
	ds_read_b128 v[140:143], v156
	ds_read_b128 v[144:147], v156 offset:1024
	ds_read_b128 v[152:155], v156 offset:2048
	ds_read_b128 v[156:159], v156 offset:3072
	ds_read_b128 v[160:163], v172
	ds_read_b128 v[164:167], v172 offset:1024
	ds_read_b128 v[168:171], v172 offset:2048
	ds_read_b128 v[172:175], v172 offset:3072
	v_lshl_add_u64 v[192:193], s[2:3], 0, v[138:139]
	s_add_i32 m0, s9, 0xc000
	ds_read_b128 v[176:179], v151
	ds_read_b128 v[180:183], v151 offset:1024
	ds_read_b128 v[184:187], v151 offset:2048
	ds_read_b128 v[188:191], v151 offset:3072
	ds_read_b128 v[198:201], v151 offset:4096
	ds_read_b128 v[212:215], v151 offset:5120
	ds_read_b128 v[216:219], v151 offset:6144
	ds_read_b128 v[220:223], v151 offset:7168
	global_load_lds_dwordx4 v[192:193], off
	v_lshl_add_u64 v[192:193], s[2:3], 0, v[136:137]
	s_add_i32 m0, s9, 0xe000
	s_nop 0
	global_load_lds_dwordx4 v[192:193], off
	s_waitcnt vmcnt(8)
	s_waitcnt lgkmcnt(0)
	s_barrier
	s_setprio 1
	s_waitcnt lgkmcnt(0)
	v_mfma_f32_16x16x32_bf16 v[126:129], v[140:143], v[176:179], v[126:129]
	v_mfma_f32_16x16x32_bf16 v[118:121], v[152:155], v[176:179], v[118:121]
	v_mfma_f32_16x16x32_bf16 v[102:105], v[152:155], v[184:187], v[102:105]
	v_mfma_f32_16x16x32_bf16 v[110:113], v[140:143], v[184:187], v[110:113]
	v_mfma_f32_16x16x32_bf16 v[94:97], v[140:143], v[198:201], v[94:97]
	v_mfma_f32_16x16x32_bf16 v[86:89], v[152:155], v[198:201], v[86:89]
	v_mfma_f32_16x16x32_bf16 v[70:73], v[152:155], v[216:219], v[70:73]
	v_mfma_f32_16x16x32_bf16 v[78:81], v[140:143], v[216:219], v[78:81]
	v_mfma_f32_16x16x32_bf16 v[126:129], v[144:147], v[180:183], v[126:129]
	v_mfma_f32_16x16x32_bf16 v[118:121], v[156:159], v[180:183], v[118:121]
	v_mfma_f32_16x16x32_bf16 v[102:105], v[156:159], v[188:191], v[102:105]
	v_mfma_f32_16x16x32_bf16 v[110:113], v[144:147], v[188:191], v[110:113]
	v_mfma_f32_16x16x32_bf16 v[94:97], v[144:147], v[212:215], v[94:97]
	v_mfma_f32_16x16x32_bf16 v[86:89], v[156:159], v[212:215], v[86:89]
	v_mfma_f32_16x16x32_bf16 v[70:73], v[156:159], v[220:223], v[70:73]
	v_mfma_f32_16x16x32_bf16 v[78:81], v[144:147], v[220:223], v[78:81]
	s_setprio 0
	s_setprio 1
	v_mfma_f32_16x16x32_bf16 v[122:125], v[160:163], v[176:179], v[122:125]
	v_mfma_f32_16x16x32_bf16 v[114:117], v[168:171], v[176:179], v[114:117]
	v_mfma_f32_16x16x32_bf16 v[98:101], v[168:171], v[184:187], v[98:101]
	v_mfma_f32_16x16x32_bf16 v[106:109], v[160:163], v[184:187], v[106:109]
	v_mfma_f32_16x16x32_bf16 v[90:93], v[160:163], v[198:201], v[90:93]
	v_mfma_f32_16x16x32_bf16 v[82:85], v[168:171], v[198:201], v[82:85]
	v_mfma_f32_16x16x32_bf16 v[66:69], v[168:171], v[216:219], v[66:69]
	v_mfma_f32_16x16x32_bf16 v[74:77], v[160:163], v[216:219], v[74:77]
	v_mfma_f32_16x16x32_bf16 v[122:125], v[164:167], v[180:183], v[122:125]
	v_mfma_f32_16x16x32_bf16 v[114:117], v[172:175], v[180:183], v[114:117]
	v_mfma_f32_16x16x32_bf16 v[98:101], v[172:175], v[188:191], v[98:101]
	v_mfma_f32_16x16x32_bf16 v[106:109], v[164:167], v[188:191], v[106:109]
	v_mfma_f32_16x16x32_bf16 v[90:93], v[164:167], v[212:215], v[90:93]
	v_mfma_f32_16x16x32_bf16 v[82:85], v[172:175], v[212:215], v[82:85]
	v_mfma_f32_16x16x32_bf16 v[66:69], v[172:175], v[220:223], v[66:69]
	v_mfma_f32_16x16x32_bf16 v[74:77], v[164:167], v[220:223], v[74:77]
	s_setprio 0
	s_barrier
	s_add_i32 s67, s67, s22
	v_lshl_add_u64 v[192:193], s[26:27], 0, v[0:1]
	s_mov_b32 m0, s67
	ds_read_b128 v[176:179], v151 offset:16384
	ds_read_b128 v[180:183], v151 offset:17408
	ds_read_b128 v[184:187], v151 offset:18432
	ds_read_b128 v[188:191], v151 offset:19456
	ds_read_b128 v[198:201], v151 offset:20480
	ds_read_b128 v[212:215], v151 offset:21504
	ds_read_b128 v[216:219], v151 offset:22528
	ds_read_b128 v[220:223], v151 offset:23552
	global_load_lds_dwordx4 v[192:193], off
	s_add_i32 m0, s67, 0x2000
	s_add_u32 s92, s26, 0x80000
	v_lshl_add_u64 v[202:203], s[26:27], 0, v[134:135]
	s_addc_u32 s93, s27, 0
	s_add_i32 s67, s94, s22
	global_load_lds_dwordx4 v[202:203], off
	v_lshl_add_u64 v[224:225], s[92:93], 0, v[0:1]
	s_mov_b32 m0, s67
	v_lshl_add_u64 v[226:227], s[28:29], 0, v[132:133]
	global_load_lds_dwordx4 v[224:225], off
	v_lshl_add_u64 v[224:225], s[92:93], 0, v[134:135]
	s_add_i32 m0, s67, 0x2000
	s_nop 0
	global_load_lds_dwordx4 v[224:225], off
	v_lshl_add_u64 v[224:225], s[28:29], 0, v[130:131]
	s_mov_b32 m0, s9
	s_nop 0
	global_load_lds_dwordx4 v[224:225], off
	s_mov_b32 m0, s23
	s_nop 0
	global_load_lds_dwordx4 v[226:227], off
	s_waitcnt vmcnt(8)
	s_waitcnt lgkmcnt(0)
	s_barrier
; #define PG8_STAGE(bufoff, gbase, voff) do { _Pragma("unroll") for (int _i = 0; _i < 2; ++_i) \
;         __builtin_amdgcn_global_load_lds((const unsigned*)((const char*)(gbase) + (voff)[_i]), (PG8_LAS unsigned*)(lds + (bufoff) + ldsw + _i * 8192), 16, 0, 0); } while (0)
; #define PG8_LDA(dst, b, h) do { _Pragma("unroll") for (int m = 0; m < 4; ++m) _Pragma("unroll") for (int k = 0; k < 2; ++k) dst[m][k] = *(const PG8_LAS bf16x8*)(lds + PG8_SA(b, h) + aoff + m * 2048 + k * 1024); } while (0)
; #define PG8_LDB(dst, b, h) do { _Pragma("unroll") for (int n = 0; n < 2; ++n) _Pragma("unroll") for (int k = 0; k < 2; ++k) dst[n][k] = *(const PG8_LAS bf16x8*)(lds + PG8_SB(b, h) + boff + n * 2048 + k * 1024); } while (0)
; #define PG8_MMA(ai, bj, At, Bt) do { __builtin_amdgcn_s_setprio(1); _Pragma("unroll") for (int m = 0; m < 4; ++m) _Pragma("unroll") for (int n = 0; n < 2; ++n) _Pragma("unroll") for (int k = 0; k < 2; ++k) \
;         acc[ai][bj][m][n] = __builtin_amdgcn_mfma_f32_16x16x32_bf16(Bt[n][k], At[m][k], acc[ai][bj][m][n], 0, 0, 0); __builtin_amdgcn_s_setprio(0); } while (0)
; #define PG8_WAIT_V(n) asm volatile("s_waitcnt vmcnt(" #n ")" ::: "memory")
; #define PG8_WAIT_L(n) asm volatile("s_waitcnt lgkmcnt(" #n ")" ::: "memory")
; #define PG8_BAR __builtin_amdgcn_s_barrier()
; #define PG8_SCHED __builtin_amdgcn_sched_barrier(0)
; template <class Epi, class Sched, bool ALIGN_EPI = false, bool SP2 = false>
; __device__ __forceinline__ void gemm_phase(PG8_LAS unsigned char* lds, const Gemm g, const Sched& S, const Epi& E, const int tid) {
;     ...
;             PG8_WAIT_V(8); PG8_WAIT_L(0); PG8_BAR; PG8_MMA(1, 0, At, B0); PG8_MMA(1, 1, At, B1); PG8_BAR; PG8_SCHED;
;             PG8_LDB(B0, 1, 0); PG8_LDB(B1, 1, 1); PG8_SCHED; PG8_LDA(At, 1, 0); PG8_STAGE(PG8_SA(0, 1), a2 + hstepA, voffA);
;             PG8_WAIT_V(8); PG8_WAIT_L(0); PG8_BAR; PG8_MMA(0, 0, At, B0); PG8_MMA(0, 1, At, B1); PG8_BAR; PG8_SCHED;
	s_setprio 1
	s_waitcnt lgkmcnt(0)
	v_mfma_f32_16x16x32_bf16 v[62:65], v[140:143], v[176:179], v[62:65]
	v_mfma_f32_16x16x32_bf16 v[54:57], v[152:155], v[176:179], v[54:57]
	v_mfma_f32_16x16x32_bf16 v[38:41], v[152:155], v[184:187], v[38:41]
	v_mfma_f32_16x16x32_bf16 v[46:49], v[140:143], v[184:187], v[46:49]
	v_mfma_f32_16x16x32_bf16 v[30:33], v[140:143], v[198:201], v[30:33]
	v_mfma_f32_16x16x32_bf16 v[22:25], v[152:155], v[198:201], v[22:25]
	v_mfma_f32_16x16x32_bf16 v[6:9], v[152:155], v[216:219], v[6:9]
	v_mfma_f32_16x16x32_bf16 v[14:17], v[140:143], v[216:219], v[14:17]
	v_mfma_f32_16x16x32_bf16 v[62:65], v[144:147], v[180:183], v[62:65]
	v_mfma_f32_16x16x32_bf16 v[54:57], v[156:159], v[180:183], v[54:57]
	v_mfma_f32_16x16x32_bf16 v[38:41], v[156:159], v[188:191], v[38:41]
	v_mfma_f32_16x16x32_bf16 v[46:49], v[144:147], v[188:191], v[46:49]
	v_mfma_f32_16x16x32_bf16 v[30:33], v[144:147], v[212:215], v[30:33]
	v_mfma_f32_16x16x32_bf16 v[22:25], v[156:159], v[212:215], v[22:25]
	v_mfma_f32_16x16x32_bf16 v[6:9], v[156:159], v[220:223], v[6:9]
	v_mfma_f32_16x16x32_bf16 v[14:17], v[144:147], v[220:223], v[14:17]
	s_setprio 0
	s_setprio 1
	v_mfma_f32_16x16x32_bf16 v[58:61], v[160:163], v[176:179], v[58:61]
	v_mfma_f32_16x16x32_bf16 v[50:53], v[168:171], v[176:179], v[50:53]
	v_mfma_f32_16x16x32_bf16 v[34:37], v[168:171], v[184:187], v[34:37]
	v_mfma_f32_16x16x32_bf16 v[42:45], v[160:163], v[184:187], v[42:45]
	v_mfma_f32_16x16x32_bf16 v[26:29], v[160:163], v[198:201], v[26:29]
	v_mfma_f32_16x16x32_bf16 v[18:21], v[168:171], v[198:201], v[18:21]
	v_mfma_f32_16x16x32_bf16 v[2:5], v[168:171], v[216:219], v[2:5]
	v_mfma_f32_16x16x32_bf16 v[10:13], v[160:163], v[216:219], v[10:13]
	v_mfma_f32_16x16x32_bf16 v[58:61], v[164:167], v[180:183], v[58:61]
	v_mfma_f32_16x16x32_bf16 v[50:53], v[172:175], v[180:183], v[50:53]
	v_mfma_f32_16x16x32_bf16 v[34:37], v[172:175], v[188:191], v[34:37]
	v_mfma_f32_16x16x32_bf16 v[42:45], v[164:167], v[188:191], v[42:45]
	v_mfma_f32_16x16x32_bf16 v[26:29], v[164:167], v[212:215], v[26:29]
	v_mfma_f32_16x16x32_bf16 v[18:21], v[172:175], v[212:215], v[18:21]
	v_mfma_f32_16x16x32_bf16 v[2:5], v[172:175], v[220:223], v[2:5]
	v_mfma_f32_16x16x32_bf16 v[10:13], v[164:167], v[220:223], v[10:13]
	s_setprio 0
	s_barrier
	s_add_i32 s67, 0, 0x18000
	s_add_i32 s92, 0, 0x1c000
	v_add_u32_e32 v156, s67, v149
	v_add_u32_e32 v172, s92, v149
	ds_read_b128 v[140:143], v156
	ds_read_b128 v[144:147], v156 offset:1024
	ds_read_b128 v[152:155], v156 offset:2048
	ds_read_b128 v[156:159], v156 offset:3072
	ds_read_b128 v[160:163], v172
	ds_read_b128 v[164:167], v172 offset:1024
	ds_read_b128 v[168:171], v172 offset:2048
	ds_read_b128 v[172:175], v172 offset:3072
	s_add_u32 s28, s28, 0x80000
	s_addc_u32 s29, s29, 0
	s_mov_b32 m0, s30
	v_lshl_add_u64 v[228:229], s[28:29], 0, v[130:131]
	ds_read_b128 v[176:179], v151 offset:32768
	ds_read_b128 v[180:183], v151 offset:33792
	ds_read_b128 v[184:187], v151 offset:34816
	ds_read_b128 v[188:191], v151 offset:35840
	ds_read_b128 v[198:201], v151 offset:36864
	ds_read_b128 v[212:215], v151 offset:37888
	ds_read_b128 v[216:219], v151 offset:38912
	ds_read_b128 v[220:223], v151 offset:39936
	global_load_lds_dwordx4 v[228:229], off
	v_lshl_add_u64 v[228:229], s[28:29], 0, v[132:133]
	s_mov_b32 m0, s31
	s_nop 0
	global_load_lds_dwordx4 v[228:229], off
	s_waitcnt vmcnt(8)
	s_waitcnt lgkmcnt(0)
	s_barrier
	s_setprio 1
	s_waitcnt lgkmcnt(0)
	v_mfma_f32_16x16x32_bf16 v[126:129], v[140:143], v[176:179], v[126:129]
	v_mfma_f32_16x16x32_bf16 v[118:121], v[152:155], v[176:179], v[118:121]
	v_mfma_f32_16x16x32_bf16 v[102:105], v[152:155], v[184:187], v[102:105]
	v_mfma_f32_16x16x32_bf16 v[110:113], v[140:143], v[184:187], v[110:113]
	v_mfma_f32_16x16x32_bf16 v[94:97], v[140:143], v[198:201], v[94:97]
	v_mfma_f32_16x16x32_bf16 v[86:89], v[152:155], v[198:201], v[86:89]
	v_mfma_f32_16x16x32_bf16 v[70:73], v[152:155], v[216:219], v[70:73]
	v_mfma_f32_16x16x32_bf16 v[78:81], v[140:143], v[216:219], v[78:81]
	v_mfma_f32_16x16x32_bf16 v[126:129], v[144:147], v[180:183], v[126:129]
	v_mfma_f32_16x16x32_bf16 v[118:121], v[156:159], v[180:183], v[118:121]
	v_mfma_f32_16x16x32_bf16 v[102:105], v[156:159], v[188:191], v[102:105]
	v_mfma_f32_16x16x32_bf16 v[110:113], v[144:147], v[188:191], v[110:113]
	v_mfma_f32_16x16x32_bf16 v[94:97], v[144:147], v[212:215], v[94:97]
	v_mfma_f32_16x16x32_bf16 v[86:89], v[156:159], v[212:215], v[86:89]
	v_mfma_f32_16x16x32_bf16 v[70:73], v[156:159], v[220:223], v[70:73]
	v_mfma_f32_16x16x32_bf16 v[78:81], v[144:147], v[220:223], v[78:81]
	s_setprio 0
	s_setprio 1
	v_mfma_f32_16x16x32_bf16 v[122:125], v[160:163], v[176:179], v[122:125]
	v_mfma_f32_16x16x32_bf16 v[114:117], v[168:171], v[176:179], v[114:117]
	v_mfma_f32_16x16x32_bf16 v[98:101], v[168:171], v[184:187], v[98:101]
	v_mfma_f32_16x16x32_bf16 v[106:109], v[160:163], v[184:187], v[106:109]
	v_mfma_f32_16x16x32_bf16 v[90:93], v[160:163], v[198:201], v[90:93]
	v_mfma_f32_16x16x32_bf16 v[82:85], v[168:171], v[198:201], v[82:85]
	v_mfma_f32_16x16x32_bf16 v[66:69], v[168:171], v[216:219], v[66:69]
	v_mfma_f32_16x16x32_bf16 v[74:77], v[160:163], v[216:219], v[74:77]
	v_mfma_f32_16x16x32_bf16 v[122:125], v[164:167], v[180:183], v[122:125]
	v_mfma_f32_16x16x32_bf16 v[114:117], v[172:175], v[180:183], v[114:117]
	v_mfma_f32_16x16x32_bf16 v[98:101], v[172:175], v[188:191], v[98:101]
	v_mfma_f32_16x16x32_bf16 v[106:109], v[164:167], v[188:191], v[106:109]
	v_mfma_f32_16x16x32_bf16 v[90:93], v[164:167], v[212:215], v[90:93]
	v_mfma_f32_16x16x32_bf16 v[82:85], v[172:175], v[212:215], v[82:85]
	v_mfma_f32_16x16x32_bf16 v[66:69], v[172:175], v[220:223], v[66:69]
	v_mfma_f32_16x16x32_bf16 v[74:77], v[164:167], v[220:223], v[74:77]
	s_setprio 0
	s_barrier
; #define PG8_STAGE(bufoff, gbase, voff) do { _Pragma("unroll") for (int _i = 0; _i < 2; ++_i) \
;         __builtin_amdgcn_global_load_lds((const unsigned*)((const char*)(gbase) + (voff)[_i]), (PG8_LAS unsigned*)(lds + (bufoff) + ldsw + _i * 8192), 16, 0, 0); } while (0)
; #define PG8_LDA(dst, b, h) do { _Pragma("unroll") for (int m = 0; m < 4; ++m) _Pragma("unroll") for (int k = 0; k < 2; ++k) dst[m][k] = *(const PG8_LAS bf16x8*)(lds + PG8_SA(b, h) + aoff + m * 2048 + k * 1024); } while (0)
; #define PG8_MMA(ai, bj, At, Bt) do { __builtin_amdgcn_s_setprio(1); _Pragma("unroll") for (int m = 0; m < 4; ++m) _Pragma("unroll") for (int n = 0; n < 2; ++n) _Pragma("unroll") for (int k = 0; k < 2; ++k) \
;         acc[ai][bj][m][n] = __builtin_amdgcn_mfma_f32_16x16x32_bf16(Bt[n][k], At[m][k], acc[ai][bj][m][n], 0, 0, 0); __builtin_amdgcn_s_setprio(0); } while (0)
; #define PG8_WAIT_V(n) asm volatile("s_waitcnt vmcnt(" #n ")" ::: "memory")
; #define PG8_WAIT_L(n) asm volatile("s_waitcnt lgkmcnt(" #n ")" ::: "memory")
; #define PG8_BAR __builtin_amdgcn_s_barrier()
; #define PG8_SCHED __builtin_amdgcn_sched_barrier(0)
; template <class Epi, class Sched, bool ALIGN_EPI = false, bool SP2 = false>
; __device__ __forceinline__ void gemm_phase(PG8_LAS unsigned char* lds, const Gemm g, const Sched& S, const Epi& E, const int tid) {
;     ...
;             PG8_LDA(At, 1, 1); PG8_STAGE(PG8_SB(1, 0), b3, voffB); PG8_STAGE(PG8_SB(1, 1), b3 + hstepB, voffB); PG8_STAGE(PG8_SA(1, 0), a3, voffA);
;             PG8_WAIT_V(8); PG8_WAIT_L(0); PG8_BAR; PG8_MMA(1, 0, At, B0); PG8_MMA(1, 1, At, B1); PG8_BAR; PG8_SCHED;
;     ...
;         if constexpr (ALIGN_EPI) { if (wr == 0) PG8_BAR; }
	s_add_i32 s28, s67, s22
	v_lshl_add_u64 v[192:193], v[192:193], 0, s[70:71]
	s_mov_b32 m0, s28
	ds_read_b128 v[176:179], v151 offset:49152
	ds_read_b128 v[180:183], v151 offset:50176
	ds_read_b128 v[184:187], v151 offset:51200
	ds_read_b128 v[188:191], v151 offset:52224
	ds_read_b128 v[198:201], v151 offset:53248
	ds_read_b128 v[212:215], v151 offset:54272
	ds_read_b128 v[216:219], v151 offset:55296
	ds_read_b128 v[220:223], v151 offset:56320
	global_load_lds_dwordx4 v[192:193], off
	s_add_i32 m0, s28, 0x2000
	s_add_u32 s26, s26, 0x80080
	v_lshl_add_u64 v[192:193], v[202:203], 0, s[70:71]
	s_addc_u32 s27, s27, 0
	s_add_i32 s28, s92, s22
	global_load_lds_dwordx4 v[192:193], off
	v_lshl_add_u64 v[192:193], s[26:27], 0, v[0:1]
	s_mov_b32 m0, s28
	s_nop 0
	global_load_lds_dwordx4 v[192:193], off
	v_lshl_add_u64 v[192:193], s[26:27], 0, v[134:135]
	s_add_i32 m0, s28, 0x2000
	s_nop 0
	global_load_lds_dwordx4 v[192:193], off
	v_lshl_add_u64 v[192:193], v[224:225], 0, s[70:71]
	s_mov_b32 m0, s34
	s_nop 0
	global_load_lds_dwordx4 v[192:193], off
	v_lshl_add_u64 v[192:193], v[226:227], 0, s[70:71]
	s_mov_b32 m0, s35
	s_nop 0
	global_load_lds_dwordx4 v[192:193], off
	s_waitcnt vmcnt(8)
	s_waitcnt lgkmcnt(0)
	s_barrier
	s_setprio 1
	s_waitcnt lgkmcnt(0)
	v_mfma_f32_16x16x32_bf16 v[62:65], v[140:143], v[176:179], v[62:65]
	v_mfma_f32_16x16x32_bf16 v[54:57], v[152:155], v[176:179], v[54:57]
	v_mfma_f32_16x16x32_bf16 v[38:41], v[152:155], v[184:187], v[38:41]
	v_mfma_f32_16x16x32_bf16 v[46:49], v[140:143], v[184:187], v[46:49]
	v_mfma_f32_16x16x32_bf16 v[30:33], v[140:143], v[198:201], v[30:33]
	v_mfma_f32_16x16x32_bf16 v[22:25], v[152:155], v[198:201], v[22:25]
	v_mfma_f32_16x16x32_bf16 v[6:9], v[152:155], v[216:219], v[6:9]
	v_mfma_f32_16x16x32_bf16 v[14:17], v[140:143], v[216:219], v[14:17]
	v_mfma_f32_16x16x32_bf16 v[62:65], v[144:147], v[180:183], v[62:65]
	v_mfma_f32_16x16x32_bf16 v[54:57], v[156:159], v[180:183], v[54:57]
	v_mfma_f32_16x16x32_bf16 v[38:41], v[156:159], v[188:191], v[38:41]
	v_mfma_f32_16x16x32_bf16 v[46:49], v[144:147], v[188:191], v[46:49]
	v_mfma_f32_16x16x32_bf16 v[30:33], v[144:147], v[212:215], v[30:33]
	v_mfma_f32_16x16x32_bf16 v[22:25], v[156:159], v[212:215], v[22:25]
	v_mfma_f32_16x16x32_bf16 v[6:9], v[156:159], v[220:223], v[6:9]
	v_mfma_f32_16x16x32_bf16 v[14:17], v[144:147], v[220:223], v[14:17]
	s_setprio 0
	s_setprio 1
	v_mfma_f32_16x16x32_bf16 v[58:61], v[160:163], v[176:179], v[58:61]
	v_mfma_f32_16x16x32_bf16 v[50:53], v[168:171], v[176:179], v[50:53]
	v_mfma_f32_16x16x32_bf16 v[34:37], v[168:171], v[184:187], v[34:37]
	v_mfma_f32_16x16x32_bf16 v[42:45], v[160:163], v[184:187], v[42:45]
	v_mfma_f32_16x16x32_bf16 v[26:29], v[160:163], v[198:201], v[26:29]
	v_mfma_f32_16x16x32_bf16 v[18:21], v[168:171], v[198:201], v[18:21]
	v_mfma_f32_16x16x32_bf16 v[2:5], v[168:171], v[216:219], v[2:5]
	v_mfma_f32_16x16x32_bf16 v[10:13], v[160:163], v[216:219], v[10:13]
	v_mfma_f32_16x16x32_bf16 v[58:61], v[164:167], v[180:183], v[58:61]
	v_mfma_f32_16x16x32_bf16 v[50:53], v[172:175], v[180:183], v[50:53]
	v_mfma_f32_16x16x32_bf16 v[34:37], v[172:175], v[188:191], v[34:37]
	v_mfma_f32_16x16x32_bf16 v[42:45], v[164:167], v[188:191], v[42:45]
	v_mfma_f32_16x16x32_bf16 v[26:29], v[164:167], v[212:215], v[26:29]
	v_mfma_f32_16x16x32_bf16 v[18:21], v[172:175], v[212:215], v[18:21]
	v_mfma_f32_16x16x32_bf16 v[2:5], v[172:175], v[220:223], v[2:5]
	v_mfma_f32_16x16x32_bf16 v[10:13], v[164:167], v[220:223], v[10:13]
	s_setprio 0
	s_barrier
	s_add_i32 s60, s60, 2
	s_add_u32 s65, s65, 0x100
	s_addc_u32 s66, s66, 0
	s_add_u32 s2, s2, 0x100
	s_addc_u32 s3, s3, 0
	s_cmp_gt_u32 s60, 29
	s_cbranch_scc0 .LBB0_387
	s_and_b64 vcc, exec, s[10:11]
	s_mov_b64 s[96:97], 0x4000
	s_mov_b64 s[90:91], 0x8000
	s_cbranch_vccz .LBB0_390
	s_barrier

; #define PG8_STAGE(bufoff, gbase, voff) do { _Pragma("unroll") for (int _i = 0; _i < 2; ++_i) \
;         __builtin_amdgcn_global_load_lds((const unsigned*)((const char*)(gbase) + (voff)[_i]), (PG8_LAS unsigned*)(lds + (bufoff) + ldsw + _i * 8192), 16, 0, 0); } while (0)
; #define PG8_LDA(dst, b, h) do { _Pragma("unroll") for (int m = 0; m < 4; ++m) _Pragma("unroll") for (int k = 0; k < 2; ++k) dst[m][k] = *(const PG8_LAS bf16x8*)(lds + PG8_SA(b, h) + aoff + m * 2048 + k * 1024); } while (0)
; #define PG8_LDB(dst, b, h) do { _Pragma("unroll") for (int n = 0; n < 2; ++n) _Pragma("unroll") for (int k = 0; k < 2; ++k) dst[n][k] = *(const PG8_LAS bf16x8*)(lds + PG8_SB(b, h) + boff + n * 2048 + k * 1024); } while (0)
; #define PG8_MMA(ai, bj, At, Bt) do { __builtin_amdgcn_s_setprio(1); _Pragma("unroll") for (int m = 0; m < 4; ++m) _Pragma("unroll") for (int n = 0; n < 2; ++n) _Pragma("unroll") for (int k = 0; k < 2; ++k) \
;         acc[ai][bj][m][n] = __builtin_amdgcn_mfma_f32_16x16x32_bf16(Bt[n][k], At[m][k], acc[ai][bj][m][n], 0, 0, 0); __builtin_amdgcn_s_setprio(0); } while (0)
; #define PG8_WAIT_V(n) asm volatile("s_waitcnt vmcnt(" #n ")" ::: "memory")
; #define PG8_BAR __builtin_amdgcn_s_barrier()
; template <class Epi, class Sched, bool ALIGN_EPI = false, bool SP2 = false>
; __device__ __forceinline__ void gemm_phase(PG8_LAS unsigned char* lds, const Gemm g, const Sched& S, const Epi& E, const int tid) {
;     ...
;         for (int t = 0; t < nt; t += 2) {
;             const bool last = (t == nt - 2);
;             const char* a1 = cA + (size_t)(t + 1) * kstep;
;             const char* a2 = last ? nA : cA + (size_t)(t + 2) * kstep; const char* b2 = last ? nB : cB + (size_t)(t + 2) * kstep;
;             const char* a3 = a2 + kstep; const char* b3 = b2 + kstep;
;             if (last && has_next) S.a_ready(nxt);
;             if constexpr (SP2) {
;             PG8_LDB(B0, 0, 0); PG8_LDB(B1, 0, 1); PG8_SCHED; PG8_LDA(At, 0, 0); PG8_STAGE(PG8_SA(1, 1), a1 + hstepA, voffA);
;             PG8_WAIT_V(8); PG8_WAIT_L(0); PG8_BAR; PG8_MMA(0, 0, At, B0); PG8_MMA(0, 1, At, B1); PG8_BAR; PG8_SCHED;
;             PG8_LDA(At, 0, 1); PG8_STAGE(PG8_SB(0, 0), b2, voffB); PG8_STAGE(PG8_SB(0, 1), b2 + hstepB, voffB); PG8_STAGE(PG8_SA(0, 0), a2, voffA);
;             PG8_WAIT_V(8); PG8_WAIT_L(0); PG8_BAR; PG8_MMA(1, 0, At, B0); PG8_MMA(1, 1, At, B1); PG8_BAR; PG8_SCHED;
.LBB0_411:
	s_add_u32 s8, s2, 0xfff80080
	s_addc_u32 s9, s3, -1
	s_add_i32 s10, 0, 0x10000
	s_cmp_eq_u32 s60, 28
	s_cselect_b32 s21, s7, s9
	s_cselect_b32 s20, s13, s8
	s_cselect_b32 s9, s22, vcc_lo
	s_cselect_b32 s8, s23, s35
	s_add_i32 vcc_hi, 0, 0x14000
	v_add_u32_e32 v158, s10, v151
	v_add_u32_e32 v174, vcc_hi, v151
	ds_read_b128 v[142:145], v158
	ds_read_b128 v[146:149], v158 offset:1024
	ds_read_b128 v[154:157], v158 offset:2048
	ds_read_b128 v[158:161], v158 offset:3072
	ds_read_b128 v[162:165], v174
	ds_read_b128 v[166:169], v174 offset:1024
	ds_read_b128 v[170:173], v174 offset:2048
	ds_read_b128 v[174:177], v174 offset:3072
	v_lshl_add_u64 v[202:203], s[2:3], 0, v[140:141]
	s_add_i32 m0, s31, 0xc000
	ds_read_b128 v[178:181], v153
	ds_read_b128 v[182:185], v153 offset:1024
	ds_read_b128 v[186:189], v153 offset:2048
	ds_read_b128 v[190:193], v153 offset:3072
	ds_read_b128 v[198:201], v153 offset:4096
	ds_read_b128 v[212:215], v153 offset:5120
	ds_read_b128 v[216:219], v153 offset:6144
	ds_read_b128 v[220:223], v153 offset:7168
	global_load_lds_dwordx4 v[202:203], off
	v_lshl_add_u64 v[202:203], s[2:3], 0, v[138:139]
	s_add_i32 m0, s31, 0xe000
	s_nop 0
	global_load_lds_dwordx4 v[202:203], off
	s_waitcnt vmcnt(8)
	s_waitcnt lgkmcnt(0)
	s_barrier
	s_setprio 1
	s_waitcnt lgkmcnt(0)
	v_mfma_f32_16x16x32_bf16 v[126:129], v[142:145], v[178:181], v[126:129]
	v_mfma_f32_16x16x32_bf16 v[122:125], v[154:157], v[178:181], v[122:125]
	v_mfma_f32_16x16x32_bf16 v[106:109], v[154:157], v[186:189], v[106:109]
	v_mfma_f32_16x16x32_bf16 v[110:113], v[142:145], v[186:189], v[110:113]
	v_mfma_f32_16x16x32_bf16 v[94:97], v[142:145], v[198:201], v[94:97]
	v_mfma_f32_16x16x32_bf16 v[90:93], v[154:157], v[198:201], v[90:93]
	v_mfma_f32_16x16x32_bf16 v[74:77], v[154:157], v[216:219], v[74:77]
	v_mfma_f32_16x16x32_bf16 v[78:81], v[142:145], v[216:219], v[78:81]
	v_mfma_f32_16x16x32_bf16 v[126:129], v[146:149], v[182:185], v[126:129]
	v_mfma_f32_16x16x32_bf16 v[122:125], v[158:161], v[182:185], v[122:125]
	v_mfma_f32_16x16x32_bf16 v[106:109], v[158:161], v[190:193], v[106:109]
	v_mfma_f32_16x16x32_bf16 v[110:113], v[146:149], v[190:193], v[110:113]
	v_mfma_f32_16x16x32_bf16 v[94:97], v[146:149], v[212:215], v[94:97]
	v_mfma_f32_16x16x32_bf16 v[90:93], v[158:161], v[212:215], v[90:93]
	v_mfma_f32_16x16x32_bf16 v[74:77], v[158:161], v[220:223], v[74:77]
	v_mfma_f32_16x16x32_bf16 v[78:81], v[146:149], v[220:223], v[78:81]
	s_setprio 0
	s_setprio 1
	v_mfma_f32_16x16x32_bf16 v[118:121], v[162:165], v[178:181], v[118:121]
	v_mfma_f32_16x16x32_bf16 v[114:117], v[170:173], v[178:181], v[114:117]
	v_mfma_f32_16x16x32_bf16 v[98:101], v[170:173], v[186:189], v[98:101]
	v_mfma_f32_16x16x32_bf16 v[102:105], v[162:165], v[186:189], v[102:105]
	v_mfma_f32_16x16x32_bf16 v[86:89], v[162:165], v[198:201], v[86:89]
	v_mfma_f32_16x16x32_bf16 v[82:85], v[170:173], v[198:201], v[82:85]
	v_mfma_f32_16x16x32_bf16 v[66:69], v[170:173], v[216:219], v[66:69]
	v_mfma_f32_16x16x32_bf16 v[70:73], v[162:165], v[216:219], v[70:73]
	v_mfma_f32_16x16x32_bf16 v[118:121], v[166:169], v[182:185], v[118:121]
	v_mfma_f32_16x16x32_bf16 v[114:117], v[174:177], v[182:185], v[114:117]
	v_mfma_f32_16x16x32_bf16 v[98:101], v[174:177], v[190:193], v[98:101]
	v_mfma_f32_16x16x32_bf16 v[102:105], v[166:169], v[190:193], v[102:105]
	v_mfma_f32_16x16x32_bf16 v[86:89], v[166:169], v[212:215], v[86:89]
	v_mfma_f32_16x16x32_bf16 v[82:85], v[174:177], v[212:215], v[82:85]
	v_mfma_f32_16x16x32_bf16 v[66:69], v[174:177], v[220:223], v[66:69]
	v_mfma_f32_16x16x32_bf16 v[70:73], v[166:169], v[220:223], v[70:73]
	s_setprio 0
	s_barrier
	s_add_i32 s10, s10, s65
	v_lshl_add_u64 v[202:203], s[8:9], 0, v[132:133]
	s_mov_b32 m0, s10
	ds_read_b128 v[178:181], v153 offset:16384
	ds_read_b128 v[182:185], v153 offset:17408
	ds_read_b128 v[186:189], v153 offset:18432
	ds_read_b128 v[190:193], v153 offset:19456
	ds_read_b128 v[198:201], v153 offset:20480
	ds_read_b128 v[212:215], v153 offset:21504
	ds_read_b128 v[216:219], v153 offset:22528
	ds_read_b128 v[220:223], v153 offset:23552
	global_load_lds_dwordx4 v[202:203], off
	s_add_i32 m0, s10, 0x2000
	s_add_u32 s10, s8, 0x80000
	v_lshl_add_u64 v[224:225], s[8:9], 0, v[136:137]
	s_addc_u32 s11, s9, 0
	s_add_i32 vcc_hi, vcc_hi, s65
	global_load_lds_dwordx4 v[224:225], off
	v_lshl_add_u64 v[226:227], s[10:11], 0, v[132:133]
	s_mov_b32 m0, vcc_hi
	v_lshl_add_u64 v[228:229], s[20:21], 0, v[134:135]
	global_load_lds_dwordx4 v[226:227], off
	v_lshl_add_u64 v[226:227], s[10:11], 0, v[136:137]
	s_add_i32 m0, vcc_hi, 0x2000
	s_nop 0
	global_load_lds_dwordx4 v[226:227], off
	v_lshl_add_u64 v[226:227], s[20:21], 0, v[130:131]
	s_mov_b32 m0, s31
	s_nop 0
	global_load_lds_dwordx4 v[226:227], off
	s_mov_b32 m0, s66
	s_nop 0
	global_load_lds_dwordx4 v[228:229], off
	s_waitcnt vmcnt(8)
	s_waitcnt lgkmcnt(0)
	s_barrier
; #define PG8_STAGE(bufoff, gbase, voff) do { _Pragma("unroll") for (int _i = 0; _i < 2; ++_i) \
;         __builtin_amdgcn_global_load_lds((const unsigned*)((const char*)(gbase) + (voff)[_i]), (PG8_LAS unsigned*)(lds + (bufoff) + ldsw + _i * 8192), 16, 0, 0); } while (0)
; #define PG8_LDA(dst, b, h) do { _Pragma("unroll") for (int m = 0; m < 4; ++m) _Pragma("unroll") for (int k = 0; k < 2; ++k) dst[m][k] = *(const PG8_LAS bf16x8*)(lds + PG8_SA(b, h) + aoff + m * 2048 + k * 1024); } while (0)
; #define PG8_LDB(dst, b, h) do { _Pragma("unroll") for (int n = 0; n < 2; ++n) _Pragma("unroll") for (int k = 0; k < 2; ++k) dst[n][k] = *(const PG8_LAS bf16x8*)(lds + PG8_SB(b, h) + boff + n * 2048 + k * 1024); } while (0)
; #define PG8_MMA(ai, bj, At, Bt) do { __builtin_amdgcn_s_setprio(1); _Pragma("unroll") for (int m = 0; m < 4; ++m) _Pragma("unroll") for (int n = 0; n < 2; ++n) _Pragma("unroll") for (int k = 0; k < 2; ++k) \
;         acc[ai][bj][m][n] = __builtin_amdgcn_mfma_f32_16x16x32_bf16(Bt[n][k], At[m][k], acc[ai][bj][m][n], 0, 0, 0); __builtin_amdgcn_s_setprio(0); } while (0)
; #define PG8_WAIT_V(n) asm volatile("s_waitcnt vmcnt(" #n ")" ::: "memory")
; #define PG8_WAIT_L(n) asm volatile("s_waitcnt lgkmcnt(" #n ")" ::: "memory")
; #define PG8_BAR __builtin_amdgcn_s_barrier()
; #define PG8_SCHED __builtin_amdgcn_sched_barrier(0)
; template <class Epi, class Sched, bool ALIGN_EPI = false, bool SP2 = false>
; __device__ __forceinline__ void gemm_phase(PG8_LAS unsigned char* lds, const Gemm g, const Sched& S, const Epi& E, const int tid) {
;     ...
;             PG8_WAIT_V(8); PG8_WAIT_L(0); PG8_BAR; PG8_MMA(1, 0, At, B0); PG8_MMA(1, 1, At, B1); PG8_BAR; PG8_SCHED;
;             PG8_LDB(B0, 1, 0); PG8_LDB(B1, 1, 1); PG8_SCHED; PG8_LDA(At, 1, 0); PG8_STAGE(PG8_SA(0, 1), a2 + hstepA, voffA);
;             PG8_WAIT_V(8); PG8_WAIT_L(0); PG8_BAR; PG8_MMA(0, 0, At, B0); PG8_MMA(0, 1, At, B1); PG8_BAR; PG8_SCHED;
	s_setprio 1
	s_waitcnt lgkmcnt(0)
	v_mfma_f32_16x16x32_bf16 v[62:65], v[142:145], v[178:181], v[62:65]
	v_mfma_f32_16x16x32_bf16 v[58:61], v[154:157], v[178:181], v[58:61]
	v_mfma_f32_16x16x32_bf16 v[42:45], v[154:157], v[186:189], v[42:45]
	v_mfma_f32_16x16x32_bf16 v[46:49], v[142:145], v[186:189], v[46:49]
	v_mfma_f32_16x16x32_bf16 v[30:33], v[142:145], v[198:201], v[30:33]
	v_mfma_f32_16x16x32_bf16 v[26:29], v[154:157], v[198:201], v[26:29]
	v_mfma_f32_16x16x32_bf16 v[10:13], v[154:157], v[216:219], v[10:13]
	v_mfma_f32_16x16x32_bf16 v[14:17], v[142:145], v[216:219], v[14:17]
	v_mfma_f32_16x16x32_bf16 v[62:65], v[146:149], v[182:185], v[62:65]
	v_mfma_f32_16x16x32_bf16 v[58:61], v[158:161], v[182:185], v[58:61]
	v_mfma_f32_16x16x32_bf16 v[42:45], v[158:161], v[190:193], v[42:45]
	v_mfma_f32_16x16x32_bf16 v[46:49], v[146:149], v[190:193], v[46:49]
	v_mfma_f32_16x16x32_bf16 v[30:33], v[146:149], v[212:215], v[30:33]
	v_mfma_f32_16x16x32_bf16 v[26:29], v[158:161], v[212:215], v[26:29]
	v_mfma_f32_16x16x32_bf16 v[10:13], v[158:161], v[220:223], v[10:13]
	v_mfma_f32_16x16x32_bf16 v[14:17], v[146:149], v[220:223], v[14:17]
	s_setprio 0
	s_setprio 1
	v_mfma_f32_16x16x32_bf16 v[54:57], v[162:165], v[178:181], v[54:57]
	v_mfma_f32_16x16x32_bf16 v[50:53], v[170:173], v[178:181], v[50:53]
	v_mfma_f32_16x16x32_bf16 v[34:37], v[170:173], v[186:189], v[34:37]
	v_mfma_f32_16x16x32_bf16 v[38:41], v[162:165], v[186:189], v[38:41]
	v_mfma_f32_16x16x32_bf16 v[22:25], v[162:165], v[198:201], v[22:25]
	v_mfma_f32_16x16x32_bf16 v[18:21], v[170:173], v[198:201], v[18:21]
	v_mfma_f32_16x16x32_bf16 v[2:5], v[170:173], v[216:219], v[2:5]
	v_mfma_f32_16x16x32_bf16 v[6:9], v[162:165], v[216:219], v[6:9]
	v_mfma_f32_16x16x32_bf16 v[54:57], v[166:169], v[182:185], v[54:57]
	v_mfma_f32_16x16x32_bf16 v[50:53], v[174:177], v[182:185], v[50:53]
	v_mfma_f32_16x16x32_bf16 v[34:37], v[174:177], v[190:193], v[34:37]
	v_mfma_f32_16x16x32_bf16 v[38:41], v[166:169], v[190:193], v[38:41]
	v_mfma_f32_16x16x32_bf16 v[22:25], v[166:169], v[212:215], v[22:25]
	v_mfma_f32_16x16x32_bf16 v[18:21], v[174:177], v[212:215], v[18:21]
	v_mfma_f32_16x16x32_bf16 v[2:5], v[174:177], v[220:223], v[2:5]
	v_mfma_f32_16x16x32_bf16 v[6:9], v[166:169], v[220:223], v[6:9]
	s_setprio 0
	s_barrier
	s_add_i32 vcc_hi, 0, 0x18000
	s_add_i32 s93, 0, 0x1c000
	v_add_u32_e32 v158, vcc_hi, v151
	v_add_u32_e32 v174, s93, v151
	ds_read_b128 v[142:145], v158
	ds_read_b128 v[146:149], v158 offset:1024
	ds_read_b128 v[154:157], v158 offset:2048
	ds_read_b128 v[158:161], v158 offset:3072
	ds_read_b128 v[162:165], v174
	ds_read_b128 v[166:169], v174 offset:1024
	ds_read_b128 v[170:173], v174 offset:2048
	ds_read_b128 v[174:177], v174 offset:3072
	s_add_u32 s10, s20, 0x80000
	s_addc_u32 s11, s21, 0
	s_mov_b32 m0, s67
	v_lshl_add_u64 v[230:231], s[10:11], 0, v[130:131]
	ds_read_b128 v[178:181], v153 offset:32768
	ds_read_b128 v[182:185], v153 offset:33792
	ds_read_b128 v[186:189], v153 offset:34816
	ds_read_b128 v[190:193], v153 offset:35840
	ds_read_b128 v[198:201], v153 offset:36864
	ds_read_b128 v[212:215], v153 offset:37888
	ds_read_b128 v[216:219], v153 offset:38912
	ds_read_b128 v[220:223], v153 offset:39936
	global_load_lds_dwordx4 v[230:231], off
	v_lshl_add_u64 v[230:231], s[10:11], 0, v[134:135]
	s_mov_b32 m0, s92
	s_nop 0
	global_load_lds_dwordx4 v[230:231], off
	s_waitcnt vmcnt(8)
	s_waitcnt lgkmcnt(0)
	s_barrier
	s_setprio 1
	s_waitcnt lgkmcnt(0)
	v_mfma_f32_16x16x32_bf16 v[126:129], v[142:145], v[178:181], v[126:129]
	v_mfma_f32_16x16x32_bf16 v[122:125], v[154:157], v[178:181], v[122:125]
	v_mfma_f32_16x16x32_bf16 v[106:109], v[154:157], v[186:189], v[106:109]
	v_mfma_f32_16x16x32_bf16 v[110:113], v[142:145], v[186:189], v[110:113]
	v_mfma_f32_16x16x32_bf16 v[94:97], v[142:145], v[198:201], v[94:97]
	v_mfma_f32_16x16x32_bf16 v[90:93], v[154:157], v[198:201], v[90:93]
	v_mfma_f32_16x16x32_bf16 v[74:77], v[154:157], v[216:219], v[74:77]
	v_mfma_f32_16x16x32_bf16 v[78:81], v[142:145], v[216:219], v[78:81]
	v_mfma_f32_16x16x32_bf16 v[126:129], v[146:149], v[182:185], v[126:129]
	v_mfma_f32_16x16x32_bf16 v[122:125], v[158:161], v[182:185], v[122:125]
	v_mfma_f32_16x16x32_bf16 v[106:109], v[158:161], v[190:193], v[106:109]
	v_mfma_f32_16x16x32_bf16 v[110:113], v[146:149], v[190:193], v[110:113]
	v_mfma_f32_16x16x32_bf16 v[94:97], v[146:149], v[212:215], v[94:97]
	v_mfma_f32_16x16x32_bf16 v[90:93], v[158:161], v[212:215], v[90:93]
	v_mfma_f32_16x16x32_bf16 v[74:77], v[158:161], v[220:223], v[74:77]
	v_mfma_f32_16x16x32_bf16 v[78:81], v[146:149], v[220:223], v[78:81]
	s_setprio 0
	s_setprio 1
	v_mfma_f32_16x16x32_bf16 v[118:121], v[162:165], v[178:181], v[118:121]
	v_mfma_f32_16x16x32_bf16 v[114:117], v[170:173], v[178:181], v[114:117]
	v_mfma_f32_16x16x32_bf16 v[98:101], v[170:173], v[186:189], v[98:101]
	v_mfma_f32_16x16x32_bf16 v[102:105], v[162:165], v[186:189], v[102:105]
	v_mfma_f32_16x16x32_bf16 v[86:89], v[162:165], v[198:201], v[86:89]
	v_mfma_f32_16x16x32_bf16 v[82:85], v[170:173], v[198:201], v[82:85]
	v_mfma_f32_16x16x32_bf16 v[66:69], v[170:173], v[216:219], v[66:69]
	v_mfma_f32_16x16x32_bf16 v[70:73], v[162:165], v[216:219], v[70:73]
	v_mfma_f32_16x16x32_bf16 v[118:121], v[166:169], v[182:185], v[118:121]
	v_mfma_f32_16x16x32_bf16 v[114:117], v[174:177], v[182:185], v[114:117]
	v_mfma_f32_16x16x32_bf16 v[98:101], v[174:177], v[190:193], v[98:101]
	v_mfma_f32_16x16x32_bf16 v[102:105], v[166:169], v[190:193], v[102:105]
	v_mfma_f32_16x16x32_bf16 v[86:89], v[166:169], v[212:215], v[86:89]
	v_mfma_f32_16x16x32_bf16 v[82:85], v[174:177], v[212:215], v[82:85]
	v_mfma_f32_16x16x32_bf16 v[66:69], v[174:177], v[220:223], v[66:69]
	v_mfma_f32_16x16x32_bf16 v[70:73], v[166:169], v[220:223], v[70:73]
	s_setprio 0
	s_barrier
; #define PG8_STAGE(bufoff, gbase, voff) do { _Pragma("unroll") for (int _i = 0; _i < 2; ++_i) \
;         __builtin_amdgcn_global_load_lds((const unsigned*)((const char*)(gbase) + (voff)[_i]), (PG8_LAS unsigned*)(lds + (bufoff) + ldsw + _i * 8192), 16, 0, 0); } while (0)
; #define PG8_LDA(dst, b, h) do { _Pragma("unroll") for (int m = 0; m < 4; ++m) _Pragma("unroll") for (int k = 0; k < 2; ++k) dst[m][k] = *(const PG8_LAS bf16x8*)(lds + PG8_SA(b, h) + aoff + m * 2048 + k * 1024); } while (0)
; #define PG8_MMA(ai, bj, At, Bt) do { __builtin_amdgcn_s_setprio(1); _Pragma("unroll") for (int m = 0; m < 4; ++m) _Pragma("unroll") for (int n = 0; n < 2; ++n) _Pragma("unroll") for (int k = 0; k < 2; ++k) \
;         acc[ai][bj][m][n] = __builtin_amdgcn_mfma_f32_16x16x32_bf16(Bt[n][k], At[m][k], acc[ai][bj][m][n], 0, 0, 0); __builtin_amdgcn_s_setprio(0); } while (0)
; #define PG8_WAIT_V(n) asm volatile("s_waitcnt vmcnt(" #n ")" ::: "memory")
; #define PG8_WAIT_L(n) asm volatile("s_waitcnt lgkmcnt(" #n ")" ::: "memory")
; #define PG8_BAR __builtin_amdgcn_s_barrier()
; #define PG8_SCHED __builtin_amdgcn_sched_barrier(0)
; template <class Epi, class Sched, bool ALIGN_EPI = false, bool SP2 = false>
; __device__ __forceinline__ void gemm_phase(PG8_LAS unsigned char* lds, const Gemm g, const Sched& S, const Epi& E, const int tid) {
;     ...
;             PG8_LDA(At, 1, 1); PG8_STAGE(PG8_SB(1, 0), b3, voffB); PG8_STAGE(PG8_SB(1, 1), b3 + hstepB, voffB); PG8_STAGE(PG8_SA(1, 0), a3, voffA);
;             PG8_WAIT_V(8); PG8_WAIT_L(0); PG8_BAR; PG8_MMA(1, 0, At, B0); PG8_MMA(1, 1, At, B1); PG8_BAR; PG8_SCHED;
;     ...
;         if constexpr (ALIGN_EPI) { if (wr == 0) PG8_BAR; }
	s_add_i32 s10, vcc_hi, s65
	v_lshl_add_u64 v[202:203], v[202:203], 0, s[70:71]
	s_mov_b32 m0, s10
	ds_read_b128 v[178:181], v153 offset:49152
	ds_read_b128 v[182:185], v153 offset:50176
	ds_read_b128 v[186:189], v153 offset:51200
	ds_read_b128 v[190:193], v153 offset:52224
	ds_read_b128 v[198:201], v153 offset:53248
	ds_read_b128 v[212:215], v153 offset:54272
	ds_read_b128 v[216:219], v153 offset:55296
	ds_read_b128 v[220:223], v153 offset:56320
	global_load_lds_dwordx4 v[202:203], off
	s_add_i32 m0, s10, 0x2000
	s_add_u32 s8, s8, 0x80080
	v_lshl_add_u64 v[202:203], v[224:225], 0, s[70:71]
	s_addc_u32 s9, s9, 0
	s_add_i32 s10, s93, s65
	global_load_lds_dwordx4 v[202:203], off
	v_lshl_add_u64 v[202:203], s[8:9], 0, v[132:133]
	s_mov_b32 m0, s10
	s_nop 0
	global_load_lds_dwordx4 v[202:203], off
	v_lshl_add_u64 v[202:203], s[8:9], 0, v[136:137]
	s_add_i32 m0, s10, 0x2000
	s_nop 0
	global_load_lds_dwordx4 v[202:203], off
	v_lshl_add_u64 v[202:203], v[226:227], 0, s[70:71]
	s_mov_b32 m0, s54
	s_nop 0
	global_load_lds_dwordx4 v[202:203], off
	v_lshl_add_u64 v[202:203], v[228:229], 0, s[70:71]
	s_mov_b32 m0, s55
	s_nop 0
	global_load_lds_dwordx4 v[202:203], off
	s_waitcnt vmcnt(8)
	s_waitcnt lgkmcnt(0)
	s_barrier
	s_setprio 1
	s_waitcnt lgkmcnt(0)
	v_mfma_f32_16x16x32_bf16 v[62:65], v[142:145], v[178:181], v[62:65]
	v_mfma_f32_16x16x32_bf16 v[58:61], v[154:157], v[178:181], v[58:61]
	v_mfma_f32_16x16x32_bf16 v[42:45], v[154:157], v[186:189], v[42:45]
	v_mfma_f32_16x16x32_bf16 v[46:49], v[142:145], v[186:189], v[46:49]
	v_mfma_f32_16x16x32_bf16 v[30:33], v[142:145], v[198:201], v[30:33]
	v_mfma_f32_16x16x32_bf16 v[26:29], v[154:157], v[198:201], v[26:29]
	v_mfma_f32_16x16x32_bf16 v[10:13], v[154:157], v[216:219], v[10:13]
	v_mfma_f32_16x16x32_bf16 v[14:17], v[142:145], v[216:219], v[14:17]
	v_mfma_f32_16x16x32_bf16 v[62:65], v[146:149], v[182:185], v[62:65]
	v_mfma_f32_16x16x32_bf16 v[58:61], v[158:161], v[182:185], v[58:61]
	v_mfma_f32_16x16x32_bf16 v[42:45], v[158:161], v[190:193], v[42:45]
	v_mfma_f32_16x16x32_bf16 v[46:49], v[146:149], v[190:193], v[46:49]
	v_mfma_f32_16x16x32_bf16 v[30:33], v[146:149], v[212:215], v[30:33]
	v_mfma_f32_16x16x32_bf16 v[26:29], v[158:161], v[212:215], v[26:29]
	v_mfma_f32_16x16x32_bf16 v[10:13], v[158:161], v[220:223], v[10:13]
	v_mfma_f32_16x16x32_bf16 v[14:17], v[146:149], v[220:223], v[14:17]
	s_setprio 0
	s_setprio 1
	v_mfma_f32_16x16x32_bf16 v[54:57], v[162:165], v[178:181], v[54:57]
	v_mfma_f32_16x16x32_bf16 v[50:53], v[170:173], v[178:181], v[50:53]
	v_mfma_f32_16x16x32_bf16 v[34:37], v[170:173], v[186:189], v[34:37]
	v_mfma_f32_16x16x32_bf16 v[38:41], v[162:165], v[186:189], v[38:41]
	v_mfma_f32_16x16x32_bf16 v[22:25], v[162:165], v[198:201], v[22:25]
	v_mfma_f32_16x16x32_bf16 v[18:21], v[170:173], v[198:201], v[18:21]
	v_mfma_f32_16x16x32_bf16 v[2:5], v[170:173], v[216:219], v[2:5]
	v_mfma_f32_16x16x32_bf16 v[6:9], v[162:165], v[216:219], v[6:9]
	v_mfma_f32_16x16x32_bf16 v[54:57], v[166:169], v[182:185], v[54:57]
	v_mfma_f32_16x16x32_bf16 v[50:53], v[174:177], v[182:185], v[50:53]
	v_mfma_f32_16x16x32_bf16 v[34:37], v[174:177], v[190:193], v[34:37]
	v_mfma_f32_16x16x32_bf16 v[38:41], v[166:169], v[190:193], v[38:41]
	v_mfma_f32_16x16x32_bf16 v[22:25], v[166:169], v[212:215], v[22:25]
	v_mfma_f32_16x16x32_bf16 v[18:21], v[174:177], v[212:215], v[18:21]
	v_mfma_f32_16x16x32_bf16 v[2:5], v[174:177], v[220:223], v[2:5]
	v_mfma_f32_16x16x32_bf16 v[6:9], v[166:169], v[220:223], v[6:9]
	s_setprio 0
	s_barrier
	s_add_i32 s60, s60, 2
	s_add_u32 s35, s35, 0x100
	s_addc_u32 vcc_lo, vcc_lo, 0
	s_add_u32 s2, s2, 0x100
	s_addc_u32 s3, s3, 0
	s_cmp_gt_u32 s60, 29
	s_cbranch_scc0 .LBB0_411
	s_and_b64 vcc, exec, s[26:27]
	s_cbranch_vccz .LBB0_414
	s_barrier
